# c7 = c6 + first K-loop iteration peeled with srcC=0 (no accumulator zeroing)
# baseline (speedup 1.0000x reference)
.LBB0_343:
	s_ashr_i32 s11, s10, 31
	s_lshl_b64 s[12:13], s[10:11], 20
	s_add_u32 s12, s26, s12
	s_addc_u32 s13, s27, s13
	s_and_b64 s[14:15], s[2:3], exec
	s_cselect_b32 s11, s13, s21
	s_cselect_b32 s75, s12, s20
	s_ashr_i32 s9, s8, 31
	s_lshl_b64 s[14:15], s[8:9], 20
	s_add_u32 s14, s28, s14
	s_addc_u32 s15, s29, s15
	s_and_b64 s[22:23], s[2:3], exec
	s_cselect_b32 s9, s15, s19
	s_cselect_b32 s76, s14, s18
	s_add_u32 s77, s18, 0x100
	s_addc_u32 s78, s19, 0
	s_add_u32 s18, s20, 0x80080
	s_addc_u32 s19, s21, 0
	s_add_u32 s79, s20, 0x100
	s_addc_u32 s80, s21, 0
	s_mov_b32 s81, -2
	ds_read_b128 v[148:151], v143
	ds_read_b128 v[152:155], v143 offset:1024
	ds_read_b128 v[156:159], v143 offset:2048
	ds_read_b128 v[160:163], v143 offset:3072
	ds_read_b128 v[164:167], v144
	ds_read_b128 v[168:171], v144 offset:1024
	ds_read_b128 v[172:175], v144 offset:2048
	ds_read_b128 v[176:179], v144 offset:3072
	s_cmp_eq_u32 s81, 28
	s_cselect_b32 s21, s9, s78
	s_cselect_b32 s20, s76, s77
	s_cselect_b32 s23, s11, s80
	s_cselect_b32 s22, s75, s79
	ds_read_b128 v[180:183], v145
	ds_read_b128 v[184:187], v145 offset:1024
	ds_read_b128 v[188:191], v145 offset:2048
	ds_read_b128 v[192:195], v145 offset:3072
	ds_read_b128 v[196:199], v145 offset:4096
	ds_read_b128 v[200:203], v145 offset:5120
	ds_read_b128 v[204:207], v145 offset:6144
	ds_read_b128 v[208:211], v145 offset:7168
	s_add_u32 s82, s18, 0xfff80000
	s_addc_u32 s83, s19, -1
	s_mov_b32 s86, m0
	s_mov_b32 m0, s64
	s_nop 0
	global_load_lds_dwordx4 v138, s[82:83]
	s_mov_b32 m0, s86
	s_nop 0
	s_mov_b32 s86, m0
	s_mov_b32 m0, s67
	s_nop 0
	global_load_lds_dwordx4 v140, s[82:83]
	s_mov_b32 m0, s86
	s_mov_b32 s82, m0
	s_mov_b32 m0, s65
	s_nop 0
	global_load_lds_dwordx4 v138, s[18:19]
	s_mov_b32 m0, s82
	s_nop 0
	s_mov_b32 s82, m0
	s_mov_b32 m0, s73
	s_nop 0
	global_load_lds_dwordx4 v140, s[18:19]
	s_mov_b32 m0, s82
	s_waitcnt vmcnt(8)
	s_waitcnt lgkmcnt(0)
	s_barrier
	s_setprio 1
	s_waitcnt lgkmcnt(7)
	v_mfma_f32_16x16x32_bf16 v[126:129], v[148:151], v[180:183], 0
	v_mfma_f32_16x16x32_bf16 v[122:125], v[156:159], v[180:183], 0
	s_waitcnt lgkmcnt(5)
	v_mfma_f32_16x16x32_bf16 v[110:113], v[148:151], v[188:191], 0
	v_mfma_f32_16x16x32_bf16 v[106:109], v[156:159], v[188:191], 0
	s_waitcnt lgkmcnt(3)
	v_mfma_f32_16x16x32_bf16 v[94:97], v[148:151], v[196:199], 0
	v_mfma_f32_16x16x32_bf16 v[90:93], v[156:159], v[196:199], 0
	s_waitcnt lgkmcnt(1)
	v_mfma_f32_16x16x32_bf16 v[78:81], v[148:151], v[204:207], 0
	v_mfma_f32_16x16x32_bf16 v[74:77], v[156:159], v[204:207], 0
	v_mfma_f32_16x16x32_bf16 v[126:129], v[152:155], v[184:187], v[126:129]
	v_mfma_f32_16x16x32_bf16 v[122:125], v[160:163], v[184:187], v[122:125]
	v_mfma_f32_16x16x32_bf16 v[110:113], v[152:155], v[192:195], v[110:113]
	v_mfma_f32_16x16x32_bf16 v[106:109], v[160:163], v[192:195], v[106:109]
	v_mfma_f32_16x16x32_bf16 v[94:97], v[152:155], v[200:203], v[94:97]
	v_mfma_f32_16x16x32_bf16 v[90:93], v[160:163], v[200:203], v[90:93]
	s_waitcnt lgkmcnt(0)
	v_mfma_f32_16x16x32_bf16 v[78:81], v[152:155], v[208:211], v[78:81]
	v_mfma_f32_16x16x32_bf16 v[74:77], v[160:163], v[208:211], v[74:77]
	s_setprio 0
	s_setprio 1
	v_mfma_f32_16x16x32_bf16 v[118:121], v[164:167], v[180:183], 0
	v_mfma_f32_16x16x32_bf16 v[114:117], v[172:175], v[180:183], 0
	v_mfma_f32_16x16x32_bf16 v[102:105], v[164:167], v[188:191], 0
	v_mfma_f32_16x16x32_bf16 v[98:101], v[172:175], v[188:191], 0
	v_mfma_f32_16x16x32_bf16 v[86:89], v[164:167], v[196:199], 0
	v_mfma_f32_16x16x32_bf16 v[82:85], v[172:175], v[196:199], 0
	v_mfma_f32_16x16x32_bf16 v[70:73], v[164:167], v[204:207], 0
	v_mfma_f32_16x16x32_bf16 v[66:69], v[172:175], v[204:207], 0
	v_mfma_f32_16x16x32_bf16 v[118:121], v[168:171], v[184:187], v[118:121]
	v_mfma_f32_16x16x32_bf16 v[114:117], v[176:179], v[184:187], v[114:117]
	v_mfma_f32_16x16x32_bf16 v[102:105], v[168:171], v[192:195], v[102:105]
	v_mfma_f32_16x16x32_bf16 v[98:101], v[176:179], v[192:195], v[98:101]
	v_mfma_f32_16x16x32_bf16 v[86:89], v[168:171], v[200:203], v[86:89]
	v_mfma_f32_16x16x32_bf16 v[82:85], v[176:179], v[200:203], v[82:85]
	s_setprio 2
	s_barrier
	v_mfma_f32_16x16x32_bf16 v[70:73], v[168:171], v[208:211], v[70:73]
	v_mfma_f32_16x16x32_bf16 v[66:69], v[176:179], v[208:211], v[66:69]
	s_setprio 0
	ds_read_b128 v[180:183], v145 offset:16384
	ds_read_b128 v[184:187], v145 offset:17408
	ds_read_b128 v[188:191], v145 offset:18432
	ds_read_b128 v[192:195], v145 offset:19456
	ds_read_b128 v[196:199], v145 offset:20480
	ds_read_b128 v[200:203], v145 offset:21504
	ds_read_b128 v[204:207], v145 offset:22528
	ds_read_b128 v[208:211], v145 offset:23552
	s_mov_b32 s82, m0
	s_mov_b32 m0, s35
	s_nop 0
	global_load_lds_dwordx4 v139, s[20:21]
	s_mov_b32 m0, s82
	s_nop 0
	s_mov_b32 s82, m0
	s_mov_b32 m0, s36
	s_nop 0
	global_load_lds_dwordx4 v141, s[20:21]
	s_mov_b32 m0, s82
	s_add_u32 s82, s20, 0x80000
	s_addc_u32 s83, s21, 0
	s_mov_b32 s86, m0
	s_mov_b32 m0, s37
	s_nop 0
	global_load_lds_dwordx4 v139, s[82:83]
	s_mov_b32 m0, s86
	s_nop 0
	s_mov_b32 s86, m0
	s_mov_b32 m0, s42
	s_nop 0
	global_load_lds_dwordx4 v141, s[82:83]
	s_mov_b32 m0, s86
	s_waitcnt vmcnt(4)
	s_waitcnt lgkmcnt(0)
	s_barrier
	s_setprio 1
	s_waitcnt lgkmcnt(7)
	v_mfma_f32_16x16x32_bf16 v[62:65], v[148:151], v[180:183], 0
	v_mfma_f32_16x16x32_bf16 v[58:61], v[156:159], v[180:183], 0
	s_waitcnt lgkmcnt(5)
	v_mfma_f32_16x16x32_bf16 v[46:49], v[148:151], v[188:191], 0
	v_mfma_f32_16x16x32_bf16 v[42:45], v[156:159], v[188:191], 0
	s_waitcnt lgkmcnt(3)
	v_mfma_f32_16x16x32_bf16 v[30:33], v[148:151], v[196:199], 0
	v_mfma_f32_16x16x32_bf16 v[26:29], v[156:159], v[196:199], 0
	s_waitcnt lgkmcnt(1)
	v_mfma_f32_16x16x32_bf16 v[14:17], v[148:151], v[204:207], 0
	v_mfma_f32_16x16x32_bf16 v[10:13], v[156:159], v[204:207], 0
	v_mfma_f32_16x16x32_bf16 v[62:65], v[152:155], v[184:187], v[62:65]
	v_mfma_f32_16x16x32_bf16 v[58:61], v[160:163], v[184:187], v[58:61]
	v_mfma_f32_16x16x32_bf16 v[46:49], v[152:155], v[192:195], v[46:49]
	v_mfma_f32_16x16x32_bf16 v[42:45], v[160:163], v[192:195], v[42:45]
	v_mfma_f32_16x16x32_bf16 v[30:33], v[152:155], v[200:203], v[30:33]
	v_mfma_f32_16x16x32_bf16 v[26:29], v[160:163], v[200:203], v[26:29]
	s_waitcnt lgkmcnt(0)
	v_mfma_f32_16x16x32_bf16 v[14:17], v[152:155], v[208:211], v[14:17]
	v_mfma_f32_16x16x32_bf16 v[10:13], v[160:163], v[208:211], v[10:13]
	s_setprio 0
	s_setprio 1
	v_mfma_f32_16x16x32_bf16 v[54:57], v[164:167], v[180:183], 0
	v_mfma_f32_16x16x32_bf16 v[50:53], v[172:175], v[180:183], 0
	v_mfma_f32_16x16x32_bf16 v[38:41], v[164:167], v[188:191], 0
	v_mfma_f32_16x16x32_bf16 v[34:37], v[172:175], v[188:191], 0
	v_mfma_f32_16x16x32_bf16 v[22:25], v[164:167], v[196:199], 0
	v_mfma_f32_16x16x32_bf16 v[18:21], v[172:175], v[196:199], 0
	v_mfma_f32_16x16x32_bf16 v[6:9], v[164:167], v[204:207], 0
	v_mfma_f32_16x16x32_bf16 v[2:5], v[172:175], v[204:207], 0
	v_mfma_f32_16x16x32_bf16 v[54:57], v[168:171], v[184:187], v[54:57]
	v_mfma_f32_16x16x32_bf16 v[50:53], v[176:179], v[184:187], v[50:53]
	v_mfma_f32_16x16x32_bf16 v[38:41], v[168:171], v[192:195], v[38:41]
	v_mfma_f32_16x16x32_bf16 v[34:37], v[176:179], v[192:195], v[34:37]
	v_mfma_f32_16x16x32_bf16 v[22:25], v[168:171], v[200:203], v[22:25]
	v_mfma_f32_16x16x32_bf16 v[18:21], v[176:179], v[200:203], v[18:21]
	s_setprio 2
	s_barrier
	v_mfma_f32_16x16x32_bf16 v[6:9], v[168:171], v[208:211], v[6:9]
	v_mfma_f32_16x16x32_bf16 v[2:5], v[176:179], v[208:211], v[2:5]
	s_setprio 0
	ds_read_b128 v[148:151], v146
	ds_read_b128 v[152:155], v146 offset:1024
	ds_read_b128 v[156:159], v146 offset:2048
	ds_read_b128 v[160:163], v146 offset:3072
	ds_read_b128 v[164:167], v147
	ds_read_b128 v[168:171], v147 offset:1024
	ds_read_b128 v[172:175], v147 offset:2048
	ds_read_b128 v[176:179], v147 offset:3072
	ds_read_b128 v[180:183], v145 offset:32768
	ds_read_b128 v[184:187], v145 offset:33792
	ds_read_b128 v[188:191], v145 offset:34816
	ds_read_b128 v[192:195], v145 offset:35840
	ds_read_b128 v[196:199], v145 offset:36864
	ds_read_b128 v[200:203], v145 offset:37888
	ds_read_b128 v[204:207], v145 offset:38912
	ds_read_b128 v[208:211], v145 offset:39936
	s_mov_b32 s82, m0
	s_mov_b32 m0, s31
	s_nop 0
	global_load_lds_dwordx4 v138, s[22:23]
	s_mov_b32 m0, s82
	s_nop 0
	s_mov_b32 s82, m0
	s_mov_b32 m0, s43
	s_nop 0
	global_load_lds_dwordx4 v140, s[22:23]
	s_mov_b32 m0, s82
	s_add_u32 s22, s22, 0x80000
	s_addc_u32 s23, s23, 0
	s_mov_b32 s82, m0
	s_mov_b32 m0, s46
	s_nop 0
	global_load_lds_dwordx4 v138, s[22:23]
	s_mov_b32 m0, s82
	s_nop 0
	s_mov_b32 s82, m0
	s_mov_b32 m0, s47
	s_nop 0
	global_load_lds_dwordx4 v140, s[22:23]
	s_mov_b32 m0, s82
	s_waitcnt vmcnt(8)
	s_waitcnt lgkmcnt(0)
	s_barrier
	s_setprio 1
	s_waitcnt lgkmcnt(7)
	v_mfma_f32_16x16x32_bf16 v[126:129], v[148:151], v[180:183], v[126:129]
	v_mfma_f32_16x16x32_bf16 v[122:125], v[156:159], v[180:183], v[122:125]
	s_waitcnt lgkmcnt(5)
	v_mfma_f32_16x16x32_bf16 v[110:113], v[148:151], v[188:191], v[110:113]
	v_mfma_f32_16x16x32_bf16 v[106:109], v[156:159], v[188:191], v[106:109]
	s_waitcnt lgkmcnt(3)
	v_mfma_f32_16x16x32_bf16 v[94:97], v[148:151], v[196:199], v[94:97]
	v_mfma_f32_16x16x32_bf16 v[90:93], v[156:159], v[196:199], v[90:93]
	s_waitcnt lgkmcnt(1)
	v_mfma_f32_16x16x32_bf16 v[78:81], v[148:151], v[204:207], v[78:81]
	v_mfma_f32_16x16x32_bf16 v[74:77], v[156:159], v[204:207], v[74:77]
	v_mfma_f32_16x16x32_bf16 v[126:129], v[152:155], v[184:187], v[126:129]
	v_mfma_f32_16x16x32_bf16 v[122:125], v[160:163], v[184:187], v[122:125]
	v_mfma_f32_16x16x32_bf16 v[110:113], v[152:155], v[192:195], v[110:113]
	v_mfma_f32_16x16x32_bf16 v[106:109], v[160:163], v[192:195], v[106:109]
	v_mfma_f32_16x16x32_bf16 v[94:97], v[152:155], v[200:203], v[94:97]
	v_mfma_f32_16x16x32_bf16 v[90:93], v[160:163], v[200:203], v[90:93]
	s_waitcnt lgkmcnt(0)
	v_mfma_f32_16x16x32_bf16 v[78:81], v[152:155], v[208:211], v[78:81]
	v_mfma_f32_16x16x32_bf16 v[74:77], v[160:163], v[208:211], v[74:77]
	s_setprio 0
	s_setprio 1
	v_mfma_f32_16x16x32_bf16 v[118:121], v[164:167], v[180:183], v[118:121]
	v_mfma_f32_16x16x32_bf16 v[114:117], v[172:175], v[180:183], v[114:117]
	v_mfma_f32_16x16x32_bf16 v[102:105], v[164:167], v[188:191], v[102:105]
	v_mfma_f32_16x16x32_bf16 v[98:101], v[172:175], v[188:191], v[98:101]
	v_mfma_f32_16x16x32_bf16 v[86:89], v[164:167], v[196:199], v[86:89]
	v_mfma_f32_16x16x32_bf16 v[82:85], v[172:175], v[196:199], v[82:85]
	v_mfma_f32_16x16x32_bf16 v[70:73], v[164:167], v[204:207], v[70:73]
	v_mfma_f32_16x16x32_bf16 v[66:69], v[172:175], v[204:207], v[66:69]
	v_mfma_f32_16x16x32_bf16 v[118:121], v[168:171], v[184:187], v[118:121]
	v_mfma_f32_16x16x32_bf16 v[114:117], v[176:179], v[184:187], v[114:117]
	v_mfma_f32_16x16x32_bf16 v[102:105], v[168:171], v[192:195], v[102:105]
	v_mfma_f32_16x16x32_bf16 v[98:101], v[176:179], v[192:195], v[98:101]
	v_mfma_f32_16x16x32_bf16 v[86:89], v[168:171], v[200:203], v[86:89]
	v_mfma_f32_16x16x32_bf16 v[82:85], v[176:179], v[200:203], v[82:85]
	s_setprio 2
	s_barrier
	v_mfma_f32_16x16x32_bf16 v[70:73], v[168:171], v[208:211], v[70:73]
	v_mfma_f32_16x16x32_bf16 v[66:69], v[176:179], v[208:211], v[66:69]
	s_setprio 0
	ds_read_b128 v[180:183], v145 offset:49152
	ds_read_b128 v[184:187], v145 offset:50176
	ds_read_b128 v[188:191], v145 offset:51200
	ds_read_b128 v[192:195], v145 offset:52224
	ds_read_b128 v[196:199], v145 offset:53248
	ds_read_b128 v[200:203], v145 offset:54272
	ds_read_b128 v[204:207], v145 offset:55296
	ds_read_b128 v[208:211], v145 offset:56320
	s_add_u32 s22, s20, 0x80
	s_addc_u32 s23, s21, 0
	s_mov_b32 s82, m0
	s_mov_b32 m0, s48
	s_nop 0
	global_load_lds_dwordx4 v139, s[22:23]
	s_mov_b32 m0, s82
	s_add_u32 s20, s20, 0x80080
	s_mov_b32 s82, m0
	s_mov_b32 m0, s49
	s_nop 0
	global_load_lds_dwordx4 v141, s[22:23]
	s_mov_b32 m0, s82
	s_addc_u32 s21, s21, 0
	s_mov_b32 s22, m0
	s_mov_b32 m0, s56
	s_nop 0
	global_load_lds_dwordx4 v139, s[20:21]
	s_mov_b32 m0, s22
	s_nop 0
	s_mov_b32 s22, m0
	s_mov_b32 m0, s57
	s_nop 0
	global_load_lds_dwordx4 v141, s[20:21]
	s_mov_b32 m0, s22
	s_waitcnt vmcnt(4)
	s_waitcnt lgkmcnt(0)
	s_barrier
	s_setprio 1
	s_waitcnt lgkmcnt(7)
	v_mfma_f32_16x16x32_bf16 v[62:65], v[148:151], v[180:183], v[62:65]
	v_mfma_f32_16x16x32_bf16 v[58:61], v[156:159], v[180:183], v[58:61]
	s_waitcnt lgkmcnt(5)
	v_mfma_f32_16x16x32_bf16 v[46:49], v[148:151], v[188:191], v[46:49]
	v_mfma_f32_16x16x32_bf16 v[42:45], v[156:159], v[188:191], v[42:45]
	s_waitcnt lgkmcnt(3)
	v_mfma_f32_16x16x32_bf16 v[30:33], v[148:151], v[196:199], v[30:33]
	v_mfma_f32_16x16x32_bf16 v[26:29], v[156:159], v[196:199], v[26:29]
	s_waitcnt lgkmcnt(1)
	v_mfma_f32_16x16x32_bf16 v[14:17], v[148:151], v[204:207], v[14:17]
	v_mfma_f32_16x16x32_bf16 v[10:13], v[156:159], v[204:207], v[10:13]
	v_mfma_f32_16x16x32_bf16 v[62:65], v[152:155], v[184:187], v[62:65]
	v_mfma_f32_16x16x32_bf16 v[58:61], v[160:163], v[184:187], v[58:61]
	v_mfma_f32_16x16x32_bf16 v[46:49], v[152:155], v[192:195], v[46:49]
	v_mfma_f32_16x16x32_bf16 v[42:45], v[160:163], v[192:195], v[42:45]
	v_mfma_f32_16x16x32_bf16 v[30:33], v[152:155], v[200:203], v[30:33]
	v_mfma_f32_16x16x32_bf16 v[26:29], v[160:163], v[200:203], v[26:29]
	s_waitcnt lgkmcnt(0)
	v_mfma_f32_16x16x32_bf16 v[14:17], v[152:155], v[208:211], v[14:17]
	v_mfma_f32_16x16x32_bf16 v[10:13], v[160:163], v[208:211], v[10:13]
	s_setprio 0
	s_setprio 1
	v_mfma_f32_16x16x32_bf16 v[54:57], v[164:167], v[180:183], v[54:57]
	v_mfma_f32_16x16x32_bf16 v[50:53], v[172:175], v[180:183], v[50:53]
	v_mfma_f32_16x16x32_bf16 v[38:41], v[164:167], v[188:191], v[38:41]
	v_mfma_f32_16x16x32_bf16 v[34:37], v[172:175], v[188:191], v[34:37]
	v_mfma_f32_16x16x32_bf16 v[22:25], v[164:167], v[196:199], v[22:25]
	v_mfma_f32_16x16x32_bf16 v[18:21], v[172:175], v[196:199], v[18:21]
	v_mfma_f32_16x16x32_bf16 v[6:9], v[164:167], v[204:207], v[6:9]
	v_mfma_f32_16x16x32_bf16 v[2:5], v[172:175], v[204:207], v[2:5]
	v_mfma_f32_16x16x32_bf16 v[54:57], v[168:171], v[184:187], v[54:57]
	v_mfma_f32_16x16x32_bf16 v[50:53], v[176:179], v[184:187], v[50:53]
	v_mfma_f32_16x16x32_bf16 v[38:41], v[168:171], v[192:195], v[38:41]
	v_mfma_f32_16x16x32_bf16 v[34:37], v[176:179], v[192:195], v[34:37]
	v_mfma_f32_16x16x32_bf16 v[22:25], v[168:171], v[200:203], v[22:25]
	v_mfma_f32_16x16x32_bf16 v[18:21], v[176:179], v[200:203], v[18:21]
	s_setprio 2
	s_barrier
	v_mfma_f32_16x16x32_bf16 v[6:9], v[168:171], v[208:211], v[6:9]
	v_mfma_f32_16x16x32_bf16 v[2:5], v[176:179], v[208:211], v[2:5]
	s_setprio 0
	s_add_i32 s81, s81, 2
	s_add_u32 s77, s77, 0x100
	s_addc_u32 s78, s78, 0
	s_add_u32 s18, s18, 0x100
	s_addc_u32 s19, s19, 0
	s_add_u32 s79, s79, 0x100
	s_addc_u32 s80, s80, 0
	s_cmp_gt_u32 s81, 29
	.p2align 6

.LBB0_472:
	s_ashr_i32 s13, s12, 31
	s_lshl_b64 s[14:15], s[12:13], 15
	s_add_u32 s14, s28, s14
	s_addc_u32 s15, s29, s15
	s_and_b64 s[16:17], s[2:3], exec
	s_cselect_b32 s13, s15, s23
	s_cselect_b32 s76, s14, s22
	s_ashr_i32 s11, s10, 31
	s_lshl_b64 s[16:17], s[10:11], 15
	s_add_u32 s16, s30, s16
	s_addc_u32 s17, s31, s17
	s_and_b64 s[24:25], s[2:3], exec
	s_cselect_b32 s11, s17, s21
	s_cselect_b32 s77, s16, s20
	s_add_u32 s78, s20, 0x80000
	s_addc_u32 s79, s21, 0
	s_add_u32 s20, s22, 0x204000
	s_addc_u32 s21, s23, 0
	s_add_u32 s80, s22, 0x400000
	s_addc_u32 s81, s23, 0
	s_mov_b32 s82, -2
	s_waitcnt vmcnt(25)
	s_waitcnt vmcnt(24)
	s_waitcnt vmcnt(23)
	s_waitcnt vmcnt(22)
	s_waitcnt vmcnt(21)
	s_waitcnt vmcnt(20)
	s_waitcnt vmcnt(15)
	s_waitcnt vmcnt(14)
	s_waitcnt vmcnt(13)
	s_waitcnt vmcnt(12)
	s_waitcnt vmcnt(7)
	s_waitcnt vmcnt(6)
	s_waitcnt vmcnt(5)
	s_waitcnt vmcnt(4)
	s_waitcnt vmcnt(3)
	s_waitcnt vmcnt(2)
	s_waitcnt vmcnt(1)
	s_waitcnt vmcnt(0)
	ds_read_b128 v[134:137], v161
	ds_read_b128 v[138:141], v161 offset:1024
	ds_read_b128 v[142:145], v161 offset:2048
	ds_read_b128 v[146:149], v161 offset:3072
	ds_read_b128 v[150:153], v162
	ds_read_b128 v[166:169], v162 offset:1024
	ds_read_b128 v[170:173], v162 offset:2048
	ds_read_b128 v[174:177], v162 offset:3072
	s_cmpk_eq_i32 s82, 0x52
	s_cselect_b32 s23, s11, s79
	s_cselect_b32 s22, s77, s78
	s_cselect_b32 s25, s13, s81
	s_cselect_b32 s24, s76, s80
	ds_read_b128 v[178:181], v163
	ds_read_b128 v[182:185], v163 offset:1024
	ds_read_b128 v[186:189], v163 offset:2048
	ds_read_b128 v[190:193], v163 offset:3072
	ds_read_b128 v[194:197], v163 offset:4096
	ds_read_b128 v[198:201], v163 offset:5120
	ds_read_b128 v[202:205], v163 offset:6144
	ds_read_b128 v[206:209], v163 offset:7168
	s_add_u32 s86, s20, 0xffffc000
	s_addc_u32 s87, s21, -1
	s_mov_b32 s83, m0
	s_mov_b32 m0, s65
	s_nop 0
	global_load_lds_dwordx4 v1, s[86:87]
	s_mov_b32 m0, s83
	s_nop 0
	s_mov_b32 s83, m0
	s_mov_b32 m0, s67
	s_nop 0
	global_load_lds_dwordx4 v157, s[86:87]
	s_mov_b32 m0, s83
	s_nop 0
	s_mov_b32 s83, m0
	s_mov_b32 m0, s66
	s_nop 0
	global_load_lds_dwordx4 v1, s[20:21]
	s_mov_b32 m0, s83
	s_nop 0
	s_mov_b32 s83, m0
	s_mov_b32 m0, s73
	s_nop 0
	global_load_lds_dwordx4 v157, s[20:21]
	s_mov_b32 m0, s83
	s_waitcnt vmcnt(8)
	s_waitcnt lgkmcnt(0)
	s_barrier
	s_setprio 1
	s_waitcnt lgkmcnt(7)
	v_mfma_f32_16x16x32_bf16 v[126:129], v[134:137], v[178:181], 0
	v_mfma_f32_16x16x32_bf16 v[122:125], v[142:145], v[178:181], 0
	s_waitcnt lgkmcnt(5)
	v_mfma_f32_16x16x32_bf16 v[118:121], v[134:137], v[186:189], 0
	v_mfma_f32_16x16x32_bf16 v[114:117], v[142:145], v[186:189], 0
	s_waitcnt lgkmcnt(3)
	v_mfma_f32_16x16x32_bf16 v[102:105], v[134:137], v[194:197], 0
	v_mfma_f32_16x16x32_bf16 v[94:97], v[142:145], v[194:197], 0
	s_waitcnt lgkmcnt(1)
	v_mfma_f32_16x16x32_bf16 v[86:89], v[134:137], v[202:205], 0
	v_mfma_f32_16x16x32_bf16 v[78:81], v[142:145], v[202:205], 0
	v_mfma_f32_16x16x32_bf16 v[126:129], v[138:141], v[182:185], v[126:129]
	v_mfma_f32_16x16x32_bf16 v[122:125], v[146:149], v[182:185], v[122:125]
	v_mfma_f32_16x16x32_bf16 v[118:121], v[138:141], v[190:193], v[118:121]
	v_mfma_f32_16x16x32_bf16 v[114:117], v[146:149], v[190:193], v[114:117]
	v_mfma_f32_16x16x32_bf16 v[102:105], v[138:141], v[198:201], v[102:105]
	v_mfma_f32_16x16x32_bf16 v[94:97], v[146:149], v[198:201], v[94:97]
	s_waitcnt lgkmcnt(0)
	v_mfma_f32_16x16x32_bf16 v[86:89], v[138:141], v[206:209], v[86:89]
	v_mfma_f32_16x16x32_bf16 v[78:81], v[146:149], v[206:209], v[78:81]
	s_setprio 0
	s_setprio 1
	v_mfma_f32_16x16x32_bf16 v[110:113], v[150:153], v[178:181], 0
	v_mfma_f32_16x16x32_bf16 v[106:109], v[170:173], v[178:181], 0
	v_mfma_f32_16x16x32_bf16 v[98:101], v[150:153], v[186:189], 0
	v_mfma_f32_16x16x32_bf16 v[90:93], v[170:173], v[186:189], 0
	v_mfma_f32_16x16x32_bf16 v[82:85], v[150:153], v[194:197], 0
	v_mfma_f32_16x16x32_bf16 v[74:77], v[170:173], v[194:197], 0
	v_mfma_f32_16x16x32_bf16 v[70:73], v[150:153], v[202:205], 0
	v_mfma_f32_16x16x32_bf16 v[66:69], v[170:173], v[202:205], 0
	v_mfma_f32_16x16x32_bf16 v[110:113], v[166:169], v[182:185], v[110:113]
	v_mfma_f32_16x16x32_bf16 v[106:109], v[174:177], v[182:185], v[106:109]
	v_mfma_f32_16x16x32_bf16 v[98:101], v[166:169], v[190:193], v[98:101]
	v_mfma_f32_16x16x32_bf16 v[90:93], v[174:177], v[190:193], v[90:93]
	v_mfma_f32_16x16x32_bf16 v[82:85], v[166:169], v[198:201], v[82:85]
	v_mfma_f32_16x16x32_bf16 v[74:77], v[174:177], v[198:201], v[74:77]
	s_setprio 2
	s_barrier
	v_mfma_f32_16x16x32_bf16 v[70:73], v[166:169], v[206:209], v[70:73]
	v_mfma_f32_16x16x32_bf16 v[66:69], v[174:177], v[206:209], v[66:69]
	s_setprio 0
	ds_read_b128 v[178:181], v163 offset:16384
	ds_read_b128 v[182:185], v163 offset:17408
	ds_read_b128 v[186:189], v163 offset:18432
	ds_read_b128 v[190:193], v163 offset:19456
	ds_read_b128 v[194:197], v163 offset:20480
	ds_read_b128 v[198:201], v163 offset:21504
	ds_read_b128 v[202:205], v163 offset:22528
	ds_read_b128 v[206:209], v163 offset:23552
	s_mov_b32 s83, m0
	s_mov_b32 m0, s19
	s_nop 0
	global_load_lds_dwordx4 v156, s[22:23]
	s_mov_b32 m0, s83
	s_add_u32 s86, s22, 0x4000
	s_mov_b32 s83, m0
	s_mov_b32 m0, s35
	s_nop 0
	global_load_lds_dwordx4 v158, s[22:23]
	s_mov_b32 m0, s83
	s_addc_u32 s87, s23, 0
	s_mov_b32 s83, m0
	s_mov_b32 m0, s36
	s_nop 0
	global_load_lds_dwordx4 v156, s[86:87]
	s_mov_b32 m0, s83
	s_nop 0
	s_mov_b32 s83, m0
	s_mov_b32 m0, s37
	s_nop 0
	global_load_lds_dwordx4 v158, s[86:87]
	s_mov_b32 m0, s83
	s_waitcnt vmcnt(4)
	s_waitcnt lgkmcnt(0)
	s_barrier
	s_setprio 1
	s_waitcnt lgkmcnt(7)
	v_mfma_f32_16x16x32_bf16 v[62:65], v[134:137], v[178:181], 0
	v_mfma_f32_16x16x32_bf16 v[58:61], v[142:145], v[178:181], 0
	s_waitcnt lgkmcnt(5)
	v_mfma_f32_16x16x32_bf16 v[54:57], v[134:137], v[186:189], 0
	v_mfma_f32_16x16x32_bf16 v[46:49], v[142:145], v[186:189], 0
	s_waitcnt lgkmcnt(3)
	v_mfma_f32_16x16x32_bf16 v[38:41], v[134:137], v[194:197], 0
	v_mfma_f32_16x16x32_bf16 v[30:33], v[142:145], v[194:197], 0
	s_waitcnt lgkmcnt(1)
	v_mfma_f32_16x16x32_bf16 v[22:25], v[134:137], v[202:205], 0
	v_mfma_f32_16x16x32_bf16 v[14:17], v[142:145], v[202:205], 0
	v_mfma_f32_16x16x32_bf16 v[62:65], v[138:141], v[182:185], v[62:65]
	v_mfma_f32_16x16x32_bf16 v[58:61], v[146:149], v[182:185], v[58:61]
	v_mfma_f32_16x16x32_bf16 v[54:57], v[138:141], v[190:193], v[54:57]
	v_mfma_f32_16x16x32_bf16 v[46:49], v[146:149], v[190:193], v[46:49]
	v_mfma_f32_16x16x32_bf16 v[38:41], v[138:141], v[198:201], v[38:41]
	v_mfma_f32_16x16x32_bf16 v[30:33], v[146:149], v[198:201], v[30:33]
	s_waitcnt lgkmcnt(0)
	v_mfma_f32_16x16x32_bf16 v[22:25], v[138:141], v[206:209], v[22:25]
	v_mfma_f32_16x16x32_bf16 v[14:17], v[146:149], v[206:209], v[14:17]
	s_setprio 0
	s_setprio 1
	v_mfma_f32_16x16x32_bf16 v[50:53], v[150:153], v[178:181], 0
	v_mfma_f32_16x16x32_bf16 v[42:45], v[170:173], v[178:181], 0
	v_mfma_f32_16x16x32_bf16 v[34:37], v[150:153], v[186:189], 0
	v_mfma_f32_16x16x32_bf16 v[26:29], v[170:173], v[186:189], 0
	v_mfma_f32_16x16x32_bf16 v[18:21], v[150:153], v[194:197], 0
	v_mfma_f32_16x16x32_bf16 v[10:13], v[170:173], v[194:197], 0
	v_mfma_f32_16x16x32_bf16 v[6:9], v[150:153], v[202:205], 0
	v_mfma_f32_16x16x32_bf16 v[2:5], v[170:173], v[202:205], 0
	v_mfma_f32_16x16x32_bf16 v[50:53], v[166:169], v[182:185], v[50:53]
	v_mfma_f32_16x16x32_bf16 v[42:45], v[174:177], v[182:185], v[42:45]
	v_mfma_f32_16x16x32_bf16 v[34:37], v[166:169], v[190:193], v[34:37]
	v_mfma_f32_16x16x32_bf16 v[26:29], v[174:177], v[190:193], v[26:29]
	v_mfma_f32_16x16x32_bf16 v[18:21], v[166:169], v[198:201], v[18:21]
	v_mfma_f32_16x16x32_bf16 v[10:13], v[174:177], v[198:201], v[10:13]
	s_setprio 2
	s_barrier
	v_mfma_f32_16x16x32_bf16 v[6:9], v[166:169], v[206:209], v[6:9]
	v_mfma_f32_16x16x32_bf16 v[2:5], v[174:177], v[206:209], v[2:5]
	s_setprio 0
	ds_read_b128 v[134:137], v164
	ds_read_b128 v[138:141], v164 offset:1024
	ds_read_b128 v[142:145], v164 offset:2048
	ds_read_b128 v[146:149], v164 offset:3072
	ds_read_b128 v[150:153], v165
	ds_read_b128 v[166:169], v165 offset:1024
	ds_read_b128 v[170:173], v165 offset:2048
	ds_read_b128 v[174:177], v165 offset:3072
	ds_read_b128 v[178:181], v163 offset:32768
	ds_read_b128 v[182:185], v163 offset:33792
	ds_read_b128 v[186:189], v163 offset:34816
	ds_read_b128 v[190:193], v163 offset:35840
	ds_read_b128 v[194:197], v163 offset:36864
	ds_read_b128 v[198:201], v163 offset:37888
	ds_read_b128 v[202:205], v163 offset:38912
	ds_read_b128 v[206:209], v163 offset:39936
	s_mov_b32 s83, m0
	s_mov_b32 m0, s34
	s_nop 0
	global_load_lds_dwordx4 v1, s[24:25]
	s_mov_b32 m0, s83
	s_nop 0
	s_mov_b32 s83, m0
	s_mov_b32 m0, s42
	s_nop 0
	global_load_lds_dwordx4 v157, s[24:25]
	s_mov_b32 m0, s83
	s_add_u32 s24, s24, 0x4000
	s_addc_u32 s25, s25, 0
	s_mov_b32 s83, m0
	s_mov_b32 m0, s43
	s_nop 0
	global_load_lds_dwordx4 v1, s[24:25]
	s_mov_b32 m0, s83
	s_nop 0
	s_mov_b32 s83, m0
	s_mov_b32 m0, s46
	s_nop 0
	global_load_lds_dwordx4 v157, s[24:25]
	s_mov_b32 m0, s83
	s_waitcnt vmcnt(8)
	s_waitcnt lgkmcnt(0)
	s_barrier
	s_setprio 1
	s_waitcnt lgkmcnt(7)
	v_mfma_f32_16x16x32_bf16 v[126:129], v[134:137], v[178:181], v[126:129]
	v_mfma_f32_16x16x32_bf16 v[122:125], v[142:145], v[178:181], v[122:125]
	s_waitcnt lgkmcnt(5)
	v_mfma_f32_16x16x32_bf16 v[118:121], v[134:137], v[186:189], v[118:121]
	v_mfma_f32_16x16x32_bf16 v[114:117], v[142:145], v[186:189], v[114:117]
	s_waitcnt lgkmcnt(3)
	v_mfma_f32_16x16x32_bf16 v[102:105], v[134:137], v[194:197], v[102:105]
	v_mfma_f32_16x16x32_bf16 v[94:97], v[142:145], v[194:197], v[94:97]
	s_waitcnt lgkmcnt(1)
	v_mfma_f32_16x16x32_bf16 v[86:89], v[134:137], v[202:205], v[86:89]
	v_mfma_f32_16x16x32_bf16 v[78:81], v[142:145], v[202:205], v[78:81]
	v_mfma_f32_16x16x32_bf16 v[126:129], v[138:141], v[182:185], v[126:129]
	v_mfma_f32_16x16x32_bf16 v[122:125], v[146:149], v[182:185], v[122:125]
	v_mfma_f32_16x16x32_bf16 v[118:121], v[138:141], v[190:193], v[118:121]
	v_mfma_f32_16x16x32_bf16 v[114:117], v[146:149], v[190:193], v[114:117]
	v_mfma_f32_16x16x32_bf16 v[102:105], v[138:141], v[198:201], v[102:105]
	v_mfma_f32_16x16x32_bf16 v[94:97], v[146:149], v[198:201], v[94:97]
	s_waitcnt lgkmcnt(0)
	v_mfma_f32_16x16x32_bf16 v[86:89], v[138:141], v[206:209], v[86:89]
	v_mfma_f32_16x16x32_bf16 v[78:81], v[146:149], v[206:209], v[78:81]
	s_setprio 0
	s_setprio 1
	v_mfma_f32_16x16x32_bf16 v[110:113], v[150:153], v[178:181], v[110:113]
	v_mfma_f32_16x16x32_bf16 v[106:109], v[170:173], v[178:181], v[106:109]
	v_mfma_f32_16x16x32_bf16 v[98:101], v[150:153], v[186:189], v[98:101]
	v_mfma_f32_16x16x32_bf16 v[90:93], v[170:173], v[186:189], v[90:93]
	v_mfma_f32_16x16x32_bf16 v[82:85], v[150:153], v[194:197], v[82:85]
	v_mfma_f32_16x16x32_bf16 v[74:77], v[170:173], v[194:197], v[74:77]
	v_mfma_f32_16x16x32_bf16 v[70:73], v[150:153], v[202:205], v[70:73]
	v_mfma_f32_16x16x32_bf16 v[66:69], v[170:173], v[202:205], v[66:69]
	v_mfma_f32_16x16x32_bf16 v[110:113], v[166:169], v[182:185], v[110:113]
	v_mfma_f32_16x16x32_bf16 v[106:109], v[174:177], v[182:185], v[106:109]
	v_mfma_f32_16x16x32_bf16 v[98:101], v[166:169], v[190:193], v[98:101]
	v_mfma_f32_16x16x32_bf16 v[90:93], v[174:177], v[190:193], v[90:93]
	v_mfma_f32_16x16x32_bf16 v[82:85], v[166:169], v[198:201], v[82:85]
	v_mfma_f32_16x16x32_bf16 v[74:77], v[174:177], v[198:201], v[74:77]
	s_setprio 2
	s_barrier
	v_mfma_f32_16x16x32_bf16 v[70:73], v[166:169], v[206:209], v[70:73]
	v_mfma_f32_16x16x32_bf16 v[66:69], v[174:177], v[206:209], v[66:69]
	s_setprio 0
	ds_read_b128 v[178:181], v163 offset:49152
	ds_read_b128 v[182:185], v163 offset:50176
	ds_read_b128 v[186:189], v163 offset:51200
	ds_read_b128 v[190:193], v163 offset:52224
	ds_read_b128 v[194:197], v163 offset:53248
	ds_read_b128 v[198:201], v163 offset:54272
	ds_read_b128 v[202:205], v163 offset:55296
	ds_read_b128 v[206:209], v163 offset:56320
	s_add_u32 s24, s22, 0x40000
	s_addc_u32 s25, s23, 0
	s_mov_b32 s83, m0
	s_mov_b32 m0, s47
	s_nop 0
	global_load_lds_dwordx4 v156, s[24:25]
	s_mov_b32 m0, s83
	s_add_u32 s22, s22, 0x44000
	s_mov_b32 s83, m0
	s_mov_b32 m0, s48
	s_nop 0
	global_load_lds_dwordx4 v158, s[24:25]
	s_mov_b32 m0, s83
	s_addc_u32 s23, s23, 0
	s_mov_b32 s24, m0
	s_mov_b32 m0, s49
	s_nop 0
	global_load_lds_dwordx4 v156, s[22:23]
	s_mov_b32 m0, s24
	s_nop 0
	s_mov_b32 s24, m0
	s_mov_b32 m0, s56
	s_nop 0
	global_load_lds_dwordx4 v158, s[22:23]
	s_mov_b32 m0, s24
	s_waitcnt vmcnt(4)
	s_waitcnt lgkmcnt(0)
	s_barrier
	s_setprio 1
	s_waitcnt lgkmcnt(7)
	v_mfma_f32_16x16x32_bf16 v[62:65], v[134:137], v[178:181], v[62:65]
	v_mfma_f32_16x16x32_bf16 v[58:61], v[142:145], v[178:181], v[58:61]
	s_waitcnt lgkmcnt(5)
	v_mfma_f32_16x16x32_bf16 v[54:57], v[134:137], v[186:189], v[54:57]
	v_mfma_f32_16x16x32_bf16 v[46:49], v[142:145], v[186:189], v[46:49]
	s_waitcnt lgkmcnt(3)
	v_mfma_f32_16x16x32_bf16 v[38:41], v[134:137], v[194:197], v[38:41]
	v_mfma_f32_16x16x32_bf16 v[30:33], v[142:145], v[194:197], v[30:33]
	s_waitcnt lgkmcnt(1)
	v_mfma_f32_16x16x32_bf16 v[22:25], v[134:137], v[202:205], v[22:25]
	v_mfma_f32_16x16x32_bf16 v[14:17], v[142:145], v[202:205], v[14:17]
	v_mfma_f32_16x16x32_bf16 v[62:65], v[138:141], v[182:185], v[62:65]
	v_mfma_f32_16x16x32_bf16 v[58:61], v[146:149], v[182:185], v[58:61]
	v_mfma_f32_16x16x32_bf16 v[54:57], v[138:141], v[190:193], v[54:57]
	v_mfma_f32_16x16x32_bf16 v[46:49], v[146:149], v[190:193], v[46:49]
	v_mfma_f32_16x16x32_bf16 v[38:41], v[138:141], v[198:201], v[38:41]
	v_mfma_f32_16x16x32_bf16 v[30:33], v[146:149], v[198:201], v[30:33]
	s_waitcnt lgkmcnt(0)
	v_mfma_f32_16x16x32_bf16 v[22:25], v[138:141], v[206:209], v[22:25]
	v_mfma_f32_16x16x32_bf16 v[14:17], v[146:149], v[206:209], v[14:17]
	s_setprio 0
	s_setprio 1
	v_mfma_f32_16x16x32_bf16 v[50:53], v[150:153], v[178:181], v[50:53]
	v_mfma_f32_16x16x32_bf16 v[42:45], v[170:173], v[178:181], v[42:45]
	v_mfma_f32_16x16x32_bf16 v[34:37], v[150:153], v[186:189], v[34:37]
	v_mfma_f32_16x16x32_bf16 v[26:29], v[170:173], v[186:189], v[26:29]
	v_mfma_f32_16x16x32_bf16 v[18:21], v[150:153], v[194:197], v[18:21]
	v_mfma_f32_16x16x32_bf16 v[10:13], v[170:173], v[194:197], v[10:13]
	v_mfma_f32_16x16x32_bf16 v[6:9], v[150:153], v[202:205], v[6:9]
	v_mfma_f32_16x16x32_bf16 v[2:5], v[170:173], v[202:205], v[2:5]
	v_mfma_f32_16x16x32_bf16 v[50:53], v[166:169], v[182:185], v[50:53]
	v_mfma_f32_16x16x32_bf16 v[42:45], v[174:177], v[182:185], v[42:45]
	v_mfma_f32_16x16x32_bf16 v[34:37], v[166:169], v[190:193], v[34:37]
	v_mfma_f32_16x16x32_bf16 v[26:29], v[174:177], v[190:193], v[26:29]
	v_mfma_f32_16x16x32_bf16 v[18:21], v[166:169], v[198:201], v[18:21]
	v_mfma_f32_16x16x32_bf16 v[10:13], v[174:177], v[198:201], v[10:13]
	s_setprio 2
	s_barrier
	v_mfma_f32_16x16x32_bf16 v[6:9], v[166:169], v[206:209], v[6:9]
	v_mfma_f32_16x16x32_bf16 v[2:5], v[174:177], v[206:209], v[2:5]
	s_setprio 0
	s_add_i32 s82, s82, 2
	s_add_u32 s78, s78, 0x80000
	s_addc_u32 s79, s79, 0
	s_add_u32 s20, s20, 0x400000
	s_addc_u32 s21, s21, 0
	s_add_u32 s80, s80, 0x400000
	s_addc_u32 s81, s81, 0
	s_cmpk_gt_u32 s82, 0x53
	.p2align 6

.LBB0_653:
	s_ashr_i32 s23, s22, 31
	s_lshl_b64 s[24:25], s[22:23], 20
	s_add_u32 s24, s35, s24
	s_addc_u32 s25, s36, s25
	s_and_b64 s[26:27], s[2:3], exec
	s_cselect_b32 s7, s25, s11
	s_cselect_b32 s9, s24, s10
	s_ashr_i32 s21, s20, 31
	s_lshl_b64 s[26:27], s[20:21], 20
	s_add_u32 s26, s37, s26
	s_addc_u32 s27, s40, s27
	s_and_b64 s[28:29], s[2:3], exec
	s_cselect_b32 s21, s27, s5
	s_cselect_b32 s23, s26, s4
	s_add_u32 s30, s4, 0x100
	s_addc_u32 s31, s5, 0
	s_add_u32 s4, s10, 0x80080
	s_addc_u32 s5, s11, 0
	s_add_u32 s33, s10, 0x100
	s_addc_u32 s73, s11, 0
	s_mov_b32 s74, -2
	s_waitcnt vmcnt(25)
	s_waitcnt vmcnt(24)
	s_waitcnt vmcnt(15)
	s_waitcnt vmcnt(14)
	s_waitcnt vmcnt(13)
	s_waitcnt vmcnt(12)
	s_waitcnt vmcnt(11)
	s_waitcnt vmcnt(10)
	s_waitcnt vmcnt(9)
	s_waitcnt vmcnt(8)
	s_waitcnt vmcnt(7)
	s_waitcnt vmcnt(6)
	s_waitcnt vmcnt(5)
	s_waitcnt vmcnt(4)
	s_waitcnt vmcnt(3)
	s_waitcnt vmcnt(2)
	s_waitcnt vmcnt(1)
	s_waitcnt vmcnt(0)
	ds_read_b128 v[130:133], v161
	ds_read_b128 v[138:141], v161 offset:1024
	ds_read_b128 v[142:145], v161 offset:2048
	ds_read_b128 v[146:149], v161 offset:3072
	ds_read_b128 v[150:153], v162
	ds_read_b128 v[168:171], v162 offset:1024
	ds_read_b128 v[172:175], v162 offset:2048
	ds_read_b128 v[176:179], v162 offset:3072
	s_cmp_eq_u32 s74, 28
	s_cselect_b32 s11, s21, s31
	s_cselect_b32 s10, s23, s30
	s_cselect_b32 s29, s7, s73
	s_cselect_b32 s28, s9, s33
	ds_read_b128 v[180:183], v163
	ds_read_b128 v[184:187], v163 offset:1024
	ds_read_b128 v[188:191], v163 offset:2048
	ds_read_b128 v[192:195], v163 offset:3072
	ds_read_b128 v[196:199], v163 offset:4096
	ds_read_b128 v[200:203], v163 offset:5120
	ds_read_b128 v[204:207], v163 offset:6144
	ds_read_b128 v[208:211], v163 offset:7168
	s_add_u32 s76, s4, 0xfff80000
	s_addc_u32 s77, s5, -1
	s_mov_b32 s75, m0
	s_mov_b32 m0, s80
	s_nop 0
	global_load_lds_dwordx4 v1, s[76:77]
	s_mov_b32 m0, s75
	s_nop 0
	s_mov_b32 s75, m0
	s_mov_b32 m0, s82
	s_nop 0
	global_load_lds_dwordx4 v157, s[76:77]
	s_mov_b32 m0, s75
	s_nop 0
	s_mov_b32 s75, m0
	s_mov_b32 m0, s81
	s_nop 0
	global_load_lds_dwordx4 v1, s[4:5]
	s_mov_b32 m0, s75
	s_nop 0
	s_mov_b32 s75, m0
	s_mov_b32 m0, s83
	s_nop 0
	global_load_lds_dwordx4 v157, s[4:5]
	s_mov_b32 m0, s75
	s_waitcnt vmcnt(8)
	s_waitcnt lgkmcnt(0)
	s_barrier
	s_setprio 1
	s_waitcnt lgkmcnt(7)
	v_mfma_f32_16x16x32_bf16 v[126:129], v[130:133], v[180:183], 0
	v_mfma_f32_16x16x32_bf16 v[122:125], v[142:145], v[180:183], 0
	s_waitcnt lgkmcnt(5)
	v_mfma_f32_16x16x32_bf16 v[110:113], v[130:133], v[188:191], 0
	v_mfma_f32_16x16x32_bf16 v[106:109], v[142:145], v[188:191], 0
	s_waitcnt lgkmcnt(3)
	v_mfma_f32_16x16x32_bf16 v[94:97], v[130:133], v[196:199], 0
	v_mfma_f32_16x16x32_bf16 v[90:93], v[142:145], v[196:199], 0
	s_waitcnt lgkmcnt(1)
	v_mfma_f32_16x16x32_bf16 v[78:81], v[130:133], v[204:207], 0
	v_mfma_f32_16x16x32_bf16 v[74:77], v[142:145], v[204:207], 0
	v_mfma_f32_16x16x32_bf16 v[126:129], v[138:141], v[184:187], v[126:129]
	v_mfma_f32_16x16x32_bf16 v[122:125], v[146:149], v[184:187], v[122:125]
	v_mfma_f32_16x16x32_bf16 v[110:113], v[138:141], v[192:195], v[110:113]
	v_mfma_f32_16x16x32_bf16 v[106:109], v[146:149], v[192:195], v[106:109]
	v_mfma_f32_16x16x32_bf16 v[94:97], v[138:141], v[200:203], v[94:97]
	v_mfma_f32_16x16x32_bf16 v[90:93], v[146:149], v[200:203], v[90:93]
	s_waitcnt lgkmcnt(0)
	v_mfma_f32_16x16x32_bf16 v[78:81], v[138:141], v[208:211], v[78:81]
	v_mfma_f32_16x16x32_bf16 v[74:77], v[146:149], v[208:211], v[74:77]
	s_setprio 0
	s_setprio 1
	v_mfma_f32_16x16x32_bf16 v[118:121], v[150:153], v[180:183], 0
	v_mfma_f32_16x16x32_bf16 v[114:117], v[172:175], v[180:183], 0
	v_mfma_f32_16x16x32_bf16 v[102:105], v[150:153], v[188:191], 0
	v_mfma_f32_16x16x32_bf16 v[98:101], v[172:175], v[188:191], 0
	v_mfma_f32_16x16x32_bf16 v[86:89], v[150:153], v[196:199], 0
	v_mfma_f32_16x16x32_bf16 v[82:85], v[172:175], v[196:199], 0
	v_mfma_f32_16x16x32_bf16 v[70:73], v[150:153], v[204:207], 0
	v_mfma_f32_16x16x32_bf16 v[66:69], v[172:175], v[204:207], 0
	v_mfma_f32_16x16x32_bf16 v[118:121], v[168:171], v[184:187], v[118:121]
	v_mfma_f32_16x16x32_bf16 v[114:117], v[176:179], v[184:187], v[114:117]
	v_mfma_f32_16x16x32_bf16 v[102:105], v[168:171], v[192:195], v[102:105]
	v_mfma_f32_16x16x32_bf16 v[98:101], v[176:179], v[192:195], v[98:101]
	v_mfma_f32_16x16x32_bf16 v[86:89], v[168:171], v[200:203], v[86:89]
	v_mfma_f32_16x16x32_bf16 v[82:85], v[176:179], v[200:203], v[82:85]
	s_setprio 2
	s_barrier
	v_mfma_f32_16x16x32_bf16 v[70:73], v[168:171], v[208:211], v[70:73]
	v_mfma_f32_16x16x32_bf16 v[66:69], v[176:179], v[208:211], v[66:69]
	s_setprio 0
	ds_read_b128 v[180:183], v163 offset:16384
	ds_read_b128 v[184:187], v163 offset:17408
	ds_read_b128 v[188:191], v163 offset:18432
	ds_read_b128 v[192:195], v163 offset:19456
	ds_read_b128 v[196:199], v163 offset:20480
	ds_read_b128 v[200:203], v163 offset:21504
	ds_read_b128 v[204:207], v163 offset:22528
	ds_read_b128 v[208:211], v163 offset:23552
	s_mov_b32 s75, m0
	s_mov_b32 m0, s43
	s_nop 0
	global_load_lds_dwordx4 v156, s[10:11]
	s_mov_b32 m0, s75
	s_add_u32 s76, s10, 0x80000
	s_mov_b32 s75, m0
	s_mov_b32 m0, s46
	s_nop 0
	global_load_lds_dwordx4 v158, s[10:11]
	s_mov_b32 m0, s75
	s_addc_u32 s77, s11, 0
	s_mov_b32 s75, m0
	s_mov_b32 m0, s47
	s_nop 0
	global_load_lds_dwordx4 v156, s[76:77]
	s_mov_b32 m0, s75
	s_nop 0
	s_mov_b32 s75, m0
	s_mov_b32 m0, s48
	s_nop 0
	global_load_lds_dwordx4 v158, s[76:77]
	s_mov_b32 m0, s75
	s_waitcnt vmcnt(4)
	s_waitcnt lgkmcnt(0)
	s_barrier
	s_setprio 1
	s_waitcnt lgkmcnt(7)
	v_mfma_f32_16x16x32_bf16 v[62:65], v[130:133], v[180:183], 0
	v_mfma_f32_16x16x32_bf16 v[58:61], v[142:145], v[180:183], 0
	s_waitcnt lgkmcnt(5)
	v_mfma_f32_16x16x32_bf16 v[46:49], v[130:133], v[188:191], 0
	v_mfma_f32_16x16x32_bf16 v[42:45], v[142:145], v[188:191], 0
	s_waitcnt lgkmcnt(3)
	v_mfma_f32_16x16x32_bf16 v[30:33], v[130:133], v[196:199], 0
	v_mfma_f32_16x16x32_bf16 v[26:29], v[142:145], v[196:199], 0
	s_waitcnt lgkmcnt(1)
	v_mfma_f32_16x16x32_bf16 v[14:17], v[130:133], v[204:207], 0
	v_mfma_f32_16x16x32_bf16 v[10:13], v[142:145], v[204:207], 0
	v_mfma_f32_16x16x32_bf16 v[62:65], v[138:141], v[184:187], v[62:65]
	v_mfma_f32_16x16x32_bf16 v[58:61], v[146:149], v[184:187], v[58:61]
	v_mfma_f32_16x16x32_bf16 v[46:49], v[138:141], v[192:195], v[46:49]
	v_mfma_f32_16x16x32_bf16 v[42:45], v[146:149], v[192:195], v[42:45]
	v_mfma_f32_16x16x32_bf16 v[30:33], v[138:141], v[200:203], v[30:33]
	v_mfma_f32_16x16x32_bf16 v[26:29], v[146:149], v[200:203], v[26:29]
	s_waitcnt lgkmcnt(0)
	v_mfma_f32_16x16x32_bf16 v[14:17], v[138:141], v[208:211], v[14:17]
	v_mfma_f32_16x16x32_bf16 v[10:13], v[146:149], v[208:211], v[10:13]
	s_setprio 0
	s_setprio 1
	v_mfma_f32_16x16x32_bf16 v[54:57], v[150:153], v[180:183], 0
	v_mfma_f32_16x16x32_bf16 v[50:53], v[172:175], v[180:183], 0
	v_mfma_f32_16x16x32_bf16 v[38:41], v[150:153], v[188:191], 0
	v_mfma_f32_16x16x32_bf16 v[34:37], v[172:175], v[188:191], 0
	v_mfma_f32_16x16x32_bf16 v[22:25], v[150:153], v[196:199], 0
	v_mfma_f32_16x16x32_bf16 v[18:21], v[172:175], v[196:199], 0
	v_mfma_f32_16x16x32_bf16 v[6:9], v[150:153], v[204:207], 0
	v_mfma_f32_16x16x32_bf16 v[2:5], v[172:175], v[204:207], 0
	v_mfma_f32_16x16x32_bf16 v[54:57], v[168:171], v[184:187], v[54:57]
	v_mfma_f32_16x16x32_bf16 v[50:53], v[176:179], v[184:187], v[50:53]
	v_mfma_f32_16x16x32_bf16 v[38:41], v[168:171], v[192:195], v[38:41]
	v_mfma_f32_16x16x32_bf16 v[34:37], v[176:179], v[192:195], v[34:37]
	v_mfma_f32_16x16x32_bf16 v[22:25], v[168:171], v[200:203], v[22:25]
	v_mfma_f32_16x16x32_bf16 v[18:21], v[176:179], v[200:203], v[18:21]
	s_setprio 2
	s_barrier
	v_mfma_f32_16x16x32_bf16 v[6:9], v[168:171], v[208:211], v[6:9]
	v_mfma_f32_16x16x32_bf16 v[2:5], v[176:179], v[208:211], v[2:5]
	s_setprio 0
	ds_read_b128 v[130:133], v164
	ds_read_b128 v[138:141], v164 offset:1024
	ds_read_b128 v[142:145], v164 offset:2048
	ds_read_b128 v[146:149], v164 offset:3072
	ds_read_b128 v[150:153], v165
	ds_read_b128 v[168:171], v165 offset:1024
	ds_read_b128 v[172:175], v165 offset:2048
	ds_read_b128 v[176:179], v165 offset:3072
	ds_read_b128 v[180:183], v163 offset:32768
	ds_read_b128 v[184:187], v163 offset:33792
	ds_read_b128 v[188:191], v163 offset:34816
	ds_read_b128 v[192:195], v163 offset:35840
	ds_read_b128 v[196:199], v163 offset:36864
	ds_read_b128 v[200:203], v163 offset:37888
	ds_read_b128 v[204:207], v163 offset:38912
	ds_read_b128 v[208:211], v163 offset:39936
	s_mov_b32 s75, m0
	s_mov_b32 m0, s42
	s_nop 0
	global_load_lds_dwordx4 v1, s[28:29]
	s_mov_b32 m0, s75
	s_nop 0
	s_mov_b32 s75, m0
	s_mov_b32 m0, s49
	s_nop 0
	global_load_lds_dwordx4 v157, s[28:29]
	s_mov_b32 m0, s75
	s_add_u32 s28, s28, 0x80000
	s_addc_u32 s29, s29, 0
	s_mov_b32 s75, m0
	s_mov_b32 m0, s56
	s_nop 0
	global_load_lds_dwordx4 v1, s[28:29]
	s_mov_b32 m0, s75
	s_nop 0
	s_mov_b32 s75, m0
	s_mov_b32 m0, s57
	s_nop 0
	global_load_lds_dwordx4 v157, s[28:29]
	s_mov_b32 m0, s75
	s_waitcnt vmcnt(8)
	s_waitcnt lgkmcnt(0)
	s_barrier
	s_setprio 1
	s_waitcnt lgkmcnt(7)
	v_mfma_f32_16x16x32_bf16 v[126:129], v[130:133], v[180:183], v[126:129]
	v_mfma_f32_16x16x32_bf16 v[122:125], v[142:145], v[180:183], v[122:125]
	s_waitcnt lgkmcnt(5)
	v_mfma_f32_16x16x32_bf16 v[110:113], v[130:133], v[188:191], v[110:113]
	v_mfma_f32_16x16x32_bf16 v[106:109], v[142:145], v[188:191], v[106:109]
	s_waitcnt lgkmcnt(3)
	v_mfma_f32_16x16x32_bf16 v[94:97], v[130:133], v[196:199], v[94:97]
	v_mfma_f32_16x16x32_bf16 v[90:93], v[142:145], v[196:199], v[90:93]
	s_waitcnt lgkmcnt(1)
	v_mfma_f32_16x16x32_bf16 v[78:81], v[130:133], v[204:207], v[78:81]
	v_mfma_f32_16x16x32_bf16 v[74:77], v[142:145], v[204:207], v[74:77]
	v_mfma_f32_16x16x32_bf16 v[126:129], v[138:141], v[184:187], v[126:129]
	v_mfma_f32_16x16x32_bf16 v[122:125], v[146:149], v[184:187], v[122:125]
	v_mfma_f32_16x16x32_bf16 v[110:113], v[138:141], v[192:195], v[110:113]
	v_mfma_f32_16x16x32_bf16 v[106:109], v[146:149], v[192:195], v[106:109]
	v_mfma_f32_16x16x32_bf16 v[94:97], v[138:141], v[200:203], v[94:97]
	v_mfma_f32_16x16x32_bf16 v[90:93], v[146:149], v[200:203], v[90:93]
	s_waitcnt lgkmcnt(0)
	v_mfma_f32_16x16x32_bf16 v[78:81], v[138:141], v[208:211], v[78:81]
	v_mfma_f32_16x16x32_bf16 v[74:77], v[146:149], v[208:211], v[74:77]
	s_setprio 0
	s_setprio 1
	v_mfma_f32_16x16x32_bf16 v[118:121], v[150:153], v[180:183], v[118:121]
	v_mfma_f32_16x16x32_bf16 v[114:117], v[172:175], v[180:183], v[114:117]
	v_mfma_f32_16x16x32_bf16 v[102:105], v[150:153], v[188:191], v[102:105]
	v_mfma_f32_16x16x32_bf16 v[98:101], v[172:175], v[188:191], v[98:101]
	v_mfma_f32_16x16x32_bf16 v[86:89], v[150:153], v[196:199], v[86:89]
	v_mfma_f32_16x16x32_bf16 v[82:85], v[172:175], v[196:199], v[82:85]
	v_mfma_f32_16x16x32_bf16 v[70:73], v[150:153], v[204:207], v[70:73]
	v_mfma_f32_16x16x32_bf16 v[66:69], v[172:175], v[204:207], v[66:69]
	v_mfma_f32_16x16x32_bf16 v[118:121], v[168:171], v[184:187], v[118:121]
	v_mfma_f32_16x16x32_bf16 v[114:117], v[176:179], v[184:187], v[114:117]
	v_mfma_f32_16x16x32_bf16 v[102:105], v[168:171], v[192:195], v[102:105]
	v_mfma_f32_16x16x32_bf16 v[98:101], v[176:179], v[192:195], v[98:101]
	v_mfma_f32_16x16x32_bf16 v[86:89], v[168:171], v[200:203], v[86:89]
	v_mfma_f32_16x16x32_bf16 v[82:85], v[176:179], v[200:203], v[82:85]
	s_setprio 2
	s_barrier
	v_mfma_f32_16x16x32_bf16 v[70:73], v[168:171], v[208:211], v[70:73]
	v_mfma_f32_16x16x32_bf16 v[66:69], v[176:179], v[208:211], v[66:69]
	s_setprio 0
	ds_read_b128 v[180:183], v163 offset:49152
	ds_read_b128 v[184:187], v163 offset:50176
	ds_read_b128 v[188:191], v163 offset:51200
	ds_read_b128 v[192:195], v163 offset:52224
	ds_read_b128 v[196:199], v163 offset:53248
	ds_read_b128 v[200:203], v163 offset:54272
	ds_read_b128 v[204:207], v163 offset:55296
	ds_read_b128 v[208:211], v163 offset:56320
	s_add_u32 s28, s10, 0x80
	s_addc_u32 s29, s11, 0
	s_mov_b32 s75, m0
	s_mov_b32 m0, s64
	s_nop 0
	global_load_lds_dwordx4 v156, s[28:29]
	s_mov_b32 m0, s75
	s_add_u32 s10, s10, 0x80080
	s_mov_b32 s75, m0
	s_mov_b32 m0, s65
	s_nop 0
	global_load_lds_dwordx4 v158, s[28:29]
	s_mov_b32 m0, s75
	s_addc_u32 s11, s11, 0
	s_mov_b32 s28, m0
	s_mov_b32 m0, s66
	s_nop 0
	global_load_lds_dwordx4 v156, s[10:11]
	s_mov_b32 m0, s28
	s_nop 0
	s_mov_b32 s28, m0
	s_mov_b32 m0, s67
	s_nop 0
	global_load_lds_dwordx4 v158, s[10:11]
	s_mov_b32 m0, s28
	s_waitcnt vmcnt(4)
	s_waitcnt lgkmcnt(0)
	s_barrier
	s_setprio 1
	s_waitcnt lgkmcnt(7)
	v_mfma_f32_16x16x32_bf16 v[62:65], v[130:133], v[180:183], v[62:65]
	v_mfma_f32_16x16x32_bf16 v[58:61], v[142:145], v[180:183], v[58:61]
	s_waitcnt lgkmcnt(5)
	v_mfma_f32_16x16x32_bf16 v[46:49], v[130:133], v[188:191], v[46:49]
	v_mfma_f32_16x16x32_bf16 v[42:45], v[142:145], v[188:191], v[42:45]
	s_waitcnt lgkmcnt(3)
	v_mfma_f32_16x16x32_bf16 v[30:33], v[130:133], v[196:199], v[30:33]
	v_mfma_f32_16x16x32_bf16 v[26:29], v[142:145], v[196:199], v[26:29]
	s_waitcnt lgkmcnt(1)
	v_mfma_f32_16x16x32_bf16 v[14:17], v[130:133], v[204:207], v[14:17]
	v_mfma_f32_16x16x32_bf16 v[10:13], v[142:145], v[204:207], v[10:13]
	v_mfma_f32_16x16x32_bf16 v[62:65], v[138:141], v[184:187], v[62:65]
	v_mfma_f32_16x16x32_bf16 v[58:61], v[146:149], v[184:187], v[58:61]
	v_mfma_f32_16x16x32_bf16 v[46:49], v[138:141], v[192:195], v[46:49]
	v_mfma_f32_16x16x32_bf16 v[42:45], v[146:149], v[192:195], v[42:45]
	v_mfma_f32_16x16x32_bf16 v[30:33], v[138:141], v[200:203], v[30:33]
	v_mfma_f32_16x16x32_bf16 v[26:29], v[146:149], v[200:203], v[26:29]
	s_waitcnt lgkmcnt(0)
	v_mfma_f32_16x16x32_bf16 v[14:17], v[138:141], v[208:211], v[14:17]
	v_mfma_f32_16x16x32_bf16 v[10:13], v[146:149], v[208:211], v[10:13]
	s_setprio 0
	s_setprio 1
	v_mfma_f32_16x16x32_bf16 v[54:57], v[150:153], v[180:183], v[54:57]
	v_mfma_f32_16x16x32_bf16 v[50:53], v[172:175], v[180:183], v[50:53]
	v_mfma_f32_16x16x32_bf16 v[38:41], v[150:153], v[188:191], v[38:41]
	v_mfma_f32_16x16x32_bf16 v[34:37], v[172:175], v[188:191], v[34:37]
	v_mfma_f32_16x16x32_bf16 v[22:25], v[150:153], v[196:199], v[22:25]
	v_mfma_f32_16x16x32_bf16 v[18:21], v[172:175], v[196:199], v[18:21]
	v_mfma_f32_16x16x32_bf16 v[6:9], v[150:153], v[204:207], v[6:9]
	v_mfma_f32_16x16x32_bf16 v[2:5], v[172:175], v[204:207], v[2:5]
	v_mfma_f32_16x16x32_bf16 v[54:57], v[168:171], v[184:187], v[54:57]
	v_mfma_f32_16x16x32_bf16 v[50:53], v[176:179], v[184:187], v[50:53]
	v_mfma_f32_16x16x32_bf16 v[38:41], v[168:171], v[192:195], v[38:41]
	v_mfma_f32_16x16x32_bf16 v[34:37], v[176:179], v[192:195], v[34:37]
	v_mfma_f32_16x16x32_bf16 v[22:25], v[168:171], v[200:203], v[22:25]
	v_mfma_f32_16x16x32_bf16 v[18:21], v[176:179], v[200:203], v[18:21]
	s_setprio 2
	s_barrier
	v_mfma_f32_16x16x32_bf16 v[6:9], v[168:171], v[208:211], v[6:9]
	v_mfma_f32_16x16x32_bf16 v[2:5], v[176:179], v[208:211], v[2:5]
	s_setprio 0
	s_add_i32 s74, s74, 2
	s_add_u32 s30, s30, 0x100
	s_addc_u32 s31, s31, 0
	s_add_u32 s4, s4, 0x100
	s_addc_u32 s5, s5, 0
	s_add_u32 s33, s33, 0x100
	s_addc_u32 s73, s73, 0
	s_cmp_gt_u32 s74, 29
	.p2align 6

.LBB0_1052:
	s_ashr_i32 s13, s12, 31
	s_lshl_b64 s[14:15], s[12:13], 20
	s_add_u32 s14, s28, s14
	s_addc_u32 s15, s29, s15
	s_and_b64 s[16:17], s[2:3], exec
	s_cselect_b32 s13, s15, s23
	s_cselect_b32 s67, s14, s22
	s_ashr_i32 s11, s10, 31
	s_lshl_b64 s[16:17], s[10:11], 20
	s_add_u32 s16, s30, s16
	s_addc_u32 s17, s31, s17
	s_and_b64 s[24:25], s[2:3], exec
	s_cselect_b32 s11, s17, s21
	s_cselect_b32 s73, s16, s20
	s_add_u32 s74, s20, 0x100
	s_addc_u32 s75, s21, 0
	s_add_u32 s20, s22, 0x80080
	s_addc_u32 s21, s23, 0
	s_add_u32 s76, s22, 0x100
	s_addc_u32 s77, s23, 0
	s_mov_b32 s78, -2
	s_waitcnt vmcnt(25)
	s_waitcnt vmcnt(24)
	s_waitcnt vmcnt(15)
	s_waitcnt vmcnt(14)
	s_waitcnt vmcnt(13)
	s_waitcnt vmcnt(12)
	s_waitcnt vmcnt(11)
	s_waitcnt vmcnt(10)
	s_waitcnt vmcnt(9)
	s_waitcnt vmcnt(8)
	s_waitcnt vmcnt(7)
	s_waitcnt vmcnt(6)
	s_waitcnt vmcnt(5)
	s_waitcnt vmcnt(4)
	s_waitcnt vmcnt(3)
	s_waitcnt vmcnt(2)
	s_waitcnt vmcnt(1)
	s_waitcnt vmcnt(0)
	ds_read_b128 v[130:133], v181
	ds_read_b128 v[134:137], v181 offset:1024
	ds_read_b128 v[138:141], v181 offset:2048
	ds_read_b128 v[142:145], v181 offset:3072
	ds_read_b128 v[146:149], v182
	ds_read_b128 v[150:153], v182 offset:1024
	ds_read_b128 v[154:157], v182 offset:2048
	ds_read_b128 v[158:161], v182 offset:3072
	s_cmp_eq_u32 s78, 28
	s_cselect_b32 s23, s11, s75
	s_cselect_b32 s22, s73, s74
	s_cselect_b32 s25, s13, s77
	s_cselect_b32 s24, s67, s76
	ds_read_b128 v[166:169], v183
	ds_read_b128 v[170:173], v183 offset:1024
	ds_read_b128 v[186:189], v183 offset:2048
	ds_read_b128 v[190:193], v183 offset:3072
	ds_read_b128 v[194:197], v183 offset:4096
	ds_read_b128 v[198:201], v183 offset:5120
	ds_read_b128 v[202:205], v183 offset:6144
	ds_read_b128 v[206:209], v183 offset:7168
	s_add_u32 s80, s20, 0xfff80000
	s_addc_u32 s81, s21, -1
	s_mov_b32 s79, m0
	s_mov_b32 m0, s58
	s_nop 0
	global_load_lds_dwordx4 v1, s[80:81]
	s_mov_b32 m0, s79
	s_nop 0
	s_mov_b32 s79, m0
	s_mov_b32 m0, s64
	s_nop 0
	global_load_lds_dwordx4 v177, s[80:81]
	s_mov_b32 m0, s79
	s_nop 0
	s_mov_b32 s79, m0
	s_mov_b32 m0, s59
	s_nop 0
	global_load_lds_dwordx4 v1, s[20:21]
	s_mov_b32 m0, s79
	s_nop 0
	s_mov_b32 s79, m0
	s_mov_b32 m0, s65
	s_nop 0
	global_load_lds_dwordx4 v177, s[20:21]
	s_mov_b32 m0, s79
	s_waitcnt vmcnt(8)
	s_waitcnt lgkmcnt(0)
	s_barrier
	s_setprio 1
	s_waitcnt lgkmcnt(7)
	v_mfma_f32_16x16x32_bf16 v[126:129], v[130:133], v[166:169], 0
	v_mfma_f32_16x16x32_bf16 v[122:125], v[138:141], v[166:169], 0
	s_waitcnt lgkmcnt(5)
	v_mfma_f32_16x16x32_bf16 v[118:121], v[130:133], v[186:189], 0
	v_mfma_f32_16x16x32_bf16 v[114:117], v[138:141], v[186:189], 0
	s_waitcnt lgkmcnt(3)
	v_mfma_f32_16x16x32_bf16 v[94:97], v[130:133], v[194:197], 0
	v_mfma_f32_16x16x32_bf16 v[90:93], v[138:141], v[194:197], 0
	s_waitcnt lgkmcnt(1)
	v_mfma_f32_16x16x32_bf16 v[86:89], v[130:133], v[202:205], 0
	v_mfma_f32_16x16x32_bf16 v[78:81], v[138:141], v[202:205], 0
	v_mfma_f32_16x16x32_bf16 v[126:129], v[134:137], v[170:173], v[126:129]
	v_mfma_f32_16x16x32_bf16 v[122:125], v[142:145], v[170:173], v[122:125]
	v_mfma_f32_16x16x32_bf16 v[118:121], v[134:137], v[190:193], v[118:121]
	v_mfma_f32_16x16x32_bf16 v[114:117], v[142:145], v[190:193], v[114:117]
	v_mfma_f32_16x16x32_bf16 v[94:97], v[134:137], v[198:201], v[94:97]
	v_mfma_f32_16x16x32_bf16 v[90:93], v[142:145], v[198:201], v[90:93]
	s_waitcnt lgkmcnt(0)
	v_mfma_f32_16x16x32_bf16 v[86:89], v[134:137], v[206:209], v[86:89]
	v_mfma_f32_16x16x32_bf16 v[78:81], v[142:145], v[206:209], v[78:81]
	s_setprio 0
	s_setprio 1
	v_mfma_f32_16x16x32_bf16 v[110:113], v[146:149], v[166:169], 0
	v_mfma_f32_16x16x32_bf16 v[106:109], v[154:157], v[166:169], 0
	v_mfma_f32_16x16x32_bf16 v[102:105], v[146:149], v[186:189], 0
	v_mfma_f32_16x16x32_bf16 v[98:101], v[154:157], v[186:189], 0
	v_mfma_f32_16x16x32_bf16 v[82:85], v[146:149], v[194:197], 0
	v_mfma_f32_16x16x32_bf16 v[74:77], v[154:157], v[194:197], 0
	v_mfma_f32_16x16x32_bf16 v[70:73], v[146:149], v[202:205], 0
	v_mfma_f32_16x16x32_bf16 v[66:69], v[154:157], v[202:205], 0
	v_mfma_f32_16x16x32_bf16 v[110:113], v[150:153], v[170:173], v[110:113]
	v_mfma_f32_16x16x32_bf16 v[106:109], v[158:161], v[170:173], v[106:109]
	v_mfma_f32_16x16x32_bf16 v[102:105], v[150:153], v[190:193], v[102:105]
	v_mfma_f32_16x16x32_bf16 v[98:101], v[158:161], v[190:193], v[98:101]
	v_mfma_f32_16x16x32_bf16 v[82:85], v[150:153], v[198:201], v[82:85]
	v_mfma_f32_16x16x32_bf16 v[74:77], v[158:161], v[198:201], v[74:77]
	s_setprio 2
	s_barrier
	v_mfma_f32_16x16x32_bf16 v[70:73], v[150:153], v[206:209], v[70:73]
	v_mfma_f32_16x16x32_bf16 v[66:69], v[158:161], v[206:209], v[66:69]
	s_setprio 0
	ds_read_b128 v[166:169], v183 offset:16384
	ds_read_b128 v[170:173], v183 offset:17408
	ds_read_b128 v[186:189], v183 offset:18432
	ds_read_b128 v[190:193], v183 offset:19456
	ds_read_b128 v[194:197], v183 offset:20480
	ds_read_b128 v[198:201], v183 offset:21504
	ds_read_b128 v[202:205], v183 offset:22528
	ds_read_b128 v[206:209], v183 offset:23552
	s_mov_b32 s79, m0
	s_mov_b32 m0, s35
	s_nop 0
	global_load_lds_dwordx4 v176, s[22:23]
	s_mov_b32 m0, s79
	s_add_u32 s80, s22, 0x80000
	s_mov_b32 s79, m0
	s_mov_b32 m0, s36
	s_nop 0
	global_load_lds_dwordx4 v178, s[22:23]
	s_mov_b32 m0, s79
	s_addc_u32 s81, s23, 0
	s_mov_b32 s79, m0
	s_mov_b32 m0, s37
	s_nop 0
	global_load_lds_dwordx4 v176, s[80:81]
	s_mov_b32 m0, s79
	s_nop 0
	s_mov_b32 s79, m0
	s_mov_b32 m0, s40
	s_nop 0
	global_load_lds_dwordx4 v178, s[80:81]
	s_mov_b32 m0, s79
	s_waitcnt vmcnt(4)
	s_waitcnt lgkmcnt(0)
	s_barrier
	s_setprio 1
	s_waitcnt lgkmcnt(7)
	v_mfma_f32_16x16x32_bf16 v[62:65], v[130:133], v[166:169], 0
	v_mfma_f32_16x16x32_bf16 v[58:61], v[138:141], v[166:169], 0
	s_waitcnt lgkmcnt(5)
	v_mfma_f32_16x16x32_bf16 v[46:49], v[130:133], v[186:189], 0
	v_mfma_f32_16x16x32_bf16 v[42:45], v[138:141], v[186:189], 0
	s_waitcnt lgkmcnt(3)
	v_mfma_f32_16x16x32_bf16 v[30:33], v[130:133], v[194:197], 0
	v_mfma_f32_16x16x32_bf16 v[26:29], v[138:141], v[194:197], 0
	s_waitcnt lgkmcnt(1)
	v_mfma_f32_16x16x32_bf16 v[14:17], v[130:133], v[202:205], 0
	v_mfma_f32_16x16x32_bf16 v[10:13], v[138:141], v[202:205], 0
	v_mfma_f32_16x16x32_bf16 v[62:65], v[134:137], v[170:173], v[62:65]
	v_mfma_f32_16x16x32_bf16 v[58:61], v[142:145], v[170:173], v[58:61]
	v_mfma_f32_16x16x32_bf16 v[46:49], v[134:137], v[190:193], v[46:49]
	v_mfma_f32_16x16x32_bf16 v[42:45], v[142:145], v[190:193], v[42:45]
	v_mfma_f32_16x16x32_bf16 v[30:33], v[134:137], v[198:201], v[30:33]
	v_mfma_f32_16x16x32_bf16 v[26:29], v[142:145], v[198:201], v[26:29]
	s_waitcnt lgkmcnt(0)
	v_mfma_f32_16x16x32_bf16 v[14:17], v[134:137], v[206:209], v[14:17]
	v_mfma_f32_16x16x32_bf16 v[10:13], v[142:145], v[206:209], v[10:13]
	s_setprio 0
	s_setprio 1
	v_mfma_f32_16x16x32_bf16 v[54:57], v[146:149], v[166:169], 0
	v_mfma_f32_16x16x32_bf16 v[50:53], v[154:157], v[166:169], 0
	v_mfma_f32_16x16x32_bf16 v[38:41], v[146:149], v[186:189], 0
	v_mfma_f32_16x16x32_bf16 v[34:37], v[154:157], v[186:189], 0
	v_mfma_f32_16x16x32_bf16 v[22:25], v[146:149], v[194:197], 0
	v_mfma_f32_16x16x32_bf16 v[18:21], v[154:157], v[194:197], 0
	v_mfma_f32_16x16x32_bf16 v[6:9], v[146:149], v[202:205], 0
	v_mfma_f32_16x16x32_bf16 v[2:5], v[154:157], v[202:205], 0
	v_mfma_f32_16x16x32_bf16 v[54:57], v[150:153], v[170:173], v[54:57]
	v_mfma_f32_16x16x32_bf16 v[50:53], v[158:161], v[170:173], v[50:53]
	v_mfma_f32_16x16x32_bf16 v[38:41], v[150:153], v[190:193], v[38:41]
	v_mfma_f32_16x16x32_bf16 v[34:37], v[158:161], v[190:193], v[34:37]
	v_mfma_f32_16x16x32_bf16 v[22:25], v[150:153], v[198:201], v[22:25]
	v_mfma_f32_16x16x32_bf16 v[18:21], v[158:161], v[198:201], v[18:21]
	s_setprio 2
	s_barrier
	v_mfma_f32_16x16x32_bf16 v[6:9], v[150:153], v[206:209], v[6:9]
	v_mfma_f32_16x16x32_bf16 v[2:5], v[158:161], v[206:209], v[2:5]
	s_setprio 0
	ds_read_b128 v[130:133], v184
	ds_read_b128 v[134:137], v184 offset:1024
	ds_read_b128 v[138:141], v184 offset:2048
	ds_read_b128 v[142:145], v184 offset:3072
	ds_read_b128 v[146:149], v185
	ds_read_b128 v[150:153], v185 offset:1024
	ds_read_b128 v[154:157], v185 offset:2048
	ds_read_b128 v[158:161], v185 offset:3072
	ds_read_b128 v[166:169], v183 offset:32768
	ds_read_b128 v[170:173], v183 offset:33792
	ds_read_b128 v[186:189], v183 offset:34816
	ds_read_b128 v[190:193], v183 offset:35840
	ds_read_b128 v[194:197], v183 offset:36864
	ds_read_b128 v[198:201], v183 offset:37888
	ds_read_b128 v[202:205], v183 offset:38912
	ds_read_b128 v[206:209], v183 offset:39936
	s_mov_b32 s79, m0
	s_mov_b32 m0, s34
	s_nop 0
	global_load_lds_dwordx4 v1, s[24:25]
	s_mov_b32 m0, s79
	s_nop 0
	s_mov_b32 s79, m0
	s_mov_b32 m0, s41
	s_nop 0
	global_load_lds_dwordx4 v177, s[24:25]
	s_mov_b32 m0, s79
	s_add_u32 s24, s24, 0x80000
	s_addc_u32 s25, s25, 0
	s_mov_b32 s79, m0
	s_mov_b32 m0, s42
	s_nop 0
	global_load_lds_dwordx4 v1, s[24:25]
	s_mov_b32 m0, s79
	s_nop 0
	s_mov_b32 s79, m0
	s_mov_b32 m0, s43
	s_nop 0
	global_load_lds_dwordx4 v177, s[24:25]
	s_mov_b32 m0, s79
	s_waitcnt vmcnt(8)
	s_waitcnt lgkmcnt(0)
	s_barrier
	s_setprio 1
	s_waitcnt lgkmcnt(7)
	v_mfma_f32_16x16x32_bf16 v[126:129], v[130:133], v[166:169], v[126:129]
	v_mfma_f32_16x16x32_bf16 v[122:125], v[138:141], v[166:169], v[122:125]
	s_waitcnt lgkmcnt(5)
	v_mfma_f32_16x16x32_bf16 v[118:121], v[130:133], v[186:189], v[118:121]
	v_mfma_f32_16x16x32_bf16 v[114:117], v[138:141], v[186:189], v[114:117]
	s_waitcnt lgkmcnt(3)
	v_mfma_f32_16x16x32_bf16 v[94:97], v[130:133], v[194:197], v[94:97]
	v_mfma_f32_16x16x32_bf16 v[90:93], v[138:141], v[194:197], v[90:93]
	s_waitcnt lgkmcnt(1)
	v_mfma_f32_16x16x32_bf16 v[86:89], v[130:133], v[202:205], v[86:89]
	v_mfma_f32_16x16x32_bf16 v[78:81], v[138:141], v[202:205], v[78:81]
	v_mfma_f32_16x16x32_bf16 v[126:129], v[134:137], v[170:173], v[126:129]
	v_mfma_f32_16x16x32_bf16 v[122:125], v[142:145], v[170:173], v[122:125]
	v_mfma_f32_16x16x32_bf16 v[118:121], v[134:137], v[190:193], v[118:121]
	v_mfma_f32_16x16x32_bf16 v[114:117], v[142:145], v[190:193], v[114:117]
	v_mfma_f32_16x16x32_bf16 v[94:97], v[134:137], v[198:201], v[94:97]
	v_mfma_f32_16x16x32_bf16 v[90:93], v[142:145], v[198:201], v[90:93]
	s_waitcnt lgkmcnt(0)
	v_mfma_f32_16x16x32_bf16 v[86:89], v[134:137], v[206:209], v[86:89]
	v_mfma_f32_16x16x32_bf16 v[78:81], v[142:145], v[206:209], v[78:81]
	s_setprio 0
	s_setprio 1
	v_mfma_f32_16x16x32_bf16 v[110:113], v[146:149], v[166:169], v[110:113]
	v_mfma_f32_16x16x32_bf16 v[106:109], v[154:157], v[166:169], v[106:109]
	v_mfma_f32_16x16x32_bf16 v[102:105], v[146:149], v[186:189], v[102:105]
	v_mfma_f32_16x16x32_bf16 v[98:101], v[154:157], v[186:189], v[98:101]
	v_mfma_f32_16x16x32_bf16 v[82:85], v[146:149], v[194:197], v[82:85]
	v_mfma_f32_16x16x32_bf16 v[74:77], v[154:157], v[194:197], v[74:77]
	v_mfma_f32_16x16x32_bf16 v[70:73], v[146:149], v[202:205], v[70:73]
	v_mfma_f32_16x16x32_bf16 v[66:69], v[154:157], v[202:205], v[66:69]
	v_mfma_f32_16x16x32_bf16 v[110:113], v[150:153], v[170:173], v[110:113]
	v_mfma_f32_16x16x32_bf16 v[106:109], v[158:161], v[170:173], v[106:109]
	v_mfma_f32_16x16x32_bf16 v[102:105], v[150:153], v[190:193], v[102:105]
	v_mfma_f32_16x16x32_bf16 v[98:101], v[158:161], v[190:193], v[98:101]
	v_mfma_f32_16x16x32_bf16 v[82:85], v[150:153], v[198:201], v[82:85]
	v_mfma_f32_16x16x32_bf16 v[74:77], v[158:161], v[198:201], v[74:77]
	s_setprio 2
	s_barrier
	v_mfma_f32_16x16x32_bf16 v[70:73], v[150:153], v[206:209], v[70:73]
	v_mfma_f32_16x16x32_bf16 v[66:69], v[158:161], v[206:209], v[66:69]
	s_setprio 0
	ds_read_b128 v[166:169], v183 offset:49152
	ds_read_b128 v[170:173], v183 offset:50176
	ds_read_b128 v[186:189], v183 offset:51200
	ds_read_b128 v[190:193], v183 offset:52224
	ds_read_b128 v[194:197], v183 offset:53248
	ds_read_b128 v[198:201], v183 offset:54272
	ds_read_b128 v[202:205], v183 offset:55296
	ds_read_b128 v[206:209], v183 offset:56320
	s_add_u32 s24, s22, 0x80
	s_addc_u32 s25, s23, 0
	s_mov_b32 s79, m0
	s_mov_b32 m0, s46
	s_nop 0
	global_load_lds_dwordx4 v176, s[24:25]
	s_mov_b32 m0, s79
	s_add_u32 s22, s22, 0x80080
	s_mov_b32 s79, m0
	s_mov_b32 m0, s47
	s_nop 0
	global_load_lds_dwordx4 v178, s[24:25]
	s_mov_b32 m0, s79
	s_addc_u32 s23, s23, 0
	s_mov_b32 s24, m0
	s_mov_b32 m0, s48
	s_nop 0
	global_load_lds_dwordx4 v176, s[22:23]
	s_mov_b32 m0, s24
	s_nop 0
	s_mov_b32 s24, m0
	s_mov_b32 m0, s49
	s_nop 0
	global_load_lds_dwordx4 v178, s[22:23]
	s_mov_b32 m0, s24
	s_waitcnt vmcnt(4)
	s_waitcnt lgkmcnt(0)
	s_barrier
	s_setprio 1
	s_waitcnt lgkmcnt(7)
	v_mfma_f32_16x16x32_bf16 v[62:65], v[130:133], v[166:169], v[62:65]
	v_mfma_f32_16x16x32_bf16 v[58:61], v[138:141], v[166:169], v[58:61]
	s_waitcnt lgkmcnt(5)
	v_mfma_f32_16x16x32_bf16 v[46:49], v[130:133], v[186:189], v[46:49]
	v_mfma_f32_16x16x32_bf16 v[42:45], v[138:141], v[186:189], v[42:45]
	s_waitcnt lgkmcnt(3)
	v_mfma_f32_16x16x32_bf16 v[30:33], v[130:133], v[194:197], v[30:33]
	v_mfma_f32_16x16x32_bf16 v[26:29], v[138:141], v[194:197], v[26:29]
	s_waitcnt lgkmcnt(1)
	v_mfma_f32_16x16x32_bf16 v[14:17], v[130:133], v[202:205], v[14:17]
	v_mfma_f32_16x16x32_bf16 v[10:13], v[138:141], v[202:205], v[10:13]
	v_mfma_f32_16x16x32_bf16 v[62:65], v[134:137], v[170:173], v[62:65]
	v_mfma_f32_16x16x32_bf16 v[58:61], v[142:145], v[170:173], v[58:61]
	v_mfma_f32_16x16x32_bf16 v[46:49], v[134:137], v[190:193], v[46:49]
	v_mfma_f32_16x16x32_bf16 v[42:45], v[142:145], v[190:193], v[42:45]
	v_mfma_f32_16x16x32_bf16 v[30:33], v[134:137], v[198:201], v[30:33]
	v_mfma_f32_16x16x32_bf16 v[26:29], v[142:145], v[198:201], v[26:29]
	s_waitcnt lgkmcnt(0)
	v_mfma_f32_16x16x32_bf16 v[14:17], v[134:137], v[206:209], v[14:17]
	v_mfma_f32_16x16x32_bf16 v[10:13], v[142:145], v[206:209], v[10:13]
	s_setprio 0
	s_setprio 1
	v_mfma_f32_16x16x32_bf16 v[54:57], v[146:149], v[166:169], v[54:57]
	v_mfma_f32_16x16x32_bf16 v[50:53], v[154:157], v[166:169], v[50:53]
	v_mfma_f32_16x16x32_bf16 v[38:41], v[146:149], v[186:189], v[38:41]
	v_mfma_f32_16x16x32_bf16 v[34:37], v[154:157], v[186:189], v[34:37]
	v_mfma_f32_16x16x32_bf16 v[22:25], v[146:149], v[194:197], v[22:25]
	v_mfma_f32_16x16x32_bf16 v[18:21], v[154:157], v[194:197], v[18:21]
	v_mfma_f32_16x16x32_bf16 v[6:9], v[146:149], v[202:205], v[6:9]
	v_mfma_f32_16x16x32_bf16 v[2:5], v[154:157], v[202:205], v[2:5]
	v_mfma_f32_16x16x32_bf16 v[54:57], v[150:153], v[170:173], v[54:57]
	v_mfma_f32_16x16x32_bf16 v[50:53], v[158:161], v[170:173], v[50:53]
	v_mfma_f32_16x16x32_bf16 v[38:41], v[150:153], v[190:193], v[38:41]
	v_mfma_f32_16x16x32_bf16 v[34:37], v[158:161], v[190:193], v[34:37]
	v_mfma_f32_16x16x32_bf16 v[22:25], v[150:153], v[198:201], v[22:25]
	v_mfma_f32_16x16x32_bf16 v[18:21], v[158:161], v[198:201], v[18:21]
	s_setprio 2
	s_barrier
	v_mfma_f32_16x16x32_bf16 v[6:9], v[150:153], v[206:209], v[6:9]
	v_mfma_f32_16x16x32_bf16 v[2:5], v[158:161], v[206:209], v[2:5]
	s_setprio 0
	s_add_i32 s78, s78, 2
	s_add_u32 s74, s74, 0x100
	s_addc_u32 s75, s75, 0
	s_add_u32 s20, s20, 0x100
	s_addc_u32 s21, s21, 0
	s_add_u32 s76, s76, 0x100
	s_addc_u32 s77, s77, 0
	s_cmp_gt_u32 s78, 29
	.p2align 6

.LBB0_1223:
	s_ashr_i32 s11, s10, 31
	s_lshl_b64 s[12:13], s[10:11], 20
	s_add_u32 s12, s26, s12
	s_addc_u32 s13, s27, s13
	s_and_b64 s[14:15], s[2:3], exec
	s_cselect_b32 s11, s13, s21
	s_cselect_b32 s66, s12, s20
	s_ashr_i32 s9, s8, 31
	s_lshl_b64 s[14:15], s[8:9], 20
	s_add_u32 s14, s28, s14
	s_addc_u32 s15, s29, s15
	s_and_b64 s[22:23], s[2:3], exec
	s_cselect_b32 s9, s15, s19
	s_cselect_b32 s67, s14, s18
	s_add_u32 s73, s18, 0x100
	s_addc_u32 s74, s19, 0
	s_add_u32 s18, s20, 0x80080
	s_addc_u32 s19, s21, 0
	s_add_u32 s75, s20, 0x100
	s_addc_u32 s76, s21, 0
	s_mov_b32 s77, -2
	ds_read_b128 v[148:151], v143
	ds_read_b128 v[152:155], v143 offset:1024
	ds_read_b128 v[156:159], v143 offset:2048
	ds_read_b128 v[160:163], v143 offset:3072
	ds_read_b128 v[164:167], v144
	ds_read_b128 v[168:171], v144 offset:1024
	ds_read_b128 v[172:175], v144 offset:2048
	ds_read_b128 v[176:179], v144 offset:3072
	s_cmp_eq_u32 s77, 28
	s_cselect_b32 s21, s9, s74
	s_cselect_b32 s20, s67, s73
	s_cselect_b32 s23, s11, s76
	s_cselect_b32 s22, s66, s75
	ds_read_b128 v[180:183], v145
	ds_read_b128 v[184:187], v145 offset:1024
	ds_read_b128 v[188:191], v145 offset:2048
	ds_read_b128 v[192:195], v145 offset:3072
	ds_read_b128 v[196:199], v145 offset:4096
	ds_read_b128 v[200:203], v145 offset:5120
	ds_read_b128 v[204:207], v145 offset:6144
	ds_read_b128 v[208:211], v145 offset:7168
	s_add_u32 s78, s18, 0xfff80000
	s_addc_u32 s79, s19, -1
	s_mov_b32 s80, m0
	s_mov_b32 m0, s56
	s_nop 0
	global_load_lds_dwordx4 v138, s[78:79]
	s_mov_b32 m0, s80
	s_nop 0
	s_mov_b32 s80, m0
	s_mov_b32 m0, s59
	s_nop 0
	global_load_lds_dwordx4 v140, s[78:79]
	s_mov_b32 m0, s80
	s_mov_b32 s78, m0
	s_mov_b32 m0, s57
	s_nop 0
	global_load_lds_dwordx4 v138, s[18:19]
	s_mov_b32 m0, s78
	s_nop 0
	s_mov_b32 s78, m0
	s_mov_b32 m0, s64
	s_nop 0
	global_load_lds_dwordx4 v140, s[18:19]
	s_mov_b32 m0, s78
	s_waitcnt vmcnt(8)
	s_waitcnt lgkmcnt(0)
	s_barrier
	s_setprio 1
	s_waitcnt lgkmcnt(7)
	v_mfma_f32_16x16x32_bf16 v[126:129], v[148:151], v[180:183], 0
	v_mfma_f32_16x16x32_bf16 v[122:125], v[156:159], v[180:183], 0
	s_waitcnt lgkmcnt(5)
	v_mfma_f32_16x16x32_bf16 v[110:113], v[148:151], v[188:191], 0
	v_mfma_f32_16x16x32_bf16 v[106:109], v[156:159], v[188:191], 0
	s_waitcnt lgkmcnt(3)
	v_mfma_f32_16x16x32_bf16 v[94:97], v[148:151], v[196:199], 0
	v_mfma_f32_16x16x32_bf16 v[90:93], v[156:159], v[196:199], 0
	s_waitcnt lgkmcnt(1)
	v_mfma_f32_16x16x32_bf16 v[78:81], v[148:151], v[204:207], 0
	v_mfma_f32_16x16x32_bf16 v[74:77], v[156:159], v[204:207], 0
	v_mfma_f32_16x16x32_bf16 v[126:129], v[152:155], v[184:187], v[126:129]
	v_mfma_f32_16x16x32_bf16 v[122:125], v[160:163], v[184:187], v[122:125]
	v_mfma_f32_16x16x32_bf16 v[110:113], v[152:155], v[192:195], v[110:113]
	v_mfma_f32_16x16x32_bf16 v[106:109], v[160:163], v[192:195], v[106:109]
	v_mfma_f32_16x16x32_bf16 v[94:97], v[152:155], v[200:203], v[94:97]
	v_mfma_f32_16x16x32_bf16 v[90:93], v[160:163], v[200:203], v[90:93]
	s_waitcnt lgkmcnt(0)
	v_mfma_f32_16x16x32_bf16 v[78:81], v[152:155], v[208:211], v[78:81]
	v_mfma_f32_16x16x32_bf16 v[74:77], v[160:163], v[208:211], v[74:77]
	s_setprio 0
	s_setprio 1
	v_mfma_f32_16x16x32_bf16 v[118:121], v[164:167], v[180:183], 0
	v_mfma_f32_16x16x32_bf16 v[114:117], v[172:175], v[180:183], 0
	v_mfma_f32_16x16x32_bf16 v[102:105], v[164:167], v[188:191], 0
	v_mfma_f32_16x16x32_bf16 v[98:101], v[172:175], v[188:191], 0
	v_mfma_f32_16x16x32_bf16 v[86:89], v[164:167], v[196:199], 0
	v_mfma_f32_16x16x32_bf16 v[82:85], v[172:175], v[196:199], 0
	v_mfma_f32_16x16x32_bf16 v[70:73], v[164:167], v[204:207], 0
	v_mfma_f32_16x16x32_bf16 v[66:69], v[172:175], v[204:207], 0
	v_mfma_f32_16x16x32_bf16 v[118:121], v[168:171], v[184:187], v[118:121]
	v_mfma_f32_16x16x32_bf16 v[114:117], v[176:179], v[184:187], v[114:117]
	v_mfma_f32_16x16x32_bf16 v[102:105], v[168:171], v[192:195], v[102:105]
	v_mfma_f32_16x16x32_bf16 v[98:101], v[176:179], v[192:195], v[98:101]
	v_mfma_f32_16x16x32_bf16 v[86:89], v[168:171], v[200:203], v[86:89]
	v_mfma_f32_16x16x32_bf16 v[82:85], v[176:179], v[200:203], v[82:85]
	s_setprio 2
	s_barrier
	v_mfma_f32_16x16x32_bf16 v[70:73], v[168:171], v[208:211], v[70:73]
	v_mfma_f32_16x16x32_bf16 v[66:69], v[176:179], v[208:211], v[66:69]
	s_setprio 0
	ds_read_b128 v[180:183], v145 offset:16384
	ds_read_b128 v[184:187], v145 offset:17408
	ds_read_b128 v[188:191], v145 offset:18432
	ds_read_b128 v[192:195], v145 offset:19456
	ds_read_b128 v[196:199], v145 offset:20480
	ds_read_b128 v[200:203], v145 offset:21504
	ds_read_b128 v[204:207], v145 offset:22528
	ds_read_b128 v[208:211], v145 offset:23552
	s_mov_b32 s78, m0
	s_mov_b32 m0, s35
	s_nop 0
	global_load_lds_dwordx4 v139, s[20:21]
	s_mov_b32 m0, s78
	s_nop 0
	s_mov_b32 s78, m0
	s_mov_b32 m0, s36
	s_nop 0
	global_load_lds_dwordx4 v141, s[20:21]
	s_mov_b32 m0, s78
	s_add_u32 s78, s20, 0x80000
	s_addc_u32 s79, s21, 0
	s_mov_b32 s80, m0
	s_mov_b32 m0, s37
	s_nop 0
	global_load_lds_dwordx4 v139, s[78:79]
	s_mov_b32 m0, s80
	s_nop 0
	s_mov_b32 s80, m0
	s_mov_b32 m0, s40
	s_nop 0
	global_load_lds_dwordx4 v141, s[78:79]
	s_mov_b32 m0, s80
	s_waitcnt vmcnt(4)
	s_waitcnt lgkmcnt(0)
	s_barrier
	s_setprio 1
	s_waitcnt lgkmcnt(7)
	v_mfma_f32_16x16x32_bf16 v[62:65], v[148:151], v[180:183], 0
	v_mfma_f32_16x16x32_bf16 v[58:61], v[156:159], v[180:183], 0
	s_waitcnt lgkmcnt(5)
	v_mfma_f32_16x16x32_bf16 v[46:49], v[148:151], v[188:191], 0
	v_mfma_f32_16x16x32_bf16 v[42:45], v[156:159], v[188:191], 0
	s_waitcnt lgkmcnt(3)
	v_mfma_f32_16x16x32_bf16 v[30:33], v[148:151], v[196:199], 0
	v_mfma_f32_16x16x32_bf16 v[26:29], v[156:159], v[196:199], 0
	s_waitcnt lgkmcnt(1)
	v_mfma_f32_16x16x32_bf16 v[14:17], v[148:151], v[204:207], 0
	v_mfma_f32_16x16x32_bf16 v[10:13], v[156:159], v[204:207], 0
	v_mfma_f32_16x16x32_bf16 v[62:65], v[152:155], v[184:187], v[62:65]
	v_mfma_f32_16x16x32_bf16 v[58:61], v[160:163], v[184:187], v[58:61]
	v_mfma_f32_16x16x32_bf16 v[46:49], v[152:155], v[192:195], v[46:49]
	v_mfma_f32_16x16x32_bf16 v[42:45], v[160:163], v[192:195], v[42:45]
	v_mfma_f32_16x16x32_bf16 v[30:33], v[152:155], v[200:203], v[30:33]
	v_mfma_f32_16x16x32_bf16 v[26:29], v[160:163], v[200:203], v[26:29]
	s_waitcnt lgkmcnt(0)
	v_mfma_f32_16x16x32_bf16 v[14:17], v[152:155], v[208:211], v[14:17]
	v_mfma_f32_16x16x32_bf16 v[10:13], v[160:163], v[208:211], v[10:13]
	s_setprio 0
	s_setprio 1
	v_mfma_f32_16x16x32_bf16 v[54:57], v[164:167], v[180:183], 0
	v_mfma_f32_16x16x32_bf16 v[50:53], v[172:175], v[180:183], 0
	v_mfma_f32_16x16x32_bf16 v[38:41], v[164:167], v[188:191], 0
	v_mfma_f32_16x16x32_bf16 v[34:37], v[172:175], v[188:191], 0
	v_mfma_f32_16x16x32_bf16 v[22:25], v[164:167], v[196:199], 0
	v_mfma_f32_16x16x32_bf16 v[18:21], v[172:175], v[196:199], 0
	v_mfma_f32_16x16x32_bf16 v[6:9], v[164:167], v[204:207], 0
	v_mfma_f32_16x16x32_bf16 v[2:5], v[172:175], v[204:207], 0
	v_mfma_f32_16x16x32_bf16 v[54:57], v[168:171], v[184:187], v[54:57]
	v_mfma_f32_16x16x32_bf16 v[50:53], v[176:179], v[184:187], v[50:53]
	v_mfma_f32_16x16x32_bf16 v[38:41], v[168:171], v[192:195], v[38:41]
	v_mfma_f32_16x16x32_bf16 v[34:37], v[176:179], v[192:195], v[34:37]
	v_mfma_f32_16x16x32_bf16 v[22:25], v[168:171], v[200:203], v[22:25]
	v_mfma_f32_16x16x32_bf16 v[18:21], v[176:179], v[200:203], v[18:21]
	s_setprio 2
	s_barrier
	v_mfma_f32_16x16x32_bf16 v[6:9], v[168:171], v[208:211], v[6:9]
	v_mfma_f32_16x16x32_bf16 v[2:5], v[176:179], v[208:211], v[2:5]
	s_setprio 0
	ds_read_b128 v[148:151], v146
	ds_read_b128 v[152:155], v146 offset:1024
	ds_read_b128 v[156:159], v146 offset:2048
	ds_read_b128 v[160:163], v146 offset:3072
	ds_read_b128 v[164:167], v147
	ds_read_b128 v[168:171], v147 offset:1024
	ds_read_b128 v[172:175], v147 offset:2048
	ds_read_b128 v[176:179], v147 offset:3072
	ds_read_b128 v[180:183], v145 offset:32768
	ds_read_b128 v[184:187], v145 offset:33792
	ds_read_b128 v[188:191], v145 offset:34816
	ds_read_b128 v[192:195], v145 offset:35840
	ds_read_b128 v[196:199], v145 offset:36864
	ds_read_b128 v[200:203], v145 offset:37888
	ds_read_b128 v[204:207], v145 offset:38912
	ds_read_b128 v[208:211], v145 offset:39936
	s_mov_b32 s78, m0
	s_mov_b32 m0, s31
	s_nop 0
	global_load_lds_dwordx4 v138, s[22:23]
	s_mov_b32 m0, s78
	s_nop 0
	s_mov_b32 s78, m0
	s_mov_b32 m0, s41
	s_nop 0
	global_load_lds_dwordx4 v140, s[22:23]
	s_mov_b32 m0, s78
	s_add_u32 s22, s22, 0x80000
	s_addc_u32 s23, s23, 0
	s_mov_b32 s78, m0
	s_mov_b32 m0, s42
	s_nop 0
	global_load_lds_dwordx4 v138, s[22:23]
	s_mov_b32 m0, s78
	s_nop 0
	s_mov_b32 s78, m0
	s_mov_b32 m0, s43
	s_nop 0
	global_load_lds_dwordx4 v140, s[22:23]
	s_mov_b32 m0, s78
	s_waitcnt vmcnt(8)
	s_waitcnt lgkmcnt(0)
	s_barrier
	s_setprio 1
	s_waitcnt lgkmcnt(7)
	v_mfma_f32_16x16x32_bf16 v[126:129], v[148:151], v[180:183], v[126:129]
	v_mfma_f32_16x16x32_bf16 v[122:125], v[156:159], v[180:183], v[122:125]
	s_waitcnt lgkmcnt(5)
	v_mfma_f32_16x16x32_bf16 v[110:113], v[148:151], v[188:191], v[110:113]
	v_mfma_f32_16x16x32_bf16 v[106:109], v[156:159], v[188:191], v[106:109]
	s_waitcnt lgkmcnt(3)
	v_mfma_f32_16x16x32_bf16 v[94:97], v[148:151], v[196:199], v[94:97]
	v_mfma_f32_16x16x32_bf16 v[90:93], v[156:159], v[196:199], v[90:93]
	s_waitcnt lgkmcnt(1)
	v_mfma_f32_16x16x32_bf16 v[78:81], v[148:151], v[204:207], v[78:81]
	v_mfma_f32_16x16x32_bf16 v[74:77], v[156:159], v[204:207], v[74:77]
	v_mfma_f32_16x16x32_bf16 v[126:129], v[152:155], v[184:187], v[126:129]
	v_mfma_f32_16x16x32_bf16 v[122:125], v[160:163], v[184:187], v[122:125]
	v_mfma_f32_16x16x32_bf16 v[110:113], v[152:155], v[192:195], v[110:113]
	v_mfma_f32_16x16x32_bf16 v[106:109], v[160:163], v[192:195], v[106:109]
	v_mfma_f32_16x16x32_bf16 v[94:97], v[152:155], v[200:203], v[94:97]
	v_mfma_f32_16x16x32_bf16 v[90:93], v[160:163], v[200:203], v[90:93]
	s_waitcnt lgkmcnt(0)
	v_mfma_f32_16x16x32_bf16 v[78:81], v[152:155], v[208:211], v[78:81]
	v_mfma_f32_16x16x32_bf16 v[74:77], v[160:163], v[208:211], v[74:77]
	s_setprio 0
	s_setprio 1
	v_mfma_f32_16x16x32_bf16 v[118:121], v[164:167], v[180:183], v[118:121]
	v_mfma_f32_16x16x32_bf16 v[114:117], v[172:175], v[180:183], v[114:117]
	v_mfma_f32_16x16x32_bf16 v[102:105], v[164:167], v[188:191], v[102:105]
	v_mfma_f32_16x16x32_bf16 v[98:101], v[172:175], v[188:191], v[98:101]
	v_mfma_f32_16x16x32_bf16 v[86:89], v[164:167], v[196:199], v[86:89]
	v_mfma_f32_16x16x32_bf16 v[82:85], v[172:175], v[196:199], v[82:85]
	v_mfma_f32_16x16x32_bf16 v[70:73], v[164:167], v[204:207], v[70:73]
	v_mfma_f32_16x16x32_bf16 v[66:69], v[172:175], v[204:207], v[66:69]
	v_mfma_f32_16x16x32_bf16 v[118:121], v[168:171], v[184:187], v[118:121]
	v_mfma_f32_16x16x32_bf16 v[114:117], v[176:179], v[184:187], v[114:117]
	v_mfma_f32_16x16x32_bf16 v[102:105], v[168:171], v[192:195], v[102:105]
	v_mfma_f32_16x16x32_bf16 v[98:101], v[176:179], v[192:195], v[98:101]
	v_mfma_f32_16x16x32_bf16 v[86:89], v[168:171], v[200:203], v[86:89]
	v_mfma_f32_16x16x32_bf16 v[82:85], v[176:179], v[200:203], v[82:85]
	s_setprio 2
	s_barrier
	v_mfma_f32_16x16x32_bf16 v[70:73], v[168:171], v[208:211], v[70:73]
	v_mfma_f32_16x16x32_bf16 v[66:69], v[176:179], v[208:211], v[66:69]
	s_setprio 0
	ds_read_b128 v[180:183], v145 offset:49152
	ds_read_b128 v[184:187], v145 offset:50176
	ds_read_b128 v[188:191], v145 offset:51200
	ds_read_b128 v[192:195], v145 offset:52224
	ds_read_b128 v[196:199], v145 offset:53248
	ds_read_b128 v[200:203], v145 offset:54272
	ds_read_b128 v[204:207], v145 offset:55296
	ds_read_b128 v[208:211], v145 offset:56320
	s_add_u32 s22, s20, 0x80
	s_addc_u32 s23, s21, 0
	s_mov_b32 s78, m0
	s_mov_b32 m0, s46
	s_nop 0
	global_load_lds_dwordx4 v139, s[22:23]
	s_mov_b32 m0, s78
	s_add_u32 s20, s20, 0x80080
	s_mov_b32 s78, m0
	s_mov_b32 m0, s47
	s_nop 0
	global_load_lds_dwordx4 v141, s[22:23]
	s_mov_b32 m0, s78
	s_addc_u32 s21, s21, 0
	s_mov_b32 s22, m0
	s_mov_b32 m0, s48
	s_nop 0
	global_load_lds_dwordx4 v139, s[20:21]
	s_mov_b32 m0, s22
	s_nop 0
	s_mov_b32 s22, m0
	s_mov_b32 m0, s49
	s_nop 0
	global_load_lds_dwordx4 v141, s[20:21]
	s_mov_b32 m0, s22
	s_waitcnt vmcnt(4)
	s_waitcnt lgkmcnt(0)
	s_barrier
	s_setprio 1
	s_waitcnt lgkmcnt(7)
	v_mfma_f32_16x16x32_bf16 v[62:65], v[148:151], v[180:183], v[62:65]
	v_mfma_f32_16x16x32_bf16 v[58:61], v[156:159], v[180:183], v[58:61]
	s_waitcnt lgkmcnt(5)
	v_mfma_f32_16x16x32_bf16 v[46:49], v[148:151], v[188:191], v[46:49]
	v_mfma_f32_16x16x32_bf16 v[42:45], v[156:159], v[188:191], v[42:45]
	s_waitcnt lgkmcnt(3)
	v_mfma_f32_16x16x32_bf16 v[30:33], v[148:151], v[196:199], v[30:33]
	v_mfma_f32_16x16x32_bf16 v[26:29], v[156:159], v[196:199], v[26:29]
	s_waitcnt lgkmcnt(1)
	v_mfma_f32_16x16x32_bf16 v[14:17], v[148:151], v[204:207], v[14:17]
	v_mfma_f32_16x16x32_bf16 v[10:13], v[156:159], v[204:207], v[10:13]
	v_mfma_f32_16x16x32_bf16 v[62:65], v[152:155], v[184:187], v[62:65]
	v_mfma_f32_16x16x32_bf16 v[58:61], v[160:163], v[184:187], v[58:61]
	v_mfma_f32_16x16x32_bf16 v[46:49], v[152:155], v[192:195], v[46:49]
	v_mfma_f32_16x16x32_bf16 v[42:45], v[160:163], v[192:195], v[42:45]
	v_mfma_f32_16x16x32_bf16 v[30:33], v[152:155], v[200:203], v[30:33]
	v_mfma_f32_16x16x32_bf16 v[26:29], v[160:163], v[200:203], v[26:29]
	s_waitcnt lgkmcnt(0)
	v_mfma_f32_16x16x32_bf16 v[14:17], v[152:155], v[208:211], v[14:17]
	v_mfma_f32_16x16x32_bf16 v[10:13], v[160:163], v[208:211], v[10:13]
	s_setprio 0
	s_setprio 1
	v_mfma_f32_16x16x32_bf16 v[54:57], v[164:167], v[180:183], v[54:57]
	v_mfma_f32_16x16x32_bf16 v[50:53], v[172:175], v[180:183], v[50:53]
	v_mfma_f32_16x16x32_bf16 v[38:41], v[164:167], v[188:191], v[38:41]
	v_mfma_f32_16x16x32_bf16 v[34:37], v[172:175], v[188:191], v[34:37]
	v_mfma_f32_16x16x32_bf16 v[22:25], v[164:167], v[196:199], v[22:25]
	v_mfma_f32_16x16x32_bf16 v[18:21], v[172:175], v[196:199], v[18:21]
	v_mfma_f32_16x16x32_bf16 v[6:9], v[164:167], v[204:207], v[6:9]
	v_mfma_f32_16x16x32_bf16 v[2:5], v[172:175], v[204:207], v[2:5]
	v_mfma_f32_16x16x32_bf16 v[54:57], v[168:171], v[184:187], v[54:57]
	v_mfma_f32_16x16x32_bf16 v[50:53], v[176:179], v[184:187], v[50:53]
	v_mfma_f32_16x16x32_bf16 v[38:41], v[168:171], v[192:195], v[38:41]
	v_mfma_f32_16x16x32_bf16 v[34:37], v[176:179], v[192:195], v[34:37]
	v_mfma_f32_16x16x32_bf16 v[22:25], v[168:171], v[200:203], v[22:25]
	v_mfma_f32_16x16x32_bf16 v[18:21], v[176:179], v[200:203], v[18:21]
	s_setprio 2
	s_barrier
	v_mfma_f32_16x16x32_bf16 v[6:9], v[168:171], v[208:211], v[6:9]
	v_mfma_f32_16x16x32_bf16 v[2:5], v[176:179], v[208:211], v[2:5]
	s_setprio 0
	s_add_i32 s77, s77, 2
	s_add_u32 s73, s73, 0x100
	s_addc_u32 s74, s74, 0
	s_add_u32 s18, s18, 0x100
	s_addc_u32 s19, s19, 0
	s_add_u32 s75, s75, 0x100
	s_addc_u32 s76, s76, 0
	s_cmp_gt_u32 s77, 29
	.p2align 6

.LBB0_1356:
	s_ashr_i32 s13, s12, 31
	s_lshl_b64 s[14:15], s[12:13], 15
	s_add_u32 s14, s28, s14
	s_addc_u32 s15, s29, s15
	s_and_b64 s[16:17], s[2:3], exec
	s_cselect_b32 s13, s15, s23
	s_cselect_b32 s67, s14, s22
	s_ashr_i32 s11, s10, 31
	s_lshl_b64 s[16:17], s[10:11], 15
	s_add_u32 s16, s30, s16
	s_addc_u32 s17, s31, s17
	s_and_b64 s[24:25], s[2:3], exec
	s_cselect_b32 s11, s17, s21
	s_cselect_b32 s73, s16, s20
	s_add_u32 s74, s20, 0x80000
	s_addc_u32 s75, s21, 0
	s_add_u32 s20, s22, 0x204000
	s_addc_u32 s21, s23, 0
	s_add_u32 s76, s22, 0x400000
	s_addc_u32 s77, s23, 0
	s_mov_b32 s78, -2
	s_waitcnt vmcnt(25)
	s_waitcnt vmcnt(24)
	s_waitcnt vmcnt(15)
	s_waitcnt vmcnt(14)
	s_waitcnt vmcnt(13)
	s_waitcnt vmcnt(12)
	s_waitcnt vmcnt(11)
	s_waitcnt vmcnt(10)
	s_waitcnt vmcnt(9)
	s_waitcnt vmcnt(8)
	s_waitcnt vmcnt(7)
	s_waitcnt vmcnt(6)
	s_waitcnt vmcnt(5)
	s_waitcnt vmcnt(4)
	s_waitcnt vmcnt(3)
	s_waitcnt vmcnt(2)
	s_waitcnt vmcnt(1)
	s_waitcnt vmcnt(0)
	ds_read_b128 v[130:133], v181
	ds_read_b128 v[134:137], v181 offset:1024
	ds_read_b128 v[138:141], v181 offset:2048
	ds_read_b128 v[142:145], v181 offset:3072
	ds_read_b128 v[150:153], v182
	ds_read_b128 v[154:157], v182 offset:1024
	ds_read_b128 v[158:161], v182 offset:2048
	ds_read_b128 v[162:165], v182 offset:3072
	s_cmpk_eq_i32 s78, 0x52
	s_cselect_b32 s23, s11, s75
	s_cselect_b32 s22, s73, s74
	s_cselect_b32 s25, s13, s77
	s_cselect_b32 s24, s67, s76
	ds_read_b128 v[166:169], v183
	ds_read_b128 v[170:173], v183 offset:1024
	ds_read_b128 v[186:189], v183 offset:2048
	ds_read_b128 v[190:193], v183 offset:3072
	ds_read_b128 v[194:197], v183 offset:4096
	ds_read_b128 v[198:201], v183 offset:5120
	ds_read_b128 v[202:205], v183 offset:6144
	ds_read_b128 v[206:209], v183 offset:7168
	s_add_u32 s80, s20, 0xffffc000
	s_addc_u32 s81, s21, -1
	s_mov_b32 s79, m0
	s_mov_b32 m0, s58
	s_nop 0
	global_load_lds_dwordx4 v1, s[80:81]
	s_mov_b32 m0, s79
	s_nop 0
	s_mov_b32 s79, m0
	s_mov_b32 m0, s64
	s_nop 0
	global_load_lds_dwordx4 v177, s[80:81]
	s_mov_b32 m0, s79
	s_nop 0
	s_mov_b32 s79, m0
	s_mov_b32 m0, s59
	s_nop 0
	global_load_lds_dwordx4 v1, s[20:21]
	s_mov_b32 m0, s79
	s_nop 0
	s_mov_b32 s79, m0
	s_mov_b32 m0, s65
	s_nop 0
	global_load_lds_dwordx4 v177, s[20:21]
	s_mov_b32 m0, s79
	s_waitcnt vmcnt(8)
	s_waitcnt lgkmcnt(0)
	s_barrier
	s_setprio 1
	s_waitcnt lgkmcnt(7)
	v_mfma_f32_16x16x32_bf16 v[126:129], v[130:133], v[166:169], 0
	v_mfma_f32_16x16x32_bf16 v[122:125], v[138:141], v[166:169], 0
	s_waitcnt lgkmcnt(5)
	v_mfma_f32_16x16x32_bf16 v[118:121], v[130:133], v[186:189], 0
	v_mfma_f32_16x16x32_bf16 v[110:113], v[138:141], v[186:189], 0
	s_waitcnt lgkmcnt(3)
	v_mfma_f32_16x16x32_bf16 v[94:97], v[130:133], v[194:197], 0
	v_mfma_f32_16x16x32_bf16 v[90:93], v[138:141], v[194:197], 0
	s_waitcnt lgkmcnt(1)
	v_mfma_f32_16x16x32_bf16 v[86:89], v[130:133], v[202:205], 0
	v_mfma_f32_16x16x32_bf16 v[78:81], v[138:141], v[202:205], 0
	v_mfma_f32_16x16x32_bf16 v[126:129], v[134:137], v[170:173], v[126:129]
	v_mfma_f32_16x16x32_bf16 v[122:125], v[142:145], v[170:173], v[122:125]
	v_mfma_f32_16x16x32_bf16 v[118:121], v[134:137], v[190:193], v[118:121]
	v_mfma_f32_16x16x32_bf16 v[110:113], v[142:145], v[190:193], v[110:113]
	v_mfma_f32_16x16x32_bf16 v[94:97], v[134:137], v[198:201], v[94:97]
	v_mfma_f32_16x16x32_bf16 v[90:93], v[142:145], v[198:201], v[90:93]
	s_waitcnt lgkmcnt(0)
	v_mfma_f32_16x16x32_bf16 v[86:89], v[134:137], v[206:209], v[86:89]
	v_mfma_f32_16x16x32_bf16 v[78:81], v[142:145], v[206:209], v[78:81]
	s_setprio 0
	s_setprio 1
	v_mfma_f32_16x16x32_bf16 v[114:117], v[150:153], v[166:169], 0
	v_mfma_f32_16x16x32_bf16 v[106:109], v[158:161], v[166:169], 0
	v_mfma_f32_16x16x32_bf16 v[102:105], v[150:153], v[186:189], 0
	v_mfma_f32_16x16x32_bf16 v[98:101], v[158:161], v[186:189], 0
	v_mfma_f32_16x16x32_bf16 v[82:85], v[150:153], v[194:197], 0
	v_mfma_f32_16x16x32_bf16 v[74:77], v[158:161], v[194:197], 0
	v_mfma_f32_16x16x32_bf16 v[70:73], v[150:153], v[202:205], 0
	v_mfma_f32_16x16x32_bf16 v[66:69], v[158:161], v[202:205], 0
	v_mfma_f32_16x16x32_bf16 v[114:117], v[154:157], v[170:173], v[114:117]
	v_mfma_f32_16x16x32_bf16 v[106:109], v[162:165], v[170:173], v[106:109]
	v_mfma_f32_16x16x32_bf16 v[102:105], v[154:157], v[190:193], v[102:105]
	v_mfma_f32_16x16x32_bf16 v[98:101], v[162:165], v[190:193], v[98:101]
	v_mfma_f32_16x16x32_bf16 v[82:85], v[154:157], v[198:201], v[82:85]
	v_mfma_f32_16x16x32_bf16 v[74:77], v[162:165], v[198:201], v[74:77]
	s_setprio 2
	s_barrier
	v_mfma_f32_16x16x32_bf16 v[70:73], v[154:157], v[206:209], v[70:73]
	v_mfma_f32_16x16x32_bf16 v[66:69], v[162:165], v[206:209], v[66:69]
	s_setprio 0
	ds_read_b128 v[166:169], v183 offset:16384
	ds_read_b128 v[170:173], v183 offset:17408
	ds_read_b128 v[186:189], v183 offset:18432
	ds_read_b128 v[190:193], v183 offset:19456
	ds_read_b128 v[194:197], v183 offset:20480
	ds_read_b128 v[198:201], v183 offset:21504
	ds_read_b128 v[202:205], v183 offset:22528
	ds_read_b128 v[206:209], v183 offset:23552
	s_mov_b32 s79, m0
	s_mov_b32 m0, s35
	s_nop 0
	global_load_lds_dwordx4 v176, s[22:23]
	s_mov_b32 m0, s79
	s_add_u32 s80, s22, 0x4000
	s_mov_b32 s79, m0
	s_mov_b32 m0, s36
	s_nop 0
	global_load_lds_dwordx4 v178, s[22:23]
	s_mov_b32 m0, s79
	s_addc_u32 s81, s23, 0
	s_mov_b32 s79, m0
	s_mov_b32 m0, s37
	s_nop 0
	global_load_lds_dwordx4 v176, s[80:81]
	s_mov_b32 m0, s79
	s_nop 0
	s_mov_b32 s79, m0
	s_mov_b32 m0, s40
	s_nop 0
	global_load_lds_dwordx4 v178, s[80:81]
	s_mov_b32 m0, s79
	s_waitcnt vmcnt(4)
	s_waitcnt lgkmcnt(0)
	s_barrier
	s_setprio 1
	s_waitcnt lgkmcnt(7)
	v_mfma_f32_16x16x32_bf16 v[62:65], v[130:133], v[166:169], 0
	v_mfma_f32_16x16x32_bf16 v[58:61], v[138:141], v[166:169], 0
	s_waitcnt lgkmcnt(5)
	v_mfma_f32_16x16x32_bf16 v[46:49], v[130:133], v[186:189], 0
	v_mfma_f32_16x16x32_bf16 v[42:45], v[138:141], v[186:189], 0
	s_waitcnt lgkmcnt(3)
	v_mfma_f32_16x16x32_bf16 v[30:33], v[130:133], v[194:197], 0
	v_mfma_f32_16x16x32_bf16 v[26:29], v[138:141], v[194:197], 0
	s_waitcnt lgkmcnt(1)
	v_mfma_f32_16x16x32_bf16 v[14:17], v[130:133], v[202:205], 0
	v_mfma_f32_16x16x32_bf16 v[10:13], v[138:141], v[202:205], 0
	v_mfma_f32_16x16x32_bf16 v[62:65], v[134:137], v[170:173], v[62:65]
	v_mfma_f32_16x16x32_bf16 v[58:61], v[142:145], v[170:173], v[58:61]
	v_mfma_f32_16x16x32_bf16 v[46:49], v[134:137], v[190:193], v[46:49]
	v_mfma_f32_16x16x32_bf16 v[42:45], v[142:145], v[190:193], v[42:45]
	v_mfma_f32_16x16x32_bf16 v[30:33], v[134:137], v[198:201], v[30:33]
	v_mfma_f32_16x16x32_bf16 v[26:29], v[142:145], v[198:201], v[26:29]
	s_waitcnt lgkmcnt(0)
	v_mfma_f32_16x16x32_bf16 v[14:17], v[134:137], v[206:209], v[14:17]
	v_mfma_f32_16x16x32_bf16 v[10:13], v[142:145], v[206:209], v[10:13]
	s_setprio 0
	s_setprio 1
	v_mfma_f32_16x16x32_bf16 v[54:57], v[150:153], v[166:169], 0
	v_mfma_f32_16x16x32_bf16 v[50:53], v[158:161], v[166:169], 0
	v_mfma_f32_16x16x32_bf16 v[38:41], v[150:153], v[186:189], 0
	v_mfma_f32_16x16x32_bf16 v[34:37], v[158:161], v[186:189], 0
	v_mfma_f32_16x16x32_bf16 v[22:25], v[150:153], v[194:197], 0
	v_mfma_f32_16x16x32_bf16 v[18:21], v[158:161], v[194:197], 0
	v_mfma_f32_16x16x32_bf16 v[6:9], v[150:153], v[202:205], 0
	v_mfma_f32_16x16x32_bf16 v[2:5], v[158:161], v[202:205], 0
	v_mfma_f32_16x16x32_bf16 v[54:57], v[154:157], v[170:173], v[54:57]
	v_mfma_f32_16x16x32_bf16 v[50:53], v[162:165], v[170:173], v[50:53]
	v_mfma_f32_16x16x32_bf16 v[38:41], v[154:157], v[190:193], v[38:41]
	v_mfma_f32_16x16x32_bf16 v[34:37], v[162:165], v[190:193], v[34:37]
	v_mfma_f32_16x16x32_bf16 v[22:25], v[154:157], v[198:201], v[22:25]
	v_mfma_f32_16x16x32_bf16 v[18:21], v[162:165], v[198:201], v[18:21]
	s_setprio 2
	s_barrier
	v_mfma_f32_16x16x32_bf16 v[6:9], v[154:157], v[206:209], v[6:9]
	v_mfma_f32_16x16x32_bf16 v[2:5], v[162:165], v[206:209], v[2:5]
	s_setprio 0
	ds_read_b128 v[130:133], v184
	ds_read_b128 v[134:137], v184 offset:1024
	ds_read_b128 v[138:141], v184 offset:2048
	ds_read_b128 v[142:145], v184 offset:3072
	ds_read_b128 v[150:153], v185
	ds_read_b128 v[154:157], v185 offset:1024
	ds_read_b128 v[158:161], v185 offset:2048
	ds_read_b128 v[162:165], v185 offset:3072
	ds_read_b128 v[166:169], v183 offset:32768
	ds_read_b128 v[170:173], v183 offset:33792
	ds_read_b128 v[186:189], v183 offset:34816
	ds_read_b128 v[190:193], v183 offset:35840
	ds_read_b128 v[194:197], v183 offset:36864
	ds_read_b128 v[198:201], v183 offset:37888
	ds_read_b128 v[202:205], v183 offset:38912
	ds_read_b128 v[206:209], v183 offset:39936
	s_mov_b32 s79, m0
	s_mov_b32 m0, s34
	s_nop 0
	global_load_lds_dwordx4 v1, s[24:25]
	s_mov_b32 m0, s79
	s_nop 0
	s_mov_b32 s79, m0
	s_mov_b32 m0, s41
	s_nop 0
	global_load_lds_dwordx4 v177, s[24:25]
	s_mov_b32 m0, s79
	s_add_u32 s24, s24, 0x4000
	s_addc_u32 s25, s25, 0
	s_mov_b32 s79, m0
	s_mov_b32 m0, s42
	s_nop 0
	global_load_lds_dwordx4 v1, s[24:25]
	s_mov_b32 m0, s79
	s_nop 0
	s_mov_b32 s79, m0
	s_mov_b32 m0, s43
	s_nop 0
	global_load_lds_dwordx4 v177, s[24:25]
	s_mov_b32 m0, s79
	s_waitcnt vmcnt(8)
	s_waitcnt lgkmcnt(0)
	s_barrier
	s_setprio 1
	s_waitcnt lgkmcnt(7)
	v_mfma_f32_16x16x32_bf16 v[126:129], v[130:133], v[166:169], v[126:129]
	v_mfma_f32_16x16x32_bf16 v[122:125], v[138:141], v[166:169], v[122:125]
	s_waitcnt lgkmcnt(5)
	v_mfma_f32_16x16x32_bf16 v[118:121], v[130:133], v[186:189], v[118:121]
	v_mfma_f32_16x16x32_bf16 v[110:113], v[138:141], v[186:189], v[110:113]
	s_waitcnt lgkmcnt(3)
	v_mfma_f32_16x16x32_bf16 v[94:97], v[130:133], v[194:197], v[94:97]
	v_mfma_f32_16x16x32_bf16 v[90:93], v[138:141], v[194:197], v[90:93]
	s_waitcnt lgkmcnt(1)
	v_mfma_f32_16x16x32_bf16 v[86:89], v[130:133], v[202:205], v[86:89]
	v_mfma_f32_16x16x32_bf16 v[78:81], v[138:141], v[202:205], v[78:81]
	v_mfma_f32_16x16x32_bf16 v[126:129], v[134:137], v[170:173], v[126:129]
	v_mfma_f32_16x16x32_bf16 v[122:125], v[142:145], v[170:173], v[122:125]
	v_mfma_f32_16x16x32_bf16 v[118:121], v[134:137], v[190:193], v[118:121]
	v_mfma_f32_16x16x32_bf16 v[110:113], v[142:145], v[190:193], v[110:113]
	v_mfma_f32_16x16x32_bf16 v[94:97], v[134:137], v[198:201], v[94:97]
	v_mfma_f32_16x16x32_bf16 v[90:93], v[142:145], v[198:201], v[90:93]
	s_waitcnt lgkmcnt(0)
	v_mfma_f32_16x16x32_bf16 v[86:89], v[134:137], v[206:209], v[86:89]
	v_mfma_f32_16x16x32_bf16 v[78:81], v[142:145], v[206:209], v[78:81]
	s_setprio 0
	s_setprio 1
	v_mfma_f32_16x16x32_bf16 v[114:117], v[150:153], v[166:169], v[114:117]
	v_mfma_f32_16x16x32_bf16 v[106:109], v[158:161], v[166:169], v[106:109]
	v_mfma_f32_16x16x32_bf16 v[102:105], v[150:153], v[186:189], v[102:105]
	v_mfma_f32_16x16x32_bf16 v[98:101], v[158:161], v[186:189], v[98:101]
	v_mfma_f32_16x16x32_bf16 v[82:85], v[150:153], v[194:197], v[82:85]
	v_mfma_f32_16x16x32_bf16 v[74:77], v[158:161], v[194:197], v[74:77]
	v_mfma_f32_16x16x32_bf16 v[70:73], v[150:153], v[202:205], v[70:73]
	v_mfma_f32_16x16x32_bf16 v[66:69], v[158:161], v[202:205], v[66:69]
	v_mfma_f32_16x16x32_bf16 v[114:117], v[154:157], v[170:173], v[114:117]
	v_mfma_f32_16x16x32_bf16 v[106:109], v[162:165], v[170:173], v[106:109]
	v_mfma_f32_16x16x32_bf16 v[102:105], v[154:157], v[190:193], v[102:105]
	v_mfma_f32_16x16x32_bf16 v[98:101], v[162:165], v[190:193], v[98:101]
	v_mfma_f32_16x16x32_bf16 v[82:85], v[154:157], v[198:201], v[82:85]
	v_mfma_f32_16x16x32_bf16 v[74:77], v[162:165], v[198:201], v[74:77]
	s_setprio 2
	s_barrier
	v_mfma_f32_16x16x32_bf16 v[70:73], v[154:157], v[206:209], v[70:73]
	v_mfma_f32_16x16x32_bf16 v[66:69], v[162:165], v[206:209], v[66:69]
	s_setprio 0
	ds_read_b128 v[166:169], v183 offset:49152
	ds_read_b128 v[170:173], v183 offset:50176
	ds_read_b128 v[186:189], v183 offset:51200
	ds_read_b128 v[190:193], v183 offset:52224
	ds_read_b128 v[194:197], v183 offset:53248
	ds_read_b128 v[198:201], v183 offset:54272
	ds_read_b128 v[202:205], v183 offset:55296
	ds_read_b128 v[206:209], v183 offset:56320
	s_add_u32 s24, s22, 0x40000
	s_addc_u32 s25, s23, 0
	s_mov_b32 s79, m0
	s_mov_b32 m0, s46
	s_nop 0
	global_load_lds_dwordx4 v176, s[24:25]
	s_mov_b32 m0, s79
	s_add_u32 s22, s22, 0x44000
	s_mov_b32 s79, m0
	s_mov_b32 m0, s47
	s_nop 0
	global_load_lds_dwordx4 v178, s[24:25]
	s_mov_b32 m0, s79
	s_addc_u32 s23, s23, 0
	s_mov_b32 s24, m0
	s_mov_b32 m0, s48
	s_nop 0
	global_load_lds_dwordx4 v176, s[22:23]
	s_mov_b32 m0, s24
	s_nop 0
	s_mov_b32 s24, m0
	s_mov_b32 m0, s49
	s_nop 0
	global_load_lds_dwordx4 v178, s[22:23]
	s_mov_b32 m0, s24
	s_waitcnt vmcnt(4)
	s_waitcnt lgkmcnt(0)
	s_barrier
	s_setprio 1
	s_waitcnt lgkmcnt(7)
	v_mfma_f32_16x16x32_bf16 v[62:65], v[130:133], v[166:169], v[62:65]
	v_mfma_f32_16x16x32_bf16 v[58:61], v[138:141], v[166:169], v[58:61]
	s_waitcnt lgkmcnt(5)
	v_mfma_f32_16x16x32_bf16 v[46:49], v[130:133], v[186:189], v[46:49]
	v_mfma_f32_16x16x32_bf16 v[42:45], v[138:141], v[186:189], v[42:45]
	s_waitcnt lgkmcnt(3)
	v_mfma_f32_16x16x32_bf16 v[30:33], v[130:133], v[194:197], v[30:33]
	v_mfma_f32_16x16x32_bf16 v[26:29], v[138:141], v[194:197], v[26:29]
	s_waitcnt lgkmcnt(1)
	v_mfma_f32_16x16x32_bf16 v[14:17], v[130:133], v[202:205], v[14:17]
	v_mfma_f32_16x16x32_bf16 v[10:13], v[138:141], v[202:205], v[10:13]
	v_mfma_f32_16x16x32_bf16 v[62:65], v[134:137], v[170:173], v[62:65]
	v_mfma_f32_16x16x32_bf16 v[58:61], v[142:145], v[170:173], v[58:61]
	v_mfma_f32_16x16x32_bf16 v[46:49], v[134:137], v[190:193], v[46:49]
	v_mfma_f32_16x16x32_bf16 v[42:45], v[142:145], v[190:193], v[42:45]
	v_mfma_f32_16x16x32_bf16 v[30:33], v[134:137], v[198:201], v[30:33]
	v_mfma_f32_16x16x32_bf16 v[26:29], v[142:145], v[198:201], v[26:29]
	s_waitcnt lgkmcnt(0)
	v_mfma_f32_16x16x32_bf16 v[14:17], v[134:137], v[206:209], v[14:17]
	v_mfma_f32_16x16x32_bf16 v[10:13], v[142:145], v[206:209], v[10:13]
	s_setprio 0
	s_setprio 1
	v_mfma_f32_16x16x32_bf16 v[54:57], v[150:153], v[166:169], v[54:57]
	v_mfma_f32_16x16x32_bf16 v[50:53], v[158:161], v[166:169], v[50:53]
	v_mfma_f32_16x16x32_bf16 v[38:41], v[150:153], v[186:189], v[38:41]
	v_mfma_f32_16x16x32_bf16 v[34:37], v[158:161], v[186:189], v[34:37]
	v_mfma_f32_16x16x32_bf16 v[22:25], v[150:153], v[194:197], v[22:25]
	v_mfma_f32_16x16x32_bf16 v[18:21], v[158:161], v[194:197], v[18:21]
	v_mfma_f32_16x16x32_bf16 v[6:9], v[150:153], v[202:205], v[6:9]
	v_mfma_f32_16x16x32_bf16 v[2:5], v[158:161], v[202:205], v[2:5]
	v_mfma_f32_16x16x32_bf16 v[54:57], v[154:157], v[170:173], v[54:57]
	v_mfma_f32_16x16x32_bf16 v[50:53], v[162:165], v[170:173], v[50:53]
	v_mfma_f32_16x16x32_bf16 v[38:41], v[154:157], v[190:193], v[38:41]
	v_mfma_f32_16x16x32_bf16 v[34:37], v[162:165], v[190:193], v[34:37]
	v_mfma_f32_16x16x32_bf16 v[22:25], v[154:157], v[198:201], v[22:25]
	v_mfma_f32_16x16x32_bf16 v[18:21], v[162:165], v[198:201], v[18:21]
	s_setprio 2
	s_barrier
	v_mfma_f32_16x16x32_bf16 v[6:9], v[154:157], v[206:209], v[6:9]
	v_mfma_f32_16x16x32_bf16 v[2:5], v[162:165], v[206:209], v[2:5]
	s_setprio 0
	s_add_i32 s78, s78, 2
	s_add_u32 s74, s74, 0x80000
	s_addc_u32 s75, s75, 0
	s_add_u32 s20, s20, 0x400000
	s_addc_u32 s21, s21, 0
	s_add_u32 s76, s76, 0x400000
	s_addc_u32 s77, s77, 0
	s_cmpk_gt_u32 s78, 0x53
	.p2align 6

.LBB0_1537:
	s_ashr_i32 s23, s22, 31
	s_lshl_b64 s[24:25], s[22:23], 20
	s_add_u32 s24, s41, s24
	s_addc_u32 s25, s42, s25
	s_and_b64 s[26:27], s[4:5], exec
	s_cselect_b32 s7, s25, s35
	s_cselect_b32 s23, s24, s34
	s_ashr_i32 s21, s20, 31
	s_lshl_b64 s[26:27], s[20:21], 20
	s_add_u32 s26, s43, s26
	s_addc_u32 s27, s46, s27
	s_and_b64 s[36:37], s[4:5], exec
	s_cselect_b32 s21, s27, s31
	s_cselect_b32 s29, s26, s30
	s_add_u32 s79, s30, 0x100
	s_addc_u32 s80, s31, 0
	s_add_u32 s30, s34, 0x80080
	s_addc_u32 s31, s35, 0
	s_add_u32 s81, s34, 0x100
	s_addc_u32 s82, s35, 0
	s_mov_b32 s83, -2
	s_waitcnt vmcnt(25)
	s_waitcnt vmcnt(24)
	s_waitcnt vmcnt(4)
	s_waitcnt vmcnt(14)
	s_waitcnt vmcnt(13)
	s_waitcnt vmcnt(12)
	s_waitcnt vmcnt(2)
	s_waitcnt vmcnt(10)
	s_waitcnt vmcnt(9)
	s_waitcnt vmcnt(8)
	s_waitcnt vmcnt(7)
	s_waitcnt vmcnt(6)
	s_waitcnt vmcnt(5)
	s_waitcnt vmcnt(4)
	s_waitcnt vmcnt(3)
	s_waitcnt vmcnt(2)
	s_waitcnt vmcnt(1)
	s_waitcnt vmcnt(0)
	ds_read_b128 v[46:49], v182
	ds_read_b128 v[54:57], v182 offset:1024
	ds_read_b128 v[58:61], v182 offset:2048
	ds_read_b128 v[62:65], v182 offset:3072
	ds_read_b128 v[146:149], v183
	ds_read_b128 v[150:153], v183 offset:1024
	ds_read_b128 v[154:157], v183 offset:2048
	ds_read_b128 v[158:161], v183 offset:3072
	s_cmp_eq_u32 s83, 28
	s_cselect_b32 s35, s21, s80
	s_cselect_b32 s34, s29, s79
	s_cselect_b32 s37, s7, s82
	s_cselect_b32 s36, s23, s81
	ds_read_b128 v[170:173], v184
	ds_read_b128 v[188:191], v184 offset:1024
	ds_read_b128 v[192:195], v184 offset:2048
	ds_read_b128 v[196:199], v184 offset:3072
	ds_read_b128 v[200:203], v184 offset:4096
	ds_read_b128 v[204:207], v184 offset:5120
	ds_read_b128 v[208:211], v184 offset:6144
	ds_read_b128 v[212:215], v184 offset:7168
	s_add_u32 s86, s30, 0xfff80000
	s_addc_u32 s87, s31, -1
	s_mov_b32 s92, m0
	s_mov_b32 m0, s73
	s_nop 0
	global_load_lds_dwordx4 v176, s[86:87]
	s_mov_b32 m0, s92
	s_nop 0
	s_mov_b32 s92, m0
	s_mov_b32 m0, s75
	s_nop 0
	global_load_lds_dwordx4 v178, s[86:87]
	s_mov_b32 m0, s92
	s_mov_b32 s86, m0
	s_mov_b32 m0, s74
	s_nop 0
	global_load_lds_dwordx4 v176, s[30:31]
	s_mov_b32 m0, s86
	s_nop 0
	s_mov_b32 s86, m0
	s_mov_b32 m0, s76
	s_nop 0
	global_load_lds_dwordx4 v178, s[30:31]
	s_mov_b32 m0, s86
	s_waitcnt vmcnt(8)
	s_waitcnt lgkmcnt(0)
	s_barrier
	s_setprio 1
	s_waitcnt lgkmcnt(7)
	v_mfma_f32_16x16x32_bf16 v[142:145], v[46:49], v[170:173], 0
	v_mfma_f32_16x16x32_bf16 v[138:141], v[58:61], v[170:173], 0
	s_waitcnt lgkmcnt(5)
	v_mfma_f32_16x16x32_bf16 v[126:129], v[46:49], v[192:195], 0
	v_mfma_f32_16x16x32_bf16 v[122:125], v[58:61], v[192:195], 0
	s_waitcnt lgkmcnt(3)
	v_mfma_f32_16x16x32_bf16 v[110:113], v[46:49], v[200:203], 0
	v_mfma_f32_16x16x32_bf16 v[106:109], v[58:61], v[200:203], 0
	s_waitcnt lgkmcnt(1)
	v_mfma_f32_16x16x32_bf16 v[94:97], v[46:49], v[208:211], 0
	v_mfma_f32_16x16x32_bf16 v[90:93], v[58:61], v[208:211], 0
	v_mfma_f32_16x16x32_bf16 v[142:145], v[54:57], v[188:191], v[142:145]
	v_mfma_f32_16x16x32_bf16 v[138:141], v[62:65], v[188:191], v[138:141]
	v_mfma_f32_16x16x32_bf16 v[126:129], v[54:57], v[196:199], v[126:129]
	v_mfma_f32_16x16x32_bf16 v[122:125], v[62:65], v[196:199], v[122:125]
	v_mfma_f32_16x16x32_bf16 v[110:113], v[54:57], v[204:207], v[110:113]
	v_mfma_f32_16x16x32_bf16 v[106:109], v[62:65], v[204:207], v[106:109]
	s_waitcnt lgkmcnt(0)
	v_mfma_f32_16x16x32_bf16 v[94:97], v[54:57], v[212:215], v[94:97]
	v_mfma_f32_16x16x32_bf16 v[90:93], v[62:65], v[212:215], v[90:93]
	s_setprio 0
	s_setprio 1
	v_mfma_f32_16x16x32_bf16 v[134:137], v[146:149], v[170:173], 0
	v_mfma_f32_16x16x32_bf16 v[130:133], v[154:157], v[170:173], 0
	v_mfma_f32_16x16x32_bf16 v[118:121], v[146:149], v[192:195], 0
	v_mfma_f32_16x16x32_bf16 v[114:117], v[154:157], v[192:195], 0
	v_mfma_f32_16x16x32_bf16 v[102:105], v[146:149], v[200:203], 0
	v_mfma_f32_16x16x32_bf16 v[98:101], v[154:157], v[200:203], 0
	v_mfma_f32_16x16x32_bf16 v[86:89], v[146:149], v[208:211], 0
	v_mfma_f32_16x16x32_bf16 v[82:85], v[154:157], v[208:211], 0
	v_mfma_f32_16x16x32_bf16 v[134:137], v[150:153], v[188:191], v[134:137]
	v_mfma_f32_16x16x32_bf16 v[130:133], v[158:161], v[188:191], v[130:133]
	v_mfma_f32_16x16x32_bf16 v[118:121], v[150:153], v[196:199], v[118:121]
	v_mfma_f32_16x16x32_bf16 v[114:117], v[158:161], v[196:199], v[114:117]
	v_mfma_f32_16x16x32_bf16 v[102:105], v[150:153], v[204:207], v[102:105]
	v_mfma_f32_16x16x32_bf16 v[98:101], v[158:161], v[204:207], v[98:101]
	s_setprio 2
	s_barrier
	v_mfma_f32_16x16x32_bf16 v[86:89], v[150:153], v[212:215], v[86:89]
	v_mfma_f32_16x16x32_bf16 v[82:85], v[158:161], v[212:215], v[82:85]
	s_setprio 0
	ds_read_b128 v[170:173], v184 offset:16384
	ds_read_b128 v[188:191], v184 offset:17408
	ds_read_b128 v[192:195], v184 offset:18432
	ds_read_b128 v[196:199], v184 offset:19456
	ds_read_b128 v[200:203], v184 offset:20480
	ds_read_b128 v[204:207], v184 offset:21504
	ds_read_b128 v[208:211], v184 offset:22528
	ds_read_b128 v[212:215], v184 offset:23552
	s_mov_b32 s86, m0
	s_mov_b32 m0, s49
	s_nop 0
	global_load_lds_dwordx4 v177, s[34:35]
	s_mov_b32 m0, s86
	s_nop 0
	s_mov_b32 s86, m0
	s_mov_b32 m0, s56
	s_nop 0
	global_load_lds_dwordx4 v179, s[34:35]
	s_mov_b32 m0, s86
	s_add_u32 s86, s34, 0x80000
	s_addc_u32 s87, s35, 0
	s_mov_b32 s92, m0
	s_mov_b32 m0, s57
	s_nop 0
	global_load_lds_dwordx4 v177, s[86:87]
	s_mov_b32 m0, s92
	s_nop 0
	s_mov_b32 s92, m0
	s_mov_b32 m0, s58
	s_nop 0
	global_load_lds_dwordx4 v179, s[86:87]
	s_mov_b32 m0, s92
	s_waitcnt vmcnt(4)
	s_waitcnt lgkmcnt(0)
	s_barrier
	s_setprio 1
	s_waitcnt lgkmcnt(7)
	v_mfma_f32_16x16x32_bf16 v[78:81], v[46:49], v[170:173], 0
	v_mfma_f32_16x16x32_bf16 v[74:77], v[58:61], v[170:173], 0
	s_waitcnt lgkmcnt(5)
	v_mfma_f32_16x16x32_bf16 v[50:53], v[46:49], v[192:195], 0
	v_mfma_f32_16x16x32_bf16 v[42:45], v[58:61], v[192:195], 0
	s_waitcnt lgkmcnt(3)
	v_mfma_f32_16x16x32_bf16 v[30:33], v[46:49], v[200:203], 0
	v_mfma_f32_16x16x32_bf16 v[26:29], v[58:61], v[200:203], 0
	s_waitcnt lgkmcnt(1)
	v_mfma_f32_16x16x32_bf16 v[14:17], v[46:49], v[208:211], 0
	v_mfma_f32_16x16x32_bf16 v[10:13], v[58:61], v[208:211], 0
	v_mfma_f32_16x16x32_bf16 v[78:81], v[54:57], v[188:191], v[78:81]
	v_mfma_f32_16x16x32_bf16 v[74:77], v[62:65], v[188:191], v[74:77]
	v_mfma_f32_16x16x32_bf16 v[50:53], v[54:57], v[196:199], v[50:53]
	v_mfma_f32_16x16x32_bf16 v[42:45], v[62:65], v[196:199], v[42:45]
	v_mfma_f32_16x16x32_bf16 v[30:33], v[54:57], v[204:207], v[30:33]
	v_mfma_f32_16x16x32_bf16 v[26:29], v[62:65], v[204:207], v[26:29]
	s_waitcnt lgkmcnt(0)
	v_mfma_f32_16x16x32_bf16 v[14:17], v[54:57], v[212:215], v[14:17]
	v_mfma_f32_16x16x32_bf16 v[10:13], v[62:65], v[212:215], v[10:13]
	s_setprio 0
	s_setprio 1
	v_mfma_f32_16x16x32_bf16 v[38:41], v[146:149], v[192:195], 0
	v_mfma_f32_16x16x32_bf16 v[34:37], v[154:157], v[192:195], 0
	v_mfma_f32_16x16x32_bf16 v[22:25], v[146:149], v[200:203], 0
	v_mfma_f32_16x16x32_bf16 v[18:21], v[154:157], v[200:203], 0
	v_mfma_f32_16x16x32_bf16 v[6:9], v[146:149], v[208:211], 0
	v_mfma_f32_16x16x32_bf16 v[2:5], v[154:157], v[208:211], 0
	v_mfma_f32_16x16x32_bf16 v[46:49], v[146:149], v[170:173], 0
	v_mfma_f32_16x16x32_bf16 v[54:57], v[154:157], v[170:173], 0
	v_mfma_f32_16x16x32_bf16 v[38:41], v[150:153], v[196:199], v[38:41]
	v_mfma_f32_16x16x32_bf16 v[34:37], v[158:161], v[196:199], v[34:37]
	v_mfma_f32_16x16x32_bf16 v[22:25], v[150:153], v[204:207], v[22:25]
	v_mfma_f32_16x16x32_bf16 v[18:21], v[158:161], v[204:207], v[18:21]
	v_mfma_f32_16x16x32_bf16 v[6:9], v[150:153], v[212:215], v[6:9]
	v_mfma_f32_16x16x32_bf16 v[2:5], v[158:161], v[212:215], v[2:5]
	s_setprio 2
	s_barrier
	v_mfma_f32_16x16x32_bf16 v[46:49], v[150:153], v[188:191], v[46:49]
	v_mfma_f32_16x16x32_bf16 v[54:57], v[158:161], v[188:191], v[54:57]
	s_setprio 0
	ds_read_b128 v[58:61], v185
	ds_read_b128 v[62:65], v185 offset:1024
	ds_read_b128 v[66:69], v185 offset:2048
	ds_read_b128 v[70:73], v185 offset:3072
	ds_read_b128 v[146:149], v186
	ds_read_b128 v[150:153], v186 offset:1024
	ds_read_b128 v[154:157], v186 offset:2048
	ds_read_b128 v[158:161], v186 offset:3072
	ds_read_b128 v[170:173], v184 offset:32768
	ds_read_b128 v[188:191], v184 offset:33792
	ds_read_b128 v[192:195], v184 offset:34816
	ds_read_b128 v[196:199], v184 offset:35840
	ds_read_b128 v[200:203], v184 offset:36864
	ds_read_b128 v[204:207], v184 offset:37888
	ds_read_b128 v[208:211], v184 offset:38912
	ds_read_b128 v[212:215], v184 offset:39936
	s_mov_b32 s86, m0
	s_mov_b32 m0, s48
	s_nop 0
	global_load_lds_dwordx4 v176, s[36:37]
	s_mov_b32 m0, s86
	s_nop 0
	s_mov_b32 s86, m0
	s_mov_b32 m0, s59
	s_nop 0
	global_load_lds_dwordx4 v178, s[36:37]
	s_mov_b32 m0, s86
	s_add_u32 s36, s36, 0x80000
	s_addc_u32 s37, s37, 0
	s_mov_b32 s86, m0
	s_mov_b32 m0, s62
	s_nop 0
	global_load_lds_dwordx4 v176, s[36:37]
	s_mov_b32 m0, s86
	s_nop 0
	s_mov_b32 s86, m0
	s_mov_b32 m0, s63
	s_nop 0
	global_load_lds_dwordx4 v178, s[36:37]
	s_mov_b32 m0, s86
	s_waitcnt vmcnt(8)
	s_waitcnt lgkmcnt(0)
	s_barrier
	s_setprio 1
	s_waitcnt lgkmcnt(7)
	v_mfma_f32_16x16x32_bf16 v[142:145], v[58:61], v[170:173], v[142:145]
	v_mfma_f32_16x16x32_bf16 v[138:141], v[66:69], v[170:173], v[138:141]
	s_waitcnt lgkmcnt(5)
	v_mfma_f32_16x16x32_bf16 v[126:129], v[58:61], v[192:195], v[126:129]
	v_mfma_f32_16x16x32_bf16 v[122:125], v[66:69], v[192:195], v[122:125]
	s_waitcnt lgkmcnt(3)
	v_mfma_f32_16x16x32_bf16 v[110:113], v[58:61], v[200:203], v[110:113]
	v_mfma_f32_16x16x32_bf16 v[106:109], v[66:69], v[200:203], v[106:109]
	s_waitcnt lgkmcnt(1)
	v_mfma_f32_16x16x32_bf16 v[94:97], v[58:61], v[208:211], v[94:97]
	v_mfma_f32_16x16x32_bf16 v[90:93], v[66:69], v[208:211], v[90:93]
	v_mfma_f32_16x16x32_bf16 v[142:145], v[62:65], v[188:191], v[142:145]
	v_mfma_f32_16x16x32_bf16 v[138:141], v[70:73], v[188:191], v[138:141]
	v_mfma_f32_16x16x32_bf16 v[126:129], v[62:65], v[196:199], v[126:129]
	v_mfma_f32_16x16x32_bf16 v[122:125], v[70:73], v[196:199], v[122:125]
	v_mfma_f32_16x16x32_bf16 v[110:113], v[62:65], v[204:207], v[110:113]
	v_mfma_f32_16x16x32_bf16 v[106:109], v[70:73], v[204:207], v[106:109]
	s_waitcnt lgkmcnt(0)
	v_mfma_f32_16x16x32_bf16 v[94:97], v[62:65], v[212:215], v[94:97]
	v_mfma_f32_16x16x32_bf16 v[90:93], v[70:73], v[212:215], v[90:93]
	s_setprio 0
	s_setprio 1
	v_mfma_f32_16x16x32_bf16 v[134:137], v[146:149], v[170:173], v[134:137]
	v_mfma_f32_16x16x32_bf16 v[130:133], v[154:157], v[170:173], v[130:133]
	v_mfma_f32_16x16x32_bf16 v[118:121], v[146:149], v[192:195], v[118:121]
	v_mfma_f32_16x16x32_bf16 v[114:117], v[154:157], v[192:195], v[114:117]
	v_mfma_f32_16x16x32_bf16 v[102:105], v[146:149], v[200:203], v[102:105]
	v_mfma_f32_16x16x32_bf16 v[98:101], v[154:157], v[200:203], v[98:101]
	v_mfma_f32_16x16x32_bf16 v[86:89], v[146:149], v[208:211], v[86:89]
	v_mfma_f32_16x16x32_bf16 v[82:85], v[154:157], v[208:211], v[82:85]
	v_mfma_f32_16x16x32_bf16 v[134:137], v[150:153], v[188:191], v[134:137]
	v_mfma_f32_16x16x32_bf16 v[130:133], v[158:161], v[188:191], v[130:133]
	v_mfma_f32_16x16x32_bf16 v[118:121], v[150:153], v[196:199], v[118:121]
	v_mfma_f32_16x16x32_bf16 v[114:117], v[158:161], v[196:199], v[114:117]
	v_mfma_f32_16x16x32_bf16 v[102:105], v[150:153], v[204:207], v[102:105]
	v_mfma_f32_16x16x32_bf16 v[98:101], v[158:161], v[204:207], v[98:101]
	s_setprio 2
	s_barrier
	v_mfma_f32_16x16x32_bf16 v[86:89], v[150:153], v[212:215], v[86:89]
	v_mfma_f32_16x16x32_bf16 v[82:85], v[158:161], v[212:215], v[82:85]
	s_setprio 0
	ds_read_b128 v[170:173], v184 offset:49152
	ds_read_b128 v[188:191], v184 offset:50176
	ds_read_b128 v[192:195], v184 offset:51200
	ds_read_b128 v[196:199], v184 offset:52224
	ds_read_b128 v[200:203], v184 offset:53248
	ds_read_b128 v[204:207], v184 offset:54272
	ds_read_b128 v[208:211], v184 offset:55296
	ds_read_b128 v[212:215], v184 offset:56320
	s_add_u32 s36, s34, 0x80
	s_addc_u32 s37, s35, 0
	s_mov_b32 s86, m0
	s_mov_b32 m0, s64
	s_nop 0
	global_load_lds_dwordx4 v177, s[36:37]
	s_mov_b32 m0, s86
	s_add_u32 s34, s34, 0x80080
	s_mov_b32 s86, m0
	s_mov_b32 m0, s65
	s_nop 0
	global_load_lds_dwordx4 v179, s[36:37]
	s_mov_b32 m0, s86
	s_addc_u32 s35, s35, 0
	s_mov_b32 s36, m0
	s_mov_b32 m0, s66
	s_nop 0
	global_load_lds_dwordx4 v177, s[34:35]
	s_mov_b32 m0, s36
	s_nop 0
	s_mov_b32 s36, m0
	s_mov_b32 m0, s67
	s_nop 0
	global_load_lds_dwordx4 v179, s[34:35]
	s_mov_b32 m0, s36
	s_waitcnt vmcnt(4)
	s_waitcnt lgkmcnt(0)
	s_barrier
	s_setprio 1
	s_waitcnt lgkmcnt(7)
	v_mfma_f32_16x16x32_bf16 v[78:81], v[58:61], v[170:173], v[78:81]
	v_mfma_f32_16x16x32_bf16 v[74:77], v[66:69], v[170:173], v[74:77]
	s_waitcnt lgkmcnt(5)
	v_mfma_f32_16x16x32_bf16 v[50:53], v[58:61], v[192:195], v[50:53]
	v_mfma_f32_16x16x32_bf16 v[42:45], v[66:69], v[192:195], v[42:45]
	s_waitcnt lgkmcnt(3)
	v_mfma_f32_16x16x32_bf16 v[30:33], v[58:61], v[200:203], v[30:33]
	v_mfma_f32_16x16x32_bf16 v[26:29], v[66:69], v[200:203], v[26:29]
	s_waitcnt lgkmcnt(1)
	v_mfma_f32_16x16x32_bf16 v[14:17], v[58:61], v[208:211], v[14:17]
	v_mfma_f32_16x16x32_bf16 v[10:13], v[66:69], v[208:211], v[10:13]
	v_mfma_f32_16x16x32_bf16 v[78:81], v[62:65], v[188:191], v[78:81]
	v_mfma_f32_16x16x32_bf16 v[74:77], v[70:73], v[188:191], v[74:77]
	v_mfma_f32_16x16x32_bf16 v[50:53], v[62:65], v[196:199], v[50:53]
	v_mfma_f32_16x16x32_bf16 v[42:45], v[70:73], v[196:199], v[42:45]
	v_mfma_f32_16x16x32_bf16 v[30:33], v[62:65], v[204:207], v[30:33]
	v_mfma_f32_16x16x32_bf16 v[26:29], v[70:73], v[204:207], v[26:29]
	s_waitcnt lgkmcnt(0)
	v_mfma_f32_16x16x32_bf16 v[14:17], v[62:65], v[212:215], v[14:17]
	v_mfma_f32_16x16x32_bf16 v[10:13], v[70:73], v[212:215], v[10:13]
	s_setprio 0
	s_setprio 1
	v_mfma_f32_16x16x32_bf16 v[46:49], v[146:149], v[170:173], v[46:49]
	v_mfma_f32_16x16x32_bf16 v[70:73], v[150:153], v[188:191], v[46:49]
	v_mfma_f32_16x16x32_bf16 v[46:49], v[154:157], v[170:173], v[54:57]
	v_mfma_f32_16x16x32_bf16 v[38:41], v[146:149], v[192:195], v[38:41]
	v_mfma_f32_16x16x32_bf16 v[34:37], v[154:157], v[192:195], v[34:37]
	v_mfma_f32_16x16x32_bf16 v[22:25], v[146:149], v[200:203], v[22:25]
	v_mfma_f32_16x16x32_bf16 v[18:21], v[154:157], v[200:203], v[18:21]
	v_mfma_f32_16x16x32_bf16 v[6:9], v[146:149], v[208:211], v[6:9]
	v_mfma_f32_16x16x32_bf16 v[2:5], v[154:157], v[208:211], v[2:5]
	v_mfma_f32_16x16x32_bf16 v[66:69], v[158:161], v[188:191], v[46:49]
	v_mfma_f32_16x16x32_bf16 v[38:41], v[150:153], v[196:199], v[38:41]
	v_mfma_f32_16x16x32_bf16 v[34:37], v[158:161], v[196:199], v[34:37]
	v_mfma_f32_16x16x32_bf16 v[22:25], v[150:153], v[204:207], v[22:25]
	v_mfma_f32_16x16x32_bf16 v[18:21], v[158:161], v[204:207], v[18:21]
	s_setprio 2
	s_barrier
	v_mfma_f32_16x16x32_bf16 v[6:9], v[150:153], v[212:215], v[6:9]
	v_mfma_f32_16x16x32_bf16 v[2:5], v[158:161], v[212:215], v[2:5]
	s_setprio 0
	s_add_i32 s83, s83, 2
	s_add_u32 s79, s79, 0x100
	s_addc_u32 s80, s80, 0
	s_add_u32 s30, s30, 0x100
	s_addc_u32 s31, s31, 0
	s_add_u32 s81, s81, 0x100
	s_addc_u32 s82, s82, 0
	s_cmp_gt_u32 s83, 29
	.p2align 6

.LBB0_1784:
	s_ashr_i32 s11, s10, 31
	s_lshl_b64 s[12:13], s[10:11], 20
	s_add_u32 s12, s26, s12
	s_addc_u32 s13, s27, s13
	s_and_b64 s[14:15], s[2:3], exec
	s_cselect_b32 s11, s13, s21
	s_cselect_b32 s64, s12, s20
	s_ashr_i32 s9, s8, 31
	s_lshl_b64 s[14:15], s[8:9], 20
	s_add_u32 s14, s28, s14
	s_addc_u32 s15, s29, s15
	s_and_b64 s[22:23], s[2:3], exec
	s_cselect_b32 s9, s15, s19
	s_cselect_b32 s65, s14, s18
	s_add_u32 s66, s18, 0x100
	s_addc_u32 s67, s19, 0
	s_add_u32 s18, s20, 0x80080
	s_addc_u32 s19, s21, 0
	s_add_u32 s70, s20, 0x100
	s_addc_u32 s71, s21, 0
	s_mov_b32 s73, -2
	ds_read_b128 v[148:151], v143
	ds_read_b128 v[152:155], v143 offset:1024
	ds_read_b128 v[156:159], v143 offset:2048
	ds_read_b128 v[160:163], v143 offset:3072
	ds_read_b128 v[164:167], v144
	ds_read_b128 v[168:171], v144 offset:1024
	ds_read_b128 v[172:175], v144 offset:2048
	ds_read_b128 v[176:179], v144 offset:3072
	s_cmp_eq_u32 s73, 28
	s_cselect_b32 s21, s9, s67
	s_cselect_b32 s20, s65, s66
	s_cselect_b32 s23, s11, s71
	s_cselect_b32 s22, s64, s70
	ds_read_b128 v[180:183], v145
	ds_read_b128 v[184:187], v145 offset:1024
	ds_read_b128 v[188:191], v145 offset:2048
	ds_read_b128 v[192:195], v145 offset:3072
	ds_read_b128 v[196:199], v145 offset:4096
	ds_read_b128 v[200:203], v145 offset:5120
	ds_read_b128 v[204:207], v145 offset:6144
	ds_read_b128 v[208:211], v145 offset:7168
	s_add_u32 s74, s18, 0xfff80000
	s_addc_u32 s75, s19, -1
	s_mov_b32 s76, m0
	s_mov_b32 m0, s56
	s_nop 0
	global_load_lds_dwordx4 v138, s[74:75]
	s_mov_b32 m0, s76
	s_nop 0
	s_mov_b32 s76, m0
	s_mov_b32 m0, s59
	s_nop 0
	global_load_lds_dwordx4 v140, s[74:75]
	s_mov_b32 m0, s76
	s_mov_b32 s74, m0
	s_mov_b32 m0, s57
	s_nop 0
	global_load_lds_dwordx4 v138, s[18:19]
	s_mov_b32 m0, s74
	s_nop 0
	s_mov_b32 s74, m0
	s_mov_b32 m0, s62
	s_nop 0
	global_load_lds_dwordx4 v140, s[18:19]
	s_mov_b32 m0, s74
	s_waitcnt vmcnt(8)
	s_waitcnt lgkmcnt(0)
	s_barrier
	s_setprio 1
	s_waitcnt lgkmcnt(7)
	v_mfma_f32_16x16x32_bf16 v[126:129], v[148:151], v[180:183], 0
	v_mfma_f32_16x16x32_bf16 v[122:125], v[156:159], v[180:183], 0
	s_waitcnt lgkmcnt(5)
	v_mfma_f32_16x16x32_bf16 v[110:113], v[148:151], v[188:191], 0
	v_mfma_f32_16x16x32_bf16 v[106:109], v[156:159], v[188:191], 0
	s_waitcnt lgkmcnt(3)
	v_mfma_f32_16x16x32_bf16 v[94:97], v[148:151], v[196:199], 0
	v_mfma_f32_16x16x32_bf16 v[90:93], v[156:159], v[196:199], 0
	s_waitcnt lgkmcnt(1)
	v_mfma_f32_16x16x32_bf16 v[78:81], v[148:151], v[204:207], 0
	v_mfma_f32_16x16x32_bf16 v[74:77], v[156:159], v[204:207], 0
	v_mfma_f32_16x16x32_bf16 v[126:129], v[152:155], v[184:187], v[126:129]
	v_mfma_f32_16x16x32_bf16 v[122:125], v[160:163], v[184:187], v[122:125]
	v_mfma_f32_16x16x32_bf16 v[110:113], v[152:155], v[192:195], v[110:113]
	v_mfma_f32_16x16x32_bf16 v[106:109], v[160:163], v[192:195], v[106:109]
	v_mfma_f32_16x16x32_bf16 v[94:97], v[152:155], v[200:203], v[94:97]
	v_mfma_f32_16x16x32_bf16 v[90:93], v[160:163], v[200:203], v[90:93]
	s_waitcnt lgkmcnt(0)
	v_mfma_f32_16x16x32_bf16 v[78:81], v[152:155], v[208:211], v[78:81]
	v_mfma_f32_16x16x32_bf16 v[74:77], v[160:163], v[208:211], v[74:77]
	s_setprio 0
	s_setprio 1
	v_mfma_f32_16x16x32_bf16 v[118:121], v[164:167], v[180:183], 0
	v_mfma_f32_16x16x32_bf16 v[114:117], v[172:175], v[180:183], 0
	v_mfma_f32_16x16x32_bf16 v[102:105], v[164:167], v[188:191], 0
	v_mfma_f32_16x16x32_bf16 v[98:101], v[172:175], v[188:191], 0
	v_mfma_f32_16x16x32_bf16 v[86:89], v[164:167], v[196:199], 0
	v_mfma_f32_16x16x32_bf16 v[82:85], v[172:175], v[196:199], 0
	v_mfma_f32_16x16x32_bf16 v[70:73], v[164:167], v[204:207], 0
	v_mfma_f32_16x16x32_bf16 v[66:69], v[172:175], v[204:207], 0
	v_mfma_f32_16x16x32_bf16 v[118:121], v[168:171], v[184:187], v[118:121]
	v_mfma_f32_16x16x32_bf16 v[114:117], v[176:179], v[184:187], v[114:117]
	v_mfma_f32_16x16x32_bf16 v[102:105], v[168:171], v[192:195], v[102:105]
	v_mfma_f32_16x16x32_bf16 v[98:101], v[176:179], v[192:195], v[98:101]
	v_mfma_f32_16x16x32_bf16 v[86:89], v[168:171], v[200:203], v[86:89]
	v_mfma_f32_16x16x32_bf16 v[82:85], v[176:179], v[200:203], v[82:85]
	s_setprio 2
	s_barrier
	v_mfma_f32_16x16x32_bf16 v[70:73], v[168:171], v[208:211], v[70:73]
	v_mfma_f32_16x16x32_bf16 v[66:69], v[176:179], v[208:211], v[66:69]
	s_setprio 0
	ds_read_b128 v[180:183], v145 offset:16384
	ds_read_b128 v[184:187], v145 offset:17408
	ds_read_b128 v[188:191], v145 offset:18432
	ds_read_b128 v[192:195], v145 offset:19456
	ds_read_b128 v[196:199], v145 offset:20480
	ds_read_b128 v[200:203], v145 offset:21504
	ds_read_b128 v[204:207], v145 offset:22528
	ds_read_b128 v[208:211], v145 offset:23552
	s_mov_b32 s74, m0
	s_mov_b32 m0, s35
	s_nop 0
	global_load_lds_dwordx4 v139, s[20:21]
	s_mov_b32 m0, s74
	s_nop 0
	s_mov_b32 s74, m0
	s_mov_b32 m0, s36
	s_nop 0
	global_load_lds_dwordx4 v141, s[20:21]
	s_mov_b32 m0, s74
	s_add_u32 s74, s20, 0x80000
	s_addc_u32 s75, s21, 0
	s_mov_b32 s76, m0
	s_mov_b32 m0, s37
	s_nop 0
	global_load_lds_dwordx4 v139, s[74:75]
	s_mov_b32 m0, s76
	s_nop 0
	s_mov_b32 s76, m0
	s_mov_b32 m0, s40
	s_nop 0
	global_load_lds_dwordx4 v141, s[74:75]
	s_mov_b32 m0, s76
	s_waitcnt vmcnt(4)
	s_waitcnt lgkmcnt(0)
	s_barrier
	s_setprio 1
	s_waitcnt lgkmcnt(7)
	v_mfma_f32_16x16x32_bf16 v[62:65], v[148:151], v[180:183], 0
	v_mfma_f32_16x16x32_bf16 v[58:61], v[156:159], v[180:183], 0
	s_waitcnt lgkmcnt(5)
	v_mfma_f32_16x16x32_bf16 v[46:49], v[148:151], v[188:191], 0
	v_mfma_f32_16x16x32_bf16 v[42:45], v[156:159], v[188:191], 0
	s_waitcnt lgkmcnt(3)
	v_mfma_f32_16x16x32_bf16 v[30:33], v[148:151], v[196:199], 0
	v_mfma_f32_16x16x32_bf16 v[26:29], v[156:159], v[196:199], 0
	s_waitcnt lgkmcnt(1)
	v_mfma_f32_16x16x32_bf16 v[14:17], v[148:151], v[204:207], 0
	v_mfma_f32_16x16x32_bf16 v[10:13], v[156:159], v[204:207], 0
	v_mfma_f32_16x16x32_bf16 v[62:65], v[152:155], v[184:187], v[62:65]
	v_mfma_f32_16x16x32_bf16 v[58:61], v[160:163], v[184:187], v[58:61]
	v_mfma_f32_16x16x32_bf16 v[46:49], v[152:155], v[192:195], v[46:49]
	v_mfma_f32_16x16x32_bf16 v[42:45], v[160:163], v[192:195], v[42:45]
	v_mfma_f32_16x16x32_bf16 v[30:33], v[152:155], v[200:203], v[30:33]
	v_mfma_f32_16x16x32_bf16 v[26:29], v[160:163], v[200:203], v[26:29]
	s_waitcnt lgkmcnt(0)
	v_mfma_f32_16x16x32_bf16 v[14:17], v[152:155], v[208:211], v[14:17]
	v_mfma_f32_16x16x32_bf16 v[10:13], v[160:163], v[208:211], v[10:13]
	s_setprio 0
	s_setprio 1
	v_mfma_f32_16x16x32_bf16 v[54:57], v[164:167], v[180:183], 0
	v_mfma_f32_16x16x32_bf16 v[50:53], v[172:175], v[180:183], 0
	v_mfma_f32_16x16x32_bf16 v[38:41], v[164:167], v[188:191], 0
	v_mfma_f32_16x16x32_bf16 v[34:37], v[172:175], v[188:191], 0
	v_mfma_f32_16x16x32_bf16 v[22:25], v[164:167], v[196:199], 0
	v_mfma_f32_16x16x32_bf16 v[18:21], v[172:175], v[196:199], 0
	v_mfma_f32_16x16x32_bf16 v[6:9], v[164:167], v[204:207], 0
	v_mfma_f32_16x16x32_bf16 v[2:5], v[172:175], v[204:207], 0
	v_mfma_f32_16x16x32_bf16 v[54:57], v[168:171], v[184:187], v[54:57]
	v_mfma_f32_16x16x32_bf16 v[50:53], v[176:179], v[184:187], v[50:53]
	v_mfma_f32_16x16x32_bf16 v[38:41], v[168:171], v[192:195], v[38:41]
	v_mfma_f32_16x16x32_bf16 v[34:37], v[176:179], v[192:195], v[34:37]
	v_mfma_f32_16x16x32_bf16 v[22:25], v[168:171], v[200:203], v[22:25]
	v_mfma_f32_16x16x32_bf16 v[18:21], v[176:179], v[200:203], v[18:21]
	s_setprio 2
	s_barrier
	v_mfma_f32_16x16x32_bf16 v[6:9], v[168:171], v[208:211], v[6:9]
	v_mfma_f32_16x16x32_bf16 v[2:5], v[176:179], v[208:211], v[2:5]
	s_setprio 0
	ds_read_b128 v[148:151], v146
	ds_read_b128 v[152:155], v146 offset:1024
	ds_read_b128 v[156:159], v146 offset:2048
	ds_read_b128 v[160:163], v146 offset:3072
	ds_read_b128 v[164:167], v147
	ds_read_b128 v[168:171], v147 offset:1024
	ds_read_b128 v[172:175], v147 offset:2048
	ds_read_b128 v[176:179], v147 offset:3072
	ds_read_b128 v[180:183], v145 offset:32768
	ds_read_b128 v[184:187], v145 offset:33792
	ds_read_b128 v[188:191], v145 offset:34816
	ds_read_b128 v[192:195], v145 offset:35840
	ds_read_b128 v[196:199], v145 offset:36864
	ds_read_b128 v[200:203], v145 offset:37888
	ds_read_b128 v[204:207], v145 offset:38912
	ds_read_b128 v[208:211], v145 offset:39936
	s_mov_b32 s74, m0
	s_mov_b32 m0, s31
	s_nop 0
	global_load_lds_dwordx4 v138, s[22:23]
	s_mov_b32 m0, s74
	s_nop 0
	s_mov_b32 s74, m0
	s_mov_b32 m0, s41
	s_nop 0
	global_load_lds_dwordx4 v140, s[22:23]
	s_mov_b32 m0, s74
	s_add_u32 s22, s22, 0x80000
	s_addc_u32 s23, s23, 0
	s_mov_b32 s74, m0
	s_mov_b32 m0, s42
	s_nop 0
	global_load_lds_dwordx4 v138, s[22:23]
	s_mov_b32 m0, s74
	s_nop 0
	s_mov_b32 s74, m0
	s_mov_b32 m0, s43
	s_nop 0
	global_load_lds_dwordx4 v140, s[22:23]
	s_mov_b32 m0, s74
	s_waitcnt vmcnt(8)
	s_waitcnt lgkmcnt(0)
	s_barrier
	s_setprio 1
	s_waitcnt lgkmcnt(7)
	v_mfma_f32_16x16x32_bf16 v[126:129], v[148:151], v[180:183], v[126:129]
	v_mfma_f32_16x16x32_bf16 v[122:125], v[156:159], v[180:183], v[122:125]
	s_waitcnt lgkmcnt(5)
	v_mfma_f32_16x16x32_bf16 v[110:113], v[148:151], v[188:191], v[110:113]
	v_mfma_f32_16x16x32_bf16 v[106:109], v[156:159], v[188:191], v[106:109]
	s_waitcnt lgkmcnt(3)
	v_mfma_f32_16x16x32_bf16 v[94:97], v[148:151], v[196:199], v[94:97]
	v_mfma_f32_16x16x32_bf16 v[90:93], v[156:159], v[196:199], v[90:93]
	s_waitcnt lgkmcnt(1)
	v_mfma_f32_16x16x32_bf16 v[78:81], v[148:151], v[204:207], v[78:81]
	v_mfma_f32_16x16x32_bf16 v[74:77], v[156:159], v[204:207], v[74:77]
	v_mfma_f32_16x16x32_bf16 v[126:129], v[152:155], v[184:187], v[126:129]
	v_mfma_f32_16x16x32_bf16 v[122:125], v[160:163], v[184:187], v[122:125]
	v_mfma_f32_16x16x32_bf16 v[110:113], v[152:155], v[192:195], v[110:113]
	v_mfma_f32_16x16x32_bf16 v[106:109], v[160:163], v[192:195], v[106:109]
	v_mfma_f32_16x16x32_bf16 v[94:97], v[152:155], v[200:203], v[94:97]
	v_mfma_f32_16x16x32_bf16 v[90:93], v[160:163], v[200:203], v[90:93]
	s_waitcnt lgkmcnt(0)
	v_mfma_f32_16x16x32_bf16 v[78:81], v[152:155], v[208:211], v[78:81]
	v_mfma_f32_16x16x32_bf16 v[74:77], v[160:163], v[208:211], v[74:77]
	s_setprio 0
	s_setprio 1
	v_mfma_f32_16x16x32_bf16 v[118:121], v[164:167], v[180:183], v[118:121]
	v_mfma_f32_16x16x32_bf16 v[114:117], v[172:175], v[180:183], v[114:117]
	v_mfma_f32_16x16x32_bf16 v[102:105], v[164:167], v[188:191], v[102:105]
	v_mfma_f32_16x16x32_bf16 v[98:101], v[172:175], v[188:191], v[98:101]
	v_mfma_f32_16x16x32_bf16 v[86:89], v[164:167], v[196:199], v[86:89]
	v_mfma_f32_16x16x32_bf16 v[82:85], v[172:175], v[196:199], v[82:85]
	v_mfma_f32_16x16x32_bf16 v[70:73], v[164:167], v[204:207], v[70:73]
	v_mfma_f32_16x16x32_bf16 v[66:69], v[172:175], v[204:207], v[66:69]
	v_mfma_f32_16x16x32_bf16 v[118:121], v[168:171], v[184:187], v[118:121]
	v_mfma_f32_16x16x32_bf16 v[114:117], v[176:179], v[184:187], v[114:117]
	v_mfma_f32_16x16x32_bf16 v[102:105], v[168:171], v[192:195], v[102:105]
	v_mfma_f32_16x16x32_bf16 v[98:101], v[176:179], v[192:195], v[98:101]
	v_mfma_f32_16x16x32_bf16 v[86:89], v[168:171], v[200:203], v[86:89]
	v_mfma_f32_16x16x32_bf16 v[82:85], v[176:179], v[200:203], v[82:85]
	s_setprio 2
	s_barrier
	v_mfma_f32_16x16x32_bf16 v[70:73], v[168:171], v[208:211], v[70:73]
	v_mfma_f32_16x16x32_bf16 v[66:69], v[176:179], v[208:211], v[66:69]
	s_setprio 0
	ds_read_b128 v[180:183], v145 offset:49152
	ds_read_b128 v[184:187], v145 offset:50176
	ds_read_b128 v[188:191], v145 offset:51200
	ds_read_b128 v[192:195], v145 offset:52224
	ds_read_b128 v[196:199], v145 offset:53248
	ds_read_b128 v[200:203], v145 offset:54272
	ds_read_b128 v[204:207], v145 offset:55296
	ds_read_b128 v[208:211], v145 offset:56320
	s_add_u32 s22, s20, 0x80
	s_addc_u32 s23, s21, 0
	s_mov_b32 s74, m0
	s_mov_b32 m0, s46
	s_nop 0
	global_load_lds_dwordx4 v139, s[22:23]
	s_mov_b32 m0, s74
	s_add_u32 s20, s20, 0x80080
	s_mov_b32 s74, m0
	s_mov_b32 m0, s47
	s_nop 0
	global_load_lds_dwordx4 v141, s[22:23]
	s_mov_b32 m0, s74
	s_addc_u32 s21, s21, 0
	s_mov_b32 s22, m0
	s_mov_b32 m0, s48
	s_nop 0
	global_load_lds_dwordx4 v139, s[20:21]
	s_mov_b32 m0, s22
	s_nop 0
	s_mov_b32 s22, m0
	s_mov_b32 m0, s49
	s_nop 0
	global_load_lds_dwordx4 v141, s[20:21]
	s_mov_b32 m0, s22
	s_waitcnt vmcnt(4)
	s_waitcnt lgkmcnt(0)
	s_barrier
	s_setprio 1
	s_waitcnt lgkmcnt(7)
	v_mfma_f32_16x16x32_bf16 v[62:65], v[148:151], v[180:183], v[62:65]
	v_mfma_f32_16x16x32_bf16 v[58:61], v[156:159], v[180:183], v[58:61]
	s_waitcnt lgkmcnt(5)
	v_mfma_f32_16x16x32_bf16 v[46:49], v[148:151], v[188:191], v[46:49]
	v_mfma_f32_16x16x32_bf16 v[42:45], v[156:159], v[188:191], v[42:45]
	s_waitcnt lgkmcnt(3)
	v_mfma_f32_16x16x32_bf16 v[30:33], v[148:151], v[196:199], v[30:33]
	v_mfma_f32_16x16x32_bf16 v[26:29], v[156:159], v[196:199], v[26:29]
	s_waitcnt lgkmcnt(1)
	v_mfma_f32_16x16x32_bf16 v[14:17], v[148:151], v[204:207], v[14:17]
	v_mfma_f32_16x16x32_bf16 v[10:13], v[156:159], v[204:207], v[10:13]
	v_mfma_f32_16x16x32_bf16 v[62:65], v[152:155], v[184:187], v[62:65]
	v_mfma_f32_16x16x32_bf16 v[58:61], v[160:163], v[184:187], v[58:61]
	v_mfma_f32_16x16x32_bf16 v[46:49], v[152:155], v[192:195], v[46:49]
	v_mfma_f32_16x16x32_bf16 v[42:45], v[160:163], v[192:195], v[42:45]
	v_mfma_f32_16x16x32_bf16 v[30:33], v[152:155], v[200:203], v[30:33]
	v_mfma_f32_16x16x32_bf16 v[26:29], v[160:163], v[200:203], v[26:29]
	s_waitcnt lgkmcnt(0)
	v_mfma_f32_16x16x32_bf16 v[14:17], v[152:155], v[208:211], v[14:17]
	v_mfma_f32_16x16x32_bf16 v[10:13], v[160:163], v[208:211], v[10:13]
	s_setprio 0
	s_setprio 1
	v_mfma_f32_16x16x32_bf16 v[54:57], v[164:167], v[180:183], v[54:57]
	v_mfma_f32_16x16x32_bf16 v[50:53], v[172:175], v[180:183], v[50:53]
	v_mfma_f32_16x16x32_bf16 v[38:41], v[164:167], v[188:191], v[38:41]
	v_mfma_f32_16x16x32_bf16 v[34:37], v[172:175], v[188:191], v[34:37]
	v_mfma_f32_16x16x32_bf16 v[22:25], v[164:167], v[196:199], v[22:25]
	v_mfma_f32_16x16x32_bf16 v[18:21], v[172:175], v[196:199], v[18:21]
	v_mfma_f32_16x16x32_bf16 v[6:9], v[164:167], v[204:207], v[6:9]
	v_mfma_f32_16x16x32_bf16 v[2:5], v[172:175], v[204:207], v[2:5]
	v_mfma_f32_16x16x32_bf16 v[54:57], v[168:171], v[184:187], v[54:57]
	v_mfma_f32_16x16x32_bf16 v[50:53], v[176:179], v[184:187], v[50:53]
	v_mfma_f32_16x16x32_bf16 v[38:41], v[168:171], v[192:195], v[38:41]
	v_mfma_f32_16x16x32_bf16 v[34:37], v[176:179], v[192:195], v[34:37]
	v_mfma_f32_16x16x32_bf16 v[22:25], v[168:171], v[200:203], v[22:25]
	v_mfma_f32_16x16x32_bf16 v[18:21], v[176:179], v[200:203], v[18:21]
	s_setprio 2
	s_barrier
	v_mfma_f32_16x16x32_bf16 v[6:9], v[168:171], v[208:211], v[6:9]
	v_mfma_f32_16x16x32_bf16 v[2:5], v[176:179], v[208:211], v[2:5]
	s_setprio 0
	s_add_i32 s73, s73, 2
	s_add_u32 s66, s66, 0x100
	s_addc_u32 s67, s67, 0
	s_add_u32 s18, s18, 0x100
	s_addc_u32 s19, s19, 0
	s_add_u32 s70, s70, 0x100
	s_addc_u32 s71, s71, 0
	s_cmp_gt_u32 s73, 29
	.p2align 6

.LBB0_1951:
	s_ashr_i32 s13, s12, 31
	s_lshl_b64 s[14:15], s[12:13], 15
	s_add_u32 s14, s28, s14
	s_addc_u32 s15, s29, s15
	s_and_b64 s[16:17], s[2:3], exec
	s_cselect_b32 s13, s15, s23
	s_cselect_b32 s65, s14, s22
	s_ashr_i32 s11, s10, 31
	s_lshl_b64 s[16:17], s[10:11], 15
	s_add_u32 s16, s30, s16
	s_addc_u32 s17, s31, s17
	s_and_b64 s[24:25], s[2:3], exec
	s_cselect_b32 s11, s17, s21
	s_cselect_b32 s66, s16, s20
	s_add_u32 s67, s20, 0x80000
	s_addc_u32 s70, s21, 0
	s_add_u32 s20, s22, 0x204000
	s_addc_u32 s21, s23, 0
	s_add_u32 s71, s22, 0x400000
	s_addc_u32 s73, s23, 0
	s_mov_b32 s74, -2
	s_waitcnt vmcnt(25)
	s_waitcnt vmcnt(24)
	s_waitcnt vmcnt(4)
	s_waitcnt vmcnt(2)
	s_waitcnt vmcnt(1)
	s_waitcnt vmcnt(0)
	ds_read_b128 v[130:133], v181
	ds_read_b128 v[134:137], v181 offset:1024
	ds_read_b128 v[138:141], v181 offset:2048
	ds_read_b128 v[142:145], v181 offset:3072
	ds_read_b128 v[150:153], v182
	ds_read_b128 v[154:157], v182 offset:1024
	ds_read_b128 v[158:161], v182 offset:2048
	ds_read_b128 v[162:165], v182 offset:3072
	s_cmpk_eq_i32 s74, 0x52
	s_cselect_b32 s23, s11, s70
	s_cselect_b32 s22, s66, s67
	s_cselect_b32 s25, s13, s73
	s_cselect_b32 s24, s65, s71
	ds_read_b128 v[166:169], v183
	ds_read_b128 v[170:173], v183 offset:1024
	ds_read_b128 v[186:189], v183 offset:2048
	ds_read_b128 v[190:193], v183 offset:3072
	ds_read_b128 v[194:197], v183 offset:4096
	ds_read_b128 v[198:201], v183 offset:5120
	ds_read_b128 v[202:205], v183 offset:6144
	ds_read_b128 v[206:209], v183 offset:7168
	s_add_u32 s76, s20, 0xffffc000
	s_addc_u32 s77, s21, -1
	s_mov_b32 s75, m0
	s_mov_b32 m0, s58
	s_nop 0
	global_load_lds_dwordx4 v1, s[76:77]
	s_mov_b32 m0, s75
	s_nop 0
	s_mov_b32 s75, m0
	s_mov_b32 m0, s62
	s_nop 0
	global_load_lds_dwordx4 v177, s[76:77]
	s_mov_b32 m0, s75
	s_nop 0
	s_mov_b32 s75, m0
	s_mov_b32 m0, s59
	s_nop 0
	global_load_lds_dwordx4 v1, s[20:21]
	s_mov_b32 m0, s75
	s_nop 0
	s_mov_b32 s75, m0
	s_mov_b32 m0, s63
	s_nop 0
	global_load_lds_dwordx4 v177, s[20:21]
	s_mov_b32 m0, s75
	s_waitcnt vmcnt(8)
	s_waitcnt lgkmcnt(0)
	s_barrier
	s_setprio 1
	s_waitcnt lgkmcnt(7)
	v_mfma_f32_16x16x32_bf16 v[126:129], v[130:133], v[166:169], 0
	v_mfma_f32_16x16x32_bf16 v[122:125], v[138:141], v[166:169], 0
	s_waitcnt lgkmcnt(5)
	v_mfma_f32_16x16x32_bf16 v[118:121], v[130:133], v[186:189], 0
	v_mfma_f32_16x16x32_bf16 v[110:113], v[138:141], v[186:189], 0
	s_waitcnt lgkmcnt(3)
	v_mfma_f32_16x16x32_bf16 v[94:97], v[130:133], v[194:197], 0
	v_mfma_f32_16x16x32_bf16 v[90:93], v[138:141], v[194:197], 0
	s_waitcnt lgkmcnt(1)
	v_mfma_f32_16x16x32_bf16 v[86:89], v[130:133], v[202:205], 0
	v_mfma_f32_16x16x32_bf16 v[78:81], v[138:141], v[202:205], 0
	v_mfma_f32_16x16x32_bf16 v[126:129], v[134:137], v[170:173], v[126:129]
	v_mfma_f32_16x16x32_bf16 v[122:125], v[142:145], v[170:173], v[122:125]
	v_mfma_f32_16x16x32_bf16 v[118:121], v[134:137], v[190:193], v[118:121]
	v_mfma_f32_16x16x32_bf16 v[110:113], v[142:145], v[190:193], v[110:113]
	v_mfma_f32_16x16x32_bf16 v[94:97], v[134:137], v[198:201], v[94:97]
	v_mfma_f32_16x16x32_bf16 v[90:93], v[142:145], v[198:201], v[90:93]
	s_waitcnt lgkmcnt(0)
	v_mfma_f32_16x16x32_bf16 v[86:89], v[134:137], v[206:209], v[86:89]
	v_mfma_f32_16x16x32_bf16 v[78:81], v[142:145], v[206:209], v[78:81]
	s_setprio 0
	s_setprio 1
	v_mfma_f32_16x16x32_bf16 v[114:117], v[150:153], v[166:169], 0
	v_mfma_f32_16x16x32_bf16 v[106:109], v[158:161], v[166:169], 0
	v_mfma_f32_16x16x32_bf16 v[102:105], v[150:153], v[186:189], 0
	v_mfma_f32_16x16x32_bf16 v[98:101], v[158:161], v[186:189], 0
	v_mfma_f32_16x16x32_bf16 v[82:85], v[150:153], v[194:197], 0
	v_mfma_f32_16x16x32_bf16 v[74:77], v[158:161], v[194:197], 0
	v_mfma_f32_16x16x32_bf16 v[70:73], v[150:153], v[202:205], 0
	v_mfma_f32_16x16x32_bf16 v[66:69], v[158:161], v[202:205], 0
	v_mfma_f32_16x16x32_bf16 v[114:117], v[154:157], v[170:173], v[114:117]
	v_mfma_f32_16x16x32_bf16 v[106:109], v[162:165], v[170:173], v[106:109]
	v_mfma_f32_16x16x32_bf16 v[102:105], v[154:157], v[190:193], v[102:105]
	v_mfma_f32_16x16x32_bf16 v[98:101], v[162:165], v[190:193], v[98:101]
	v_mfma_f32_16x16x32_bf16 v[82:85], v[154:157], v[198:201], v[82:85]
	v_mfma_f32_16x16x32_bf16 v[74:77], v[162:165], v[198:201], v[74:77]
	s_setprio 2
	s_barrier
	v_mfma_f32_16x16x32_bf16 v[70:73], v[154:157], v[206:209], v[70:73]
	v_mfma_f32_16x16x32_bf16 v[66:69], v[162:165], v[206:209], v[66:69]
	s_setprio 0
	ds_read_b128 v[166:169], v183 offset:16384
	ds_read_b128 v[170:173], v183 offset:17408
	ds_read_b128 v[186:189], v183 offset:18432
	ds_read_b128 v[190:193], v183 offset:19456
	ds_read_b128 v[194:197], v183 offset:20480
	ds_read_b128 v[198:201], v183 offset:21504
	ds_read_b128 v[202:205], v183 offset:22528
	ds_read_b128 v[206:209], v183 offset:23552
	s_mov_b32 s75, m0
	s_mov_b32 m0, s35
	s_nop 0
	global_load_lds_dwordx4 v176, s[22:23]
	s_mov_b32 m0, s75
	s_add_u32 s76, s22, 0x4000
	s_mov_b32 s75, m0
	s_mov_b32 m0, s36
	s_nop 0
	global_load_lds_dwordx4 v178, s[22:23]
	s_mov_b32 m0, s75
	s_addc_u32 s77, s23, 0
	s_mov_b32 s75, m0
	s_mov_b32 m0, s37
	s_nop 0
	global_load_lds_dwordx4 v176, s[76:77]
	s_mov_b32 m0, s75
	s_nop 0
	s_mov_b32 s75, m0
	s_mov_b32 m0, s40
	s_nop 0
	global_load_lds_dwordx4 v178, s[76:77]
	s_mov_b32 m0, s75
	s_waitcnt vmcnt(4)
	s_waitcnt lgkmcnt(0)
	s_barrier
	s_setprio 1
	s_waitcnt lgkmcnt(7)
	v_mfma_f32_16x16x32_bf16 v[62:65], v[130:133], v[166:169], 0
	v_mfma_f32_16x16x32_bf16 v[58:61], v[138:141], v[166:169], 0
	s_waitcnt lgkmcnt(5)
	v_mfma_f32_16x16x32_bf16 v[46:49], v[130:133], v[186:189], 0
	v_mfma_f32_16x16x32_bf16 v[42:45], v[138:141], v[186:189], 0
	s_waitcnt lgkmcnt(3)
	v_mfma_f32_16x16x32_bf16 v[30:33], v[130:133], v[194:197], 0
	v_mfma_f32_16x16x32_bf16 v[26:29], v[138:141], v[194:197], 0
	s_waitcnt lgkmcnt(1)
	v_mfma_f32_16x16x32_bf16 v[14:17], v[130:133], v[202:205], 0
	v_mfma_f32_16x16x32_bf16 v[10:13], v[138:141], v[202:205], 0
	v_mfma_f32_16x16x32_bf16 v[62:65], v[134:137], v[170:173], v[62:65]
	v_mfma_f32_16x16x32_bf16 v[58:61], v[142:145], v[170:173], v[58:61]
	v_mfma_f32_16x16x32_bf16 v[46:49], v[134:137], v[190:193], v[46:49]
	v_mfma_f32_16x16x32_bf16 v[42:45], v[142:145], v[190:193], v[42:45]
	v_mfma_f32_16x16x32_bf16 v[30:33], v[134:137], v[198:201], v[30:33]
	v_mfma_f32_16x16x32_bf16 v[26:29], v[142:145], v[198:201], v[26:29]
	s_waitcnt lgkmcnt(0)
	v_mfma_f32_16x16x32_bf16 v[14:17], v[134:137], v[206:209], v[14:17]
	v_mfma_f32_16x16x32_bf16 v[10:13], v[142:145], v[206:209], v[10:13]
	s_setprio 0
	s_setprio 1
	v_mfma_f32_16x16x32_bf16 v[54:57], v[150:153], v[166:169], 0
	v_mfma_f32_16x16x32_bf16 v[50:53], v[158:161], v[166:169], 0
	v_mfma_f32_16x16x32_bf16 v[38:41], v[150:153], v[186:189], 0
	v_mfma_f32_16x16x32_bf16 v[34:37], v[158:161], v[186:189], 0
	v_mfma_f32_16x16x32_bf16 v[22:25], v[150:153], v[194:197], 0
	v_mfma_f32_16x16x32_bf16 v[18:21], v[158:161], v[194:197], 0
	v_mfma_f32_16x16x32_bf16 v[6:9], v[150:153], v[202:205], 0
	v_mfma_f32_16x16x32_bf16 v[2:5], v[158:161], v[202:205], 0
	v_mfma_f32_16x16x32_bf16 v[54:57], v[154:157], v[170:173], v[54:57]
	v_mfma_f32_16x16x32_bf16 v[50:53], v[162:165], v[170:173], v[50:53]
	v_mfma_f32_16x16x32_bf16 v[38:41], v[154:157], v[190:193], v[38:41]
	v_mfma_f32_16x16x32_bf16 v[34:37], v[162:165], v[190:193], v[34:37]
	v_mfma_f32_16x16x32_bf16 v[22:25], v[154:157], v[198:201], v[22:25]
	v_mfma_f32_16x16x32_bf16 v[18:21], v[162:165], v[198:201], v[18:21]
	s_setprio 2
	s_barrier
	v_mfma_f32_16x16x32_bf16 v[6:9], v[154:157], v[206:209], v[6:9]
	v_mfma_f32_16x16x32_bf16 v[2:5], v[162:165], v[206:209], v[2:5]
	s_setprio 0
	ds_read_b128 v[130:133], v184
	ds_read_b128 v[134:137], v184 offset:1024
	ds_read_b128 v[138:141], v184 offset:2048
	ds_read_b128 v[142:145], v184 offset:3072
	ds_read_b128 v[150:153], v185
	ds_read_b128 v[154:157], v185 offset:1024
	ds_read_b128 v[158:161], v185 offset:2048
	ds_read_b128 v[162:165], v185 offset:3072
	ds_read_b128 v[166:169], v183 offset:32768
	ds_read_b128 v[170:173], v183 offset:33792
	ds_read_b128 v[186:189], v183 offset:34816
	ds_read_b128 v[190:193], v183 offset:35840
	ds_read_b128 v[194:197], v183 offset:36864
	ds_read_b128 v[198:201], v183 offset:37888
	ds_read_b128 v[202:205], v183 offset:38912
	ds_read_b128 v[206:209], v183 offset:39936
	s_mov_b32 s75, m0
	s_mov_b32 m0, s34
	s_nop 0
	global_load_lds_dwordx4 v1, s[24:25]
	s_mov_b32 m0, s75
	s_nop 0
	s_mov_b32 s75, m0
	s_mov_b32 m0, s41
	s_nop 0
	global_load_lds_dwordx4 v177, s[24:25]
	s_mov_b32 m0, s75
	s_add_u32 s24, s24, 0x4000
	s_addc_u32 s25, s25, 0
	s_mov_b32 s75, m0
	s_mov_b32 m0, s42
	s_nop 0
	global_load_lds_dwordx4 v1, s[24:25]
	s_mov_b32 m0, s75
	s_nop 0
	s_mov_b32 s75, m0
	s_mov_b32 m0, s43
	s_nop 0
	global_load_lds_dwordx4 v177, s[24:25]
	s_mov_b32 m0, s75
	s_waitcnt vmcnt(8)
	s_waitcnt lgkmcnt(0)
	s_barrier
	s_setprio 1
	s_waitcnt lgkmcnt(7)
	v_mfma_f32_16x16x32_bf16 v[126:129], v[130:133], v[166:169], v[126:129]
	v_mfma_f32_16x16x32_bf16 v[122:125], v[138:141], v[166:169], v[122:125]
	s_waitcnt lgkmcnt(5)
	v_mfma_f32_16x16x32_bf16 v[118:121], v[130:133], v[186:189], v[118:121]
	v_mfma_f32_16x16x32_bf16 v[110:113], v[138:141], v[186:189], v[110:113]
	s_waitcnt lgkmcnt(3)
	v_mfma_f32_16x16x32_bf16 v[94:97], v[130:133], v[194:197], v[94:97]
	v_mfma_f32_16x16x32_bf16 v[90:93], v[138:141], v[194:197], v[90:93]
	s_waitcnt lgkmcnt(1)
	v_mfma_f32_16x16x32_bf16 v[86:89], v[130:133], v[202:205], v[86:89]
	v_mfma_f32_16x16x32_bf16 v[78:81], v[138:141], v[202:205], v[78:81]
	v_mfma_f32_16x16x32_bf16 v[126:129], v[134:137], v[170:173], v[126:129]
	v_mfma_f32_16x16x32_bf16 v[122:125], v[142:145], v[170:173], v[122:125]
	v_mfma_f32_16x16x32_bf16 v[118:121], v[134:137], v[190:193], v[118:121]
	v_mfma_f32_16x16x32_bf16 v[110:113], v[142:145], v[190:193], v[110:113]
	v_mfma_f32_16x16x32_bf16 v[94:97], v[134:137], v[198:201], v[94:97]
	v_mfma_f32_16x16x32_bf16 v[90:93], v[142:145], v[198:201], v[90:93]
	s_waitcnt lgkmcnt(0)
	v_mfma_f32_16x16x32_bf16 v[86:89], v[134:137], v[206:209], v[86:89]
	v_mfma_f32_16x16x32_bf16 v[78:81], v[142:145], v[206:209], v[78:81]
	s_setprio 0
	s_setprio 1
	v_mfma_f32_16x16x32_bf16 v[114:117], v[150:153], v[166:169], v[114:117]
	v_mfma_f32_16x16x32_bf16 v[106:109], v[158:161], v[166:169], v[106:109]
	v_mfma_f32_16x16x32_bf16 v[102:105], v[150:153], v[186:189], v[102:105]
	v_mfma_f32_16x16x32_bf16 v[98:101], v[158:161], v[186:189], v[98:101]
	v_mfma_f32_16x16x32_bf16 v[82:85], v[150:153], v[194:197], v[82:85]
	v_mfma_f32_16x16x32_bf16 v[74:77], v[158:161], v[194:197], v[74:77]
	v_mfma_f32_16x16x32_bf16 v[70:73], v[150:153], v[202:205], v[70:73]
	v_mfma_f32_16x16x32_bf16 v[66:69], v[158:161], v[202:205], v[66:69]
	v_mfma_f32_16x16x32_bf16 v[114:117], v[154:157], v[170:173], v[114:117]
	v_mfma_f32_16x16x32_bf16 v[106:109], v[162:165], v[170:173], v[106:109]
	v_mfma_f32_16x16x32_bf16 v[102:105], v[154:157], v[190:193], v[102:105]
	v_mfma_f32_16x16x32_bf16 v[98:101], v[162:165], v[190:193], v[98:101]
	v_mfma_f32_16x16x32_bf16 v[82:85], v[154:157], v[198:201], v[82:85]
	v_mfma_f32_16x16x32_bf16 v[74:77], v[162:165], v[198:201], v[74:77]
	s_setprio 2
	s_barrier
	v_mfma_f32_16x16x32_bf16 v[70:73], v[154:157], v[206:209], v[70:73]
	v_mfma_f32_16x16x32_bf16 v[66:69], v[162:165], v[206:209], v[66:69]
	s_setprio 0
	ds_read_b128 v[166:169], v183 offset:49152
	ds_read_b128 v[170:173], v183 offset:50176
	ds_read_b128 v[186:189], v183 offset:51200
	ds_read_b128 v[190:193], v183 offset:52224
	ds_read_b128 v[194:197], v183 offset:53248
	ds_read_b128 v[198:201], v183 offset:54272
	ds_read_b128 v[202:205], v183 offset:55296
	ds_read_b128 v[206:209], v183 offset:56320
	s_add_u32 s24, s22, 0x40000
	s_addc_u32 s25, s23, 0
	s_mov_b32 s75, m0
	s_mov_b32 m0, s46
	s_nop 0
	global_load_lds_dwordx4 v176, s[24:25]
	s_mov_b32 m0, s75
	s_add_u32 s22, s22, 0x44000
	s_mov_b32 s75, m0
	s_mov_b32 m0, s47
	s_nop 0
	global_load_lds_dwordx4 v178, s[24:25]
	s_mov_b32 m0, s75
	s_addc_u32 s23, s23, 0
	s_mov_b32 s24, m0
	s_mov_b32 m0, s48
	s_nop 0
	global_load_lds_dwordx4 v176, s[22:23]
	s_mov_b32 m0, s24
	s_nop 0
	s_mov_b32 s24, m0
	s_mov_b32 m0, s49
	s_nop 0
	global_load_lds_dwordx4 v178, s[22:23]
	s_mov_b32 m0, s24
	s_waitcnt vmcnt(4)
	s_waitcnt lgkmcnt(0)
	s_barrier
	s_setprio 1
	s_waitcnt lgkmcnt(7)
	v_mfma_f32_16x16x32_bf16 v[62:65], v[130:133], v[166:169], v[62:65]
	v_mfma_f32_16x16x32_bf16 v[58:61], v[138:141], v[166:169], v[58:61]
	s_waitcnt lgkmcnt(5)
	v_mfma_f32_16x16x32_bf16 v[46:49], v[130:133], v[186:189], v[46:49]
	v_mfma_f32_16x16x32_bf16 v[42:45], v[138:141], v[186:189], v[42:45]
	s_waitcnt lgkmcnt(3)
	v_mfma_f32_16x16x32_bf16 v[30:33], v[130:133], v[194:197], v[30:33]
	v_mfma_f32_16x16x32_bf16 v[26:29], v[138:141], v[194:197], v[26:29]
	s_waitcnt lgkmcnt(1)
	v_mfma_f32_16x16x32_bf16 v[14:17], v[130:133], v[202:205], v[14:17]
	v_mfma_f32_16x16x32_bf16 v[10:13], v[138:141], v[202:205], v[10:13]
	v_mfma_f32_16x16x32_bf16 v[62:65], v[134:137], v[170:173], v[62:65]
	v_mfma_f32_16x16x32_bf16 v[58:61], v[142:145], v[170:173], v[58:61]
	v_mfma_f32_16x16x32_bf16 v[46:49], v[134:137], v[190:193], v[46:49]
	v_mfma_f32_16x16x32_bf16 v[42:45], v[142:145], v[190:193], v[42:45]
	v_mfma_f32_16x16x32_bf16 v[30:33], v[134:137], v[198:201], v[30:33]
	v_mfma_f32_16x16x32_bf16 v[26:29], v[142:145], v[198:201], v[26:29]
	s_waitcnt lgkmcnt(0)
	v_mfma_f32_16x16x32_bf16 v[14:17], v[134:137], v[206:209], v[14:17]
	v_mfma_f32_16x16x32_bf16 v[10:13], v[142:145], v[206:209], v[10:13]
	s_setprio 0
	s_setprio 1
	v_mfma_f32_16x16x32_bf16 v[54:57], v[150:153], v[166:169], v[54:57]
	v_mfma_f32_16x16x32_bf16 v[50:53], v[158:161], v[166:169], v[50:53]
	v_mfma_f32_16x16x32_bf16 v[38:41], v[150:153], v[186:189], v[38:41]
	v_mfma_f32_16x16x32_bf16 v[34:37], v[158:161], v[186:189], v[34:37]
	v_mfma_f32_16x16x32_bf16 v[22:25], v[150:153], v[194:197], v[22:25]
	v_mfma_f32_16x16x32_bf16 v[18:21], v[158:161], v[194:197], v[18:21]
	v_mfma_f32_16x16x32_bf16 v[6:9], v[150:153], v[202:205], v[6:9]
	v_mfma_f32_16x16x32_bf16 v[2:5], v[158:161], v[202:205], v[2:5]
	v_mfma_f32_16x16x32_bf16 v[54:57], v[154:157], v[170:173], v[54:57]
	v_mfma_f32_16x16x32_bf16 v[50:53], v[162:165], v[170:173], v[50:53]
	v_mfma_f32_16x16x32_bf16 v[38:41], v[154:157], v[190:193], v[38:41]
	v_mfma_f32_16x16x32_bf16 v[34:37], v[162:165], v[190:193], v[34:37]
	v_mfma_f32_16x16x32_bf16 v[22:25], v[154:157], v[198:201], v[22:25]
	v_mfma_f32_16x16x32_bf16 v[18:21], v[162:165], v[198:201], v[18:21]
	s_setprio 2
	s_barrier
	v_mfma_f32_16x16x32_bf16 v[6:9], v[154:157], v[206:209], v[6:9]
	v_mfma_f32_16x16x32_bf16 v[2:5], v[162:165], v[206:209], v[2:5]
	s_setprio 0
	s_add_i32 s74, s74, 2
	s_add_u32 s67, s67, 0x80000
	s_addc_u32 s70, s70, 0
	s_add_u32 s20, s20, 0x400000
	s_addc_u32 s21, s21, 0
	s_add_u32 s71, s71, 0x400000
	s_addc_u32 s73, s73, 0
	s_cmpk_gt_u32 s74, 0x53
	.p2align 6

.LBB0_2145:
	s_ashr_i32 s25, s24, 31
	s_lshl_b64 s[26:27], s[24:25], 20
	s_add_u32 s26, s33, s26
	s_addc_u32 s27, s42, s27
	s_and_b64 s[28:29], s[2:3], exec
	s_cselect_b32 s5, s27, s37
	s_cselect_b32 s25, s26, s36
	s_ashr_i32 s23, s22, 31
	s_lshl_b64 s[28:29], s[22:23], 20
	s_add_u32 s28, s43, s28
	s_addc_u32 s29, s46, s29
	s_and_b64 s[40:41], s[2:3], exec
	s_cselect_b32 s23, s29, s35
	s_cselect_b32 s31, s28, s34
	s_add_u32 s77, s34, 0x100
	s_addc_u32 s78, s35, 0
	s_add_u32 s34, s36, 0x80080
	s_addc_u32 s35, s37, 0
	s_add_u32 s79, s36, 0x100
	s_addc_u32 s80, s37, 0
	s_mov_b32 s81, -2
	s_waitcnt vmcnt(25)
	s_waitcnt vmcnt(24)
	s_waitcnt vmcnt(4)
	s_waitcnt vmcnt(2)
	s_waitcnt vmcnt(1)
	s_waitcnt vmcnt(0)
	ds_read_b128 v[42:45], v181
	ds_read_b128 v[46:49], v181 offset:1024
	ds_read_b128 v[58:61], v181 offset:2048
	ds_read_b128 v[62:65], v181 offset:3072
	ds_read_b128 v[146:149], v182
	ds_read_b128 v[150:153], v182 offset:1024
	ds_read_b128 v[154:157], v182 offset:2048
	ds_read_b128 v[158:161], v182 offset:3072
	s_cmp_eq_u32 s81, 28
	s_cselect_b32 s37, s23, s78
	s_cselect_b32 s36, s31, s77
	s_cselect_b32 s41, s5, s80
	s_cselect_b32 s40, s25, s79
	ds_read_b128 v[170:173], v183
	ds_read_b128 v[188:191], v183 offset:1024
	ds_read_b128 v[192:195], v183 offset:2048
	ds_read_b128 v[196:199], v183 offset:3072
	ds_read_b128 v[200:203], v183 offset:4096
	ds_read_b128 v[204:207], v183 offset:5120
	ds_read_b128 v[208:211], v183 offset:6144
	ds_read_b128 v[212:215], v183 offset:7168
	s_add_u32 s82, s34, 0xfff80000
	s_addc_u32 s83, s35, -1
	s_mov_b32 s86, m0
	s_mov_b32 m0, s70
	s_nop 0
	global_load_lds_dwordx4 v1, s[82:83]
	s_mov_b32 m0, s86
	s_nop 0
	s_mov_b32 s86, m0
	s_mov_b32 m0, s73
	s_nop 0
	global_load_lds_dwordx4 v177, s[82:83]
	s_mov_b32 m0, s86
	s_mov_b32 s82, m0
	s_mov_b32 m0, s71
	s_nop 0
	global_load_lds_dwordx4 v1, s[34:35]
	s_mov_b32 m0, s82
	s_nop 0
	s_mov_b32 s82, m0
	s_mov_b32 m0, s74
	s_nop 0
	global_load_lds_dwordx4 v177, s[34:35]
	s_mov_b32 m0, s82
	s_waitcnt vmcnt(8)
	s_waitcnt lgkmcnt(0)
	s_barrier
	s_setprio 1
	s_waitcnt lgkmcnt(7)
	v_mfma_f32_16x16x32_bf16 v[142:145], v[42:45], v[170:173], 0
	v_mfma_f32_16x16x32_bf16 v[138:141], v[58:61], v[170:173], 0
	s_waitcnt lgkmcnt(5)
	v_mfma_f32_16x16x32_bf16 v[126:129], v[42:45], v[192:195], 0
	v_mfma_f32_16x16x32_bf16 v[122:125], v[58:61], v[192:195], 0
	s_waitcnt lgkmcnt(3)
	v_mfma_f32_16x16x32_bf16 v[110:113], v[42:45], v[200:203], 0
	v_mfma_f32_16x16x32_bf16 v[106:109], v[58:61], v[200:203], 0
	s_waitcnt lgkmcnt(1)
	v_mfma_f32_16x16x32_bf16 v[94:97], v[42:45], v[208:211], 0
	v_mfma_f32_16x16x32_bf16 v[90:93], v[58:61], v[208:211], 0
	v_mfma_f32_16x16x32_bf16 v[142:145], v[46:49], v[188:191], v[142:145]
	v_mfma_f32_16x16x32_bf16 v[138:141], v[62:65], v[188:191], v[138:141]
	v_mfma_f32_16x16x32_bf16 v[126:129], v[46:49], v[196:199], v[126:129]
	v_mfma_f32_16x16x32_bf16 v[122:125], v[62:65], v[196:199], v[122:125]
	v_mfma_f32_16x16x32_bf16 v[110:113], v[46:49], v[204:207], v[110:113]
	v_mfma_f32_16x16x32_bf16 v[106:109], v[62:65], v[204:207], v[106:109]
	s_waitcnt lgkmcnt(0)
	v_mfma_f32_16x16x32_bf16 v[94:97], v[46:49], v[212:215], v[94:97]
	v_mfma_f32_16x16x32_bf16 v[90:93], v[62:65], v[212:215], v[90:93]
	s_setprio 0
	s_setprio 1
	v_mfma_f32_16x16x32_bf16 v[134:137], v[146:149], v[170:173], 0
	v_mfma_f32_16x16x32_bf16 v[130:133], v[154:157], v[170:173], 0
	v_mfma_f32_16x16x32_bf16 v[118:121], v[146:149], v[192:195], 0
	v_mfma_f32_16x16x32_bf16 v[114:117], v[154:157], v[192:195], 0
	v_mfma_f32_16x16x32_bf16 v[102:105], v[146:149], v[200:203], 0
	v_mfma_f32_16x16x32_bf16 v[98:101], v[154:157], v[200:203], 0
	v_mfma_f32_16x16x32_bf16 v[86:89], v[146:149], v[208:211], 0
	v_mfma_f32_16x16x32_bf16 v[82:85], v[154:157], v[208:211], 0
	v_mfma_f32_16x16x32_bf16 v[134:137], v[150:153], v[188:191], v[134:137]
	v_mfma_f32_16x16x32_bf16 v[130:133], v[158:161], v[188:191], v[130:133]
	v_mfma_f32_16x16x32_bf16 v[118:121], v[150:153], v[196:199], v[118:121]
	v_mfma_f32_16x16x32_bf16 v[114:117], v[158:161], v[196:199], v[114:117]
	v_mfma_f32_16x16x32_bf16 v[102:105], v[150:153], v[204:207], v[102:105]
	v_mfma_f32_16x16x32_bf16 v[98:101], v[158:161], v[204:207], v[98:101]
	s_setprio 2
	s_barrier
	v_mfma_f32_16x16x32_bf16 v[86:89], v[150:153], v[212:215], v[86:89]
	v_mfma_f32_16x16x32_bf16 v[82:85], v[158:161], v[212:215], v[82:85]
	s_setprio 0
	ds_read_b128 v[170:173], v183 offset:16384
	ds_read_b128 v[188:191], v183 offset:17408
	ds_read_b128 v[192:195], v183 offset:18432
	ds_read_b128 v[196:199], v183 offset:19456
	ds_read_b128 v[200:203], v183 offset:20480
	ds_read_b128 v[204:207], v183 offset:21504
	ds_read_b128 v[208:211], v183 offset:22528
	ds_read_b128 v[212:215], v183 offset:23552
	s_mov_b32 s82, m0
	s_mov_b32 m0, s49
	s_nop 0
	global_load_lds_dwordx4 v176, s[36:37]
	s_mov_b32 m0, s82
	s_nop 0
	s_mov_b32 s82, m0
	s_mov_b32 m0, s56
	s_nop 0
	global_load_lds_dwordx4 v178, s[36:37]
	s_mov_b32 m0, s82
	s_add_u32 s82, s36, 0x80000
	s_addc_u32 s83, s37, 0
	s_mov_b32 s86, m0
	s_mov_b32 m0, s57
	s_nop 0
	global_load_lds_dwordx4 v176, s[82:83]
	s_mov_b32 m0, s86
	s_nop 0
	s_mov_b32 s86, m0
	s_mov_b32 m0, s58
	s_nop 0
	global_load_lds_dwordx4 v178, s[82:83]
	s_mov_b32 m0, s86
	s_waitcnt vmcnt(4)
	s_waitcnt lgkmcnt(0)
	s_barrier
	s_setprio 1
	s_waitcnt lgkmcnt(7)
	v_mfma_f32_16x16x32_bf16 v[78:81], v[42:45], v[170:173], 0
	v_mfma_f32_16x16x32_bf16 v[74:77], v[58:61], v[170:173], 0
	s_waitcnt lgkmcnt(5)
	v_mfma_f32_16x16x32_bf16 v[54:57], v[42:45], v[192:195], 0
	v_mfma_f32_16x16x32_bf16 v[50:53], v[58:61], v[192:195], 0
	s_waitcnt lgkmcnt(3)
	v_mfma_f32_16x16x32_bf16 v[30:33], v[42:45], v[200:203], 0
	v_mfma_f32_16x16x32_bf16 v[26:29], v[58:61], v[200:203], 0
	s_waitcnt lgkmcnt(1)
	v_mfma_f32_16x16x32_bf16 v[14:17], v[42:45], v[208:211], 0
	v_mfma_f32_16x16x32_bf16 v[10:13], v[58:61], v[208:211], 0
	v_mfma_f32_16x16x32_bf16 v[78:81], v[46:49], v[188:191], v[78:81]
	v_mfma_f32_16x16x32_bf16 v[74:77], v[62:65], v[188:191], v[74:77]
	v_mfma_f32_16x16x32_bf16 v[54:57], v[46:49], v[196:199], v[54:57]
	v_mfma_f32_16x16x32_bf16 v[50:53], v[62:65], v[196:199], v[50:53]
	v_mfma_f32_16x16x32_bf16 v[30:33], v[46:49], v[204:207], v[30:33]
	v_mfma_f32_16x16x32_bf16 v[26:29], v[62:65], v[204:207], v[26:29]
	s_waitcnt lgkmcnt(0)
	v_mfma_f32_16x16x32_bf16 v[14:17], v[46:49], v[212:215], v[14:17]
	v_mfma_f32_16x16x32_bf16 v[10:13], v[62:65], v[212:215], v[10:13]
	s_setprio 0
	s_setprio 1
	v_mfma_f32_16x16x32_bf16 v[38:41], v[146:149], v[192:195], 0
	v_mfma_f32_16x16x32_bf16 v[34:37], v[154:157], v[192:195], 0
	v_mfma_f32_16x16x32_bf16 v[22:25], v[146:149], v[200:203], 0
	v_mfma_f32_16x16x32_bf16 v[18:21], v[154:157], v[200:203], 0
	v_mfma_f32_16x16x32_bf16 v[6:9], v[146:149], v[208:211], 0
	v_mfma_f32_16x16x32_bf16 v[2:5], v[154:157], v[208:211], 0
	v_mfma_f32_16x16x32_bf16 v[42:45], v[146:149], v[170:173], 0
	v_mfma_f32_16x16x32_bf16 v[46:49], v[154:157], v[170:173], 0
	v_mfma_f32_16x16x32_bf16 v[38:41], v[150:153], v[196:199], v[38:41]
	v_mfma_f32_16x16x32_bf16 v[34:37], v[158:161], v[196:199], v[34:37]
	v_mfma_f32_16x16x32_bf16 v[22:25], v[150:153], v[204:207], v[22:25]
	v_mfma_f32_16x16x32_bf16 v[18:21], v[158:161], v[204:207], v[18:21]
	v_mfma_f32_16x16x32_bf16 v[6:9], v[150:153], v[212:215], v[6:9]
	v_mfma_f32_16x16x32_bf16 v[2:5], v[158:161], v[212:215], v[2:5]
	s_setprio 2
	s_barrier
	v_mfma_f32_16x16x32_bf16 v[42:45], v[150:153], v[188:191], v[42:45]
	v_mfma_f32_16x16x32_bf16 v[46:49], v[158:161], v[188:191], v[46:49]
	s_setprio 0
	ds_read_b128 v[58:61], v184
	ds_read_b128 v[62:65], v184 offset:1024
	ds_read_b128 v[66:69], v184 offset:2048
	ds_read_b128 v[70:73], v184 offset:3072
	ds_read_b128 v[146:149], v185
	ds_read_b128 v[150:153], v185 offset:1024
	ds_read_b128 v[154:157], v185 offset:2048
	ds_read_b128 v[158:161], v185 offset:3072
	ds_read_b128 v[170:173], v183 offset:32768
	ds_read_b128 v[188:191], v183 offset:33792
	ds_read_b128 v[192:195], v183 offset:34816
	ds_read_b128 v[196:199], v183 offset:35840
	ds_read_b128 v[200:203], v183 offset:36864
	ds_read_b128 v[204:207], v183 offset:37888
	ds_read_b128 v[208:211], v183 offset:38912
	ds_read_b128 v[212:215], v183 offset:39936
	s_mov_b32 s82, m0
	s_mov_b32 m0, s48
	s_nop 0
	global_load_lds_dwordx4 v1, s[40:41]
	s_mov_b32 m0, s82
	s_nop 0
	s_mov_b32 s82, m0
	s_mov_b32 m0, s59
	s_nop 0
	global_load_lds_dwordx4 v177, s[40:41]
	s_mov_b32 m0, s82
	s_add_u32 s40, s40, 0x80000
	s_addc_u32 s41, s41, 0
	s_mov_b32 s82, m0
	s_mov_b32 m0, s62
	s_nop 0
	global_load_lds_dwordx4 v1, s[40:41]
	s_mov_b32 m0, s82
	s_nop 0
	s_mov_b32 s82, m0
	s_mov_b32 m0, s63
	s_nop 0
	global_load_lds_dwordx4 v177, s[40:41]
	s_mov_b32 m0, s82
	s_waitcnt vmcnt(8)
	s_waitcnt lgkmcnt(0)
	s_barrier
	s_setprio 1
	s_waitcnt lgkmcnt(7)
	v_mfma_f32_16x16x32_bf16 v[142:145], v[58:61], v[170:173], v[142:145]
	v_mfma_f32_16x16x32_bf16 v[138:141], v[66:69], v[170:173], v[138:141]
	s_waitcnt lgkmcnt(5)
	v_mfma_f32_16x16x32_bf16 v[126:129], v[58:61], v[192:195], v[126:129]
	v_mfma_f32_16x16x32_bf16 v[122:125], v[66:69], v[192:195], v[122:125]
	s_waitcnt lgkmcnt(3)
	v_mfma_f32_16x16x32_bf16 v[110:113], v[58:61], v[200:203], v[110:113]
	v_mfma_f32_16x16x32_bf16 v[106:109], v[66:69], v[200:203], v[106:109]
	s_waitcnt lgkmcnt(1)
	v_mfma_f32_16x16x32_bf16 v[94:97], v[58:61], v[208:211], v[94:97]
	v_mfma_f32_16x16x32_bf16 v[90:93], v[66:69], v[208:211], v[90:93]
	v_mfma_f32_16x16x32_bf16 v[142:145], v[62:65], v[188:191], v[142:145]
	v_mfma_f32_16x16x32_bf16 v[138:141], v[70:73], v[188:191], v[138:141]
	v_mfma_f32_16x16x32_bf16 v[126:129], v[62:65], v[196:199], v[126:129]
	v_mfma_f32_16x16x32_bf16 v[122:125], v[70:73], v[196:199], v[122:125]
	v_mfma_f32_16x16x32_bf16 v[110:113], v[62:65], v[204:207], v[110:113]
	v_mfma_f32_16x16x32_bf16 v[106:109], v[70:73], v[204:207], v[106:109]
	s_waitcnt lgkmcnt(0)
	v_mfma_f32_16x16x32_bf16 v[94:97], v[62:65], v[212:215], v[94:97]
	v_mfma_f32_16x16x32_bf16 v[90:93], v[70:73], v[212:215], v[90:93]
	s_setprio 0
	s_setprio 1
	v_mfma_f32_16x16x32_bf16 v[134:137], v[146:149], v[170:173], v[134:137]
	v_mfma_f32_16x16x32_bf16 v[130:133], v[154:157], v[170:173], v[130:133]
	v_mfma_f32_16x16x32_bf16 v[118:121], v[146:149], v[192:195], v[118:121]
	v_mfma_f32_16x16x32_bf16 v[114:117], v[154:157], v[192:195], v[114:117]
	v_mfma_f32_16x16x32_bf16 v[102:105], v[146:149], v[200:203], v[102:105]
	v_mfma_f32_16x16x32_bf16 v[98:101], v[154:157], v[200:203], v[98:101]
	v_mfma_f32_16x16x32_bf16 v[86:89], v[146:149], v[208:211], v[86:89]
	v_mfma_f32_16x16x32_bf16 v[82:85], v[154:157], v[208:211], v[82:85]
	v_mfma_f32_16x16x32_bf16 v[134:137], v[150:153], v[188:191], v[134:137]
	v_mfma_f32_16x16x32_bf16 v[130:133], v[158:161], v[188:191], v[130:133]
	v_mfma_f32_16x16x32_bf16 v[118:121], v[150:153], v[196:199], v[118:121]
	v_mfma_f32_16x16x32_bf16 v[114:117], v[158:161], v[196:199], v[114:117]
	v_mfma_f32_16x16x32_bf16 v[102:105], v[150:153], v[204:207], v[102:105]
	v_mfma_f32_16x16x32_bf16 v[98:101], v[158:161], v[204:207], v[98:101]
	s_setprio 2
	s_barrier
	v_mfma_f32_16x16x32_bf16 v[86:89], v[150:153], v[212:215], v[86:89]
	v_mfma_f32_16x16x32_bf16 v[82:85], v[158:161], v[212:215], v[82:85]
	s_setprio 0
	ds_read_b128 v[170:173], v183 offset:49152
	ds_read_b128 v[188:191], v183 offset:50176
	ds_read_b128 v[192:195], v183 offset:51200
	ds_read_b128 v[196:199], v183 offset:52224
	ds_read_b128 v[200:203], v183 offset:53248
	ds_read_b128 v[204:207], v183 offset:54272
	ds_read_b128 v[208:211], v183 offset:55296
	ds_read_b128 v[212:215], v183 offset:56320
	s_add_u32 s40, s36, 0x80
	s_addc_u32 s41, s37, 0
	s_mov_b32 s82, m0
	s_mov_b32 m0, s64
	s_nop 0
	global_load_lds_dwordx4 v176, s[40:41]
	s_mov_b32 m0, s82
	s_add_u32 s36, s36, 0x80080
	s_mov_b32 s82, m0
	s_mov_b32 m0, s65
	s_nop 0
	global_load_lds_dwordx4 v178, s[40:41]
	s_mov_b32 m0, s82
	s_addc_u32 s37, s37, 0
	s_mov_b32 s40, m0
	s_mov_b32 m0, s66
	s_nop 0
	global_load_lds_dwordx4 v176, s[36:37]
	s_mov_b32 m0, s40
	s_nop 0
	s_mov_b32 s40, m0
	s_mov_b32 m0, s67
	s_nop 0
	global_load_lds_dwordx4 v178, s[36:37]
	s_mov_b32 m0, s40
	s_waitcnt vmcnt(4)
	s_waitcnt lgkmcnt(0)
	s_barrier
	s_setprio 1
	s_waitcnt lgkmcnt(7)
	v_mfma_f32_16x16x32_bf16 v[78:81], v[58:61], v[170:173], v[78:81]
	v_mfma_f32_16x16x32_bf16 v[74:77], v[66:69], v[170:173], v[74:77]
	s_waitcnt lgkmcnt(5)
	v_mfma_f32_16x16x32_bf16 v[54:57], v[58:61], v[192:195], v[54:57]
	v_mfma_f32_16x16x32_bf16 v[50:53], v[66:69], v[192:195], v[50:53]
	s_waitcnt lgkmcnt(3)
	v_mfma_f32_16x16x32_bf16 v[30:33], v[58:61], v[200:203], v[30:33]
	v_mfma_f32_16x16x32_bf16 v[26:29], v[66:69], v[200:203], v[26:29]
	s_waitcnt lgkmcnt(1)
	v_mfma_f32_16x16x32_bf16 v[14:17], v[58:61], v[208:211], v[14:17]
	v_mfma_f32_16x16x32_bf16 v[10:13], v[66:69], v[208:211], v[10:13]
	v_mfma_f32_16x16x32_bf16 v[78:81], v[62:65], v[188:191], v[78:81]
	v_mfma_f32_16x16x32_bf16 v[74:77], v[70:73], v[188:191], v[74:77]
	v_mfma_f32_16x16x32_bf16 v[54:57], v[62:65], v[196:199], v[54:57]
	v_mfma_f32_16x16x32_bf16 v[50:53], v[70:73], v[196:199], v[50:53]
	v_mfma_f32_16x16x32_bf16 v[30:33], v[62:65], v[204:207], v[30:33]
	v_mfma_f32_16x16x32_bf16 v[26:29], v[70:73], v[204:207], v[26:29]
	s_waitcnt lgkmcnt(0)
	v_mfma_f32_16x16x32_bf16 v[14:17], v[62:65], v[212:215], v[14:17]
	v_mfma_f32_16x16x32_bf16 v[10:13], v[70:73], v[212:215], v[10:13]
	s_setprio 0
	s_setprio 1
	v_mfma_f32_16x16x32_bf16 v[42:45], v[146:149], v[170:173], v[42:45]
	v_mfma_f32_16x16x32_bf16 v[70:73], v[150:153], v[188:191], v[42:45]
	v_mfma_f32_16x16x32_bf16 v[42:45], v[154:157], v[170:173], v[46:49]
	v_mfma_f32_16x16x32_bf16 v[38:41], v[146:149], v[192:195], v[38:41]
	v_mfma_f32_16x16x32_bf16 v[34:37], v[154:157], v[192:195], v[34:37]
	v_mfma_f32_16x16x32_bf16 v[22:25], v[146:149], v[200:203], v[22:25]
	v_mfma_f32_16x16x32_bf16 v[18:21], v[154:157], v[200:203], v[18:21]
	v_mfma_f32_16x16x32_bf16 v[6:9], v[146:149], v[208:211], v[6:9]
	v_mfma_f32_16x16x32_bf16 v[2:5], v[154:157], v[208:211], v[2:5]
	v_mfma_f32_16x16x32_bf16 v[66:69], v[158:161], v[188:191], v[42:45]
	v_mfma_f32_16x16x32_bf16 v[38:41], v[150:153], v[196:199], v[38:41]
	v_mfma_f32_16x16x32_bf16 v[34:37], v[158:161], v[196:199], v[34:37]
	v_mfma_f32_16x16x32_bf16 v[22:25], v[150:153], v[204:207], v[22:25]
	v_mfma_f32_16x16x32_bf16 v[18:21], v[158:161], v[204:207], v[18:21]
	s_setprio 2
	s_barrier
	v_mfma_f32_16x16x32_bf16 v[6:9], v[150:153], v[212:215], v[6:9]
	v_mfma_f32_16x16x32_bf16 v[2:5], v[158:161], v[212:215], v[2:5]
	s_setprio 0
	s_add_i32 s81, s81, 2
	s_add_u32 s77, s77, 0x100
	s_addc_u32 s78, s78, 0
	s_add_u32 s34, s34, 0x100
	s_addc_u32 s35, s35, 0
	s_add_u32 s79, s79, 0x100
	s_addc_u32 s80, s80, 0
	s_cmp_gt_u32 s81, 29
	.p2align 6

.LBB0_2409:
	s_ashr_i32 s17, s16, 31
	s_lshl_b64 s[18:19], s[16:17], 20
	s_add_u32 s18, s33, s18
	s_addc_u32 s19, s34, s19
	s_and_b64 s[20:21], s[2:3], exec
	s_cselect_b32 s17, s19, s27
	s_cselect_b32 s71, s18, s26
	s_ashr_i32 s15, s14, 31
	s_lshl_b64 s[20:21], s[14:15], 20
	s_add_u32 s20, s35, s20
	s_addc_u32 s21, s36, s21
	s_and_b64 s[28:29], s[2:3], exec
	s_cselect_b32 s15, s21, s25
	s_cselect_b32 s73, s20, s24
	s_add_u32 s74, s24, 0x100
	s_addc_u32 s75, s25, 0
	s_add_u32 s24, s26, 0x80080
	s_addc_u32 s25, s27, 0
	s_add_u32 s76, s26, 0x100
	s_addc_u32 s77, s27, 0
	s_mov_b32 s78, -2
	s_waitcnt vmcnt(25)
	s_waitcnt vmcnt(24)
	s_waitcnt vmcnt(4)
	s_waitcnt vmcnt(2)
	s_waitcnt vmcnt(1)
	s_waitcnt vmcnt(0)
	ds_read_b128 v[130:133], v181
	ds_read_b128 v[134:137], v181 offset:1024
	ds_read_b128 v[138:141], v181 offset:2048
	ds_read_b128 v[142:145], v181 offset:3072
	ds_read_b128 v[146:149], v182
	ds_read_b128 v[150:153], v182 offset:1024
	ds_read_b128 v[154:157], v182 offset:2048
	ds_read_b128 v[158:161], v182 offset:3072
	s_cmp_eq_u32 s78, 28
	s_cselect_b32 s27, s15, s75
	s_cselect_b32 s26, s73, s74
	s_cselect_b32 s29, s17, s77
	s_cselect_b32 s28, s71, s76
	ds_read_b128 v[166:169], v183
	ds_read_b128 v[170:173], v183 offset:1024
	ds_read_b128 v[186:189], v183 offset:2048
	ds_read_b128 v[190:193], v183 offset:3072
	ds_read_b128 v[194:197], v183 offset:4096
	ds_read_b128 v[198:201], v183 offset:5120
	ds_read_b128 v[202:205], v183 offset:6144
	ds_read_b128 v[206:209], v183 offset:7168
	s_add_u32 s80, s24, 0xfff80000
	s_addc_u32 s81, s25, -1
	s_mov_b32 s79, m0
	s_mov_b32 m0, s64
	s_nop 0
	global_load_lds_dwordx4 v1, s[80:81]
	s_mov_b32 m0, s79
	s_nop 0
	s_mov_b32 s79, m0
	s_mov_b32 m0, s66
	s_nop 0
	global_load_lds_dwordx4 v177, s[80:81]
	s_mov_b32 m0, s79
	s_nop 0
	s_mov_b32 s79, m0
	s_mov_b32 m0, s65
	s_nop 0
	global_load_lds_dwordx4 v1, s[24:25]
	s_mov_b32 m0, s79
	s_nop 0
	s_mov_b32 s79, m0
	s_mov_b32 m0, s67
	s_nop 0
	global_load_lds_dwordx4 v177, s[24:25]
	s_mov_b32 m0, s79
	s_waitcnt vmcnt(8)
	s_waitcnt lgkmcnt(0)
	s_barrier
	s_setprio 1
	s_waitcnt lgkmcnt(7)
	v_mfma_f32_16x16x32_bf16 v[126:129], v[130:133], v[166:169], 0
	v_mfma_f32_16x16x32_bf16 v[122:125], v[138:141], v[166:169], 0
	s_waitcnt lgkmcnt(5)
	v_mfma_f32_16x16x32_bf16 v[118:121], v[130:133], v[186:189], 0
	v_mfma_f32_16x16x32_bf16 v[114:117], v[138:141], v[186:189], 0
	s_waitcnt lgkmcnt(3)
	v_mfma_f32_16x16x32_bf16 v[94:97], v[130:133], v[194:197], 0
	v_mfma_f32_16x16x32_bf16 v[90:93], v[138:141], v[194:197], 0
	s_waitcnt lgkmcnt(1)
	v_mfma_f32_16x16x32_bf16 v[86:89], v[130:133], v[202:205], 0
	v_mfma_f32_16x16x32_bf16 v[78:81], v[138:141], v[202:205], 0
	v_mfma_f32_16x16x32_bf16 v[126:129], v[134:137], v[170:173], v[126:129]
	v_mfma_f32_16x16x32_bf16 v[122:125], v[142:145], v[170:173], v[122:125]
	v_mfma_f32_16x16x32_bf16 v[118:121], v[134:137], v[190:193], v[118:121]
	v_mfma_f32_16x16x32_bf16 v[114:117], v[142:145], v[190:193], v[114:117]
	v_mfma_f32_16x16x32_bf16 v[94:97], v[134:137], v[198:201], v[94:97]
	v_mfma_f32_16x16x32_bf16 v[90:93], v[142:145], v[198:201], v[90:93]
	s_waitcnt lgkmcnt(0)
	v_mfma_f32_16x16x32_bf16 v[86:89], v[134:137], v[206:209], v[86:89]
	v_mfma_f32_16x16x32_bf16 v[78:81], v[142:145], v[206:209], v[78:81]
	s_setprio 0
	s_setprio 1
	v_mfma_f32_16x16x32_bf16 v[110:113], v[146:149], v[166:169], 0
	v_mfma_f32_16x16x32_bf16 v[106:109], v[154:157], v[166:169], 0
	v_mfma_f32_16x16x32_bf16 v[102:105], v[146:149], v[186:189], 0
	v_mfma_f32_16x16x32_bf16 v[98:101], v[154:157], v[186:189], 0
	v_mfma_f32_16x16x32_bf16 v[82:85], v[146:149], v[194:197], 0
	v_mfma_f32_16x16x32_bf16 v[74:77], v[154:157], v[194:197], 0
	v_mfma_f32_16x16x32_bf16 v[70:73], v[146:149], v[202:205], 0
	v_mfma_f32_16x16x32_bf16 v[66:69], v[154:157], v[202:205], 0
	v_mfma_f32_16x16x32_bf16 v[110:113], v[150:153], v[170:173], v[110:113]
	v_mfma_f32_16x16x32_bf16 v[106:109], v[158:161], v[170:173], v[106:109]
	v_mfma_f32_16x16x32_bf16 v[102:105], v[150:153], v[190:193], v[102:105]
	v_mfma_f32_16x16x32_bf16 v[98:101], v[158:161], v[190:193], v[98:101]
	v_mfma_f32_16x16x32_bf16 v[82:85], v[150:153], v[198:201], v[82:85]
	v_mfma_f32_16x16x32_bf16 v[74:77], v[158:161], v[198:201], v[74:77]
	s_setprio 2
	s_barrier
	v_mfma_f32_16x16x32_bf16 v[70:73], v[150:153], v[206:209], v[70:73]
	v_mfma_f32_16x16x32_bf16 v[66:69], v[158:161], v[206:209], v[66:69]
	s_setprio 0
	ds_read_b128 v[166:169], v183 offset:16384
	ds_read_b128 v[170:173], v183 offset:17408
	ds_read_b128 v[186:189], v183 offset:18432
	ds_read_b128 v[190:193], v183 offset:19456
	ds_read_b128 v[194:197], v183 offset:20480
	ds_read_b128 v[198:201], v183 offset:21504
	ds_read_b128 v[202:205], v183 offset:22528
	ds_read_b128 v[206:209], v183 offset:23552
	s_mov_b32 s79, m0
	s_mov_b32 m0, s41
	s_nop 0
	global_load_lds_dwordx4 v176, s[26:27]
	s_mov_b32 m0, s79
	s_add_u32 s80, s26, 0x80000
	s_mov_b32 s79, m0
	s_mov_b32 m0, s42
	s_nop 0
	global_load_lds_dwordx4 v178, s[26:27]
	s_mov_b32 m0, s79
	s_addc_u32 s81, s27, 0
	s_mov_b32 s79, m0
	s_mov_b32 m0, s43
	s_nop 0
	global_load_lds_dwordx4 v176, s[80:81]
	s_mov_b32 m0, s79
	s_nop 0
	s_mov_b32 s79, m0
	s_mov_b32 m0, s46
	s_nop 0
	global_load_lds_dwordx4 v178, s[80:81]
	s_mov_b32 m0, s79
	s_waitcnt vmcnt(4)
	s_waitcnt lgkmcnt(0)
	s_barrier
	s_setprio 1
	s_waitcnt lgkmcnt(7)
	v_mfma_f32_16x16x32_bf16 v[62:65], v[130:133], v[166:169], 0
	v_mfma_f32_16x16x32_bf16 v[58:61], v[138:141], v[166:169], 0
	s_waitcnt lgkmcnt(5)
	v_mfma_f32_16x16x32_bf16 v[46:49], v[130:133], v[186:189], 0
	v_mfma_f32_16x16x32_bf16 v[42:45], v[138:141], v[186:189], 0
	s_waitcnt lgkmcnt(3)
	v_mfma_f32_16x16x32_bf16 v[30:33], v[130:133], v[194:197], 0
	v_mfma_f32_16x16x32_bf16 v[26:29], v[138:141], v[194:197], 0
	s_waitcnt lgkmcnt(1)
	v_mfma_f32_16x16x32_bf16 v[14:17], v[130:133], v[202:205], 0
	v_mfma_f32_16x16x32_bf16 v[10:13], v[138:141], v[202:205], 0
	v_mfma_f32_16x16x32_bf16 v[62:65], v[134:137], v[170:173], v[62:65]
	v_mfma_f32_16x16x32_bf16 v[58:61], v[142:145], v[170:173], v[58:61]
	v_mfma_f32_16x16x32_bf16 v[46:49], v[134:137], v[190:193], v[46:49]
	v_mfma_f32_16x16x32_bf16 v[42:45], v[142:145], v[190:193], v[42:45]
	v_mfma_f32_16x16x32_bf16 v[30:33], v[134:137], v[198:201], v[30:33]
	v_mfma_f32_16x16x32_bf16 v[26:29], v[142:145], v[198:201], v[26:29]
	s_waitcnt lgkmcnt(0)
	v_mfma_f32_16x16x32_bf16 v[14:17], v[134:137], v[206:209], v[14:17]
	v_mfma_f32_16x16x32_bf16 v[10:13], v[142:145], v[206:209], v[10:13]
	s_setprio 0
	s_setprio 1
	v_mfma_f32_16x16x32_bf16 v[54:57], v[146:149], v[166:169], 0
	v_mfma_f32_16x16x32_bf16 v[50:53], v[154:157], v[166:169], 0
	v_mfma_f32_16x16x32_bf16 v[38:41], v[146:149], v[186:189], 0
	v_mfma_f32_16x16x32_bf16 v[34:37], v[154:157], v[186:189], 0
	v_mfma_f32_16x16x32_bf16 v[22:25], v[146:149], v[194:197], 0
	v_mfma_f32_16x16x32_bf16 v[18:21], v[154:157], v[194:197], 0
	v_mfma_f32_16x16x32_bf16 v[6:9], v[146:149], v[202:205], 0
	v_mfma_f32_16x16x32_bf16 v[2:5], v[154:157], v[202:205], 0
	v_mfma_f32_16x16x32_bf16 v[54:57], v[150:153], v[170:173], v[54:57]
	v_mfma_f32_16x16x32_bf16 v[50:53], v[158:161], v[170:173], v[50:53]
	v_mfma_f32_16x16x32_bf16 v[38:41], v[150:153], v[190:193], v[38:41]
	v_mfma_f32_16x16x32_bf16 v[34:37], v[158:161], v[190:193], v[34:37]
	v_mfma_f32_16x16x32_bf16 v[22:25], v[150:153], v[198:201], v[22:25]
	v_mfma_f32_16x16x32_bf16 v[18:21], v[158:161], v[198:201], v[18:21]
	s_setprio 2
	s_barrier
	v_mfma_f32_16x16x32_bf16 v[6:9], v[150:153], v[206:209], v[6:9]
	v_mfma_f32_16x16x32_bf16 v[2:5], v[158:161], v[206:209], v[2:5]
	s_setprio 0
	ds_read_b128 v[130:133], v184
	ds_read_b128 v[134:137], v184 offset:1024
	ds_read_b128 v[138:141], v184 offset:2048
	ds_read_b128 v[142:145], v184 offset:3072
	ds_read_b128 v[146:149], v185
	ds_read_b128 v[150:153], v185 offset:1024
	ds_read_b128 v[154:157], v185 offset:2048
	ds_read_b128 v[158:161], v185 offset:3072
	ds_read_b128 v[166:169], v183 offset:32768
	ds_read_b128 v[170:173], v183 offset:33792
	ds_read_b128 v[186:189], v183 offset:34816
	ds_read_b128 v[190:193], v183 offset:35840
	ds_read_b128 v[194:197], v183 offset:36864
	ds_read_b128 v[198:201], v183 offset:37888
	ds_read_b128 v[202:205], v183 offset:38912
	ds_read_b128 v[206:209], v183 offset:39936
	s_mov_b32 s79, m0
	s_mov_b32 m0, s40
	s_nop 0
	global_load_lds_dwordx4 v1, s[28:29]
	s_mov_b32 m0, s79
	s_nop 0
	s_mov_b32 s79, m0
	s_mov_b32 m0, s47
	s_nop 0
	global_load_lds_dwordx4 v177, s[28:29]
	s_mov_b32 m0, s79
	s_add_u32 s28, s28, 0x80000
	s_addc_u32 s29, s29, 0
	s_mov_b32 s79, m0
	s_mov_b32 m0, s48
	s_nop 0
	global_load_lds_dwordx4 v1, s[28:29]
	s_mov_b32 m0, s79
	s_nop 0
	s_mov_b32 s79, m0
	s_mov_b32 m0, s49
	s_nop 0
	global_load_lds_dwordx4 v177, s[28:29]
	s_mov_b32 m0, s79
	s_waitcnt vmcnt(8)
	s_waitcnt lgkmcnt(0)
	s_barrier
	s_setprio 1
	s_waitcnt lgkmcnt(7)
	v_mfma_f32_16x16x32_bf16 v[126:129], v[130:133], v[166:169], v[126:129]
	v_mfma_f32_16x16x32_bf16 v[122:125], v[138:141], v[166:169], v[122:125]
	s_waitcnt lgkmcnt(5)
	v_mfma_f32_16x16x32_bf16 v[118:121], v[130:133], v[186:189], v[118:121]
	v_mfma_f32_16x16x32_bf16 v[114:117], v[138:141], v[186:189], v[114:117]
	s_waitcnt lgkmcnt(3)
	v_mfma_f32_16x16x32_bf16 v[94:97], v[130:133], v[194:197], v[94:97]
	v_mfma_f32_16x16x32_bf16 v[90:93], v[138:141], v[194:197], v[90:93]
	s_waitcnt lgkmcnt(1)
	v_mfma_f32_16x16x32_bf16 v[86:89], v[130:133], v[202:205], v[86:89]
	v_mfma_f32_16x16x32_bf16 v[78:81], v[138:141], v[202:205], v[78:81]
	v_mfma_f32_16x16x32_bf16 v[126:129], v[134:137], v[170:173], v[126:129]
	v_mfma_f32_16x16x32_bf16 v[122:125], v[142:145], v[170:173], v[122:125]
	v_mfma_f32_16x16x32_bf16 v[118:121], v[134:137], v[190:193], v[118:121]
	v_mfma_f32_16x16x32_bf16 v[114:117], v[142:145], v[190:193], v[114:117]
	v_mfma_f32_16x16x32_bf16 v[94:97], v[134:137], v[198:201], v[94:97]
	v_mfma_f32_16x16x32_bf16 v[90:93], v[142:145], v[198:201], v[90:93]
	s_waitcnt lgkmcnt(0)
	v_mfma_f32_16x16x32_bf16 v[86:89], v[134:137], v[206:209], v[86:89]
	v_mfma_f32_16x16x32_bf16 v[78:81], v[142:145], v[206:209], v[78:81]
	s_setprio 0
	s_setprio 1
	v_mfma_f32_16x16x32_bf16 v[110:113], v[146:149], v[166:169], v[110:113]
	v_mfma_f32_16x16x32_bf16 v[106:109], v[154:157], v[166:169], v[106:109]
	v_mfma_f32_16x16x32_bf16 v[102:105], v[146:149], v[186:189], v[102:105]
	v_mfma_f32_16x16x32_bf16 v[98:101], v[154:157], v[186:189], v[98:101]
	v_mfma_f32_16x16x32_bf16 v[82:85], v[146:149], v[194:197], v[82:85]
	v_mfma_f32_16x16x32_bf16 v[74:77], v[154:157], v[194:197], v[74:77]
	v_mfma_f32_16x16x32_bf16 v[70:73], v[146:149], v[202:205], v[70:73]
	v_mfma_f32_16x16x32_bf16 v[66:69], v[154:157], v[202:205], v[66:69]
	v_mfma_f32_16x16x32_bf16 v[110:113], v[150:153], v[170:173], v[110:113]
	v_mfma_f32_16x16x32_bf16 v[106:109], v[158:161], v[170:173], v[106:109]
	v_mfma_f32_16x16x32_bf16 v[102:105], v[150:153], v[190:193], v[102:105]
	v_mfma_f32_16x16x32_bf16 v[98:101], v[158:161], v[190:193], v[98:101]
	v_mfma_f32_16x16x32_bf16 v[82:85], v[150:153], v[198:201], v[82:85]
	v_mfma_f32_16x16x32_bf16 v[74:77], v[158:161], v[198:201], v[74:77]
	s_setprio 2
	s_barrier
	v_mfma_f32_16x16x32_bf16 v[70:73], v[150:153], v[206:209], v[70:73]
	v_mfma_f32_16x16x32_bf16 v[66:69], v[158:161], v[206:209], v[66:69]
	s_setprio 0
	ds_read_b128 v[166:169], v183 offset:49152
	ds_read_b128 v[170:173], v183 offset:50176
	ds_read_b128 v[186:189], v183 offset:51200
	ds_read_b128 v[190:193], v183 offset:52224
	ds_read_b128 v[194:197], v183 offset:53248
	ds_read_b128 v[198:201], v183 offset:54272
	ds_read_b128 v[202:205], v183 offset:55296
	ds_read_b128 v[206:209], v183 offset:56320
	s_add_u32 s28, s26, 0x80
	s_addc_u32 s29, s27, 0
	s_mov_b32 s79, m0
	s_mov_b32 m0, s56
	s_nop 0
	global_load_lds_dwordx4 v176, s[28:29]
	s_mov_b32 m0, s79
	s_add_u32 s26, s26, 0x80080
	s_mov_b32 s79, m0
	s_mov_b32 m0, s57
	s_nop 0
	global_load_lds_dwordx4 v178, s[28:29]
	s_mov_b32 m0, s79
	s_addc_u32 s27, s27, 0
	s_mov_b32 s28, m0
	s_mov_b32 m0, s58
	s_nop 0
	global_load_lds_dwordx4 v176, s[26:27]
	s_mov_b32 m0, s28
	s_nop 0
	s_mov_b32 s28, m0
	s_mov_b32 m0, s59
	s_nop 0
	global_load_lds_dwordx4 v178, s[26:27]
	s_mov_b32 m0, s28
	s_waitcnt vmcnt(4)
	s_waitcnt lgkmcnt(0)
	s_barrier
	s_setprio 1
	s_waitcnt lgkmcnt(7)
	v_mfma_f32_16x16x32_bf16 v[62:65], v[130:133], v[166:169], v[62:65]
	v_mfma_f32_16x16x32_bf16 v[58:61], v[138:141], v[166:169], v[58:61]
	s_waitcnt lgkmcnt(5)
	v_mfma_f32_16x16x32_bf16 v[46:49], v[130:133], v[186:189], v[46:49]
	v_mfma_f32_16x16x32_bf16 v[42:45], v[138:141], v[186:189], v[42:45]
	s_waitcnt lgkmcnt(3)
	v_mfma_f32_16x16x32_bf16 v[30:33], v[130:133], v[194:197], v[30:33]
	v_mfma_f32_16x16x32_bf16 v[26:29], v[138:141], v[194:197], v[26:29]
	s_waitcnt lgkmcnt(1)
	v_mfma_f32_16x16x32_bf16 v[14:17], v[130:133], v[202:205], v[14:17]
	v_mfma_f32_16x16x32_bf16 v[10:13], v[138:141], v[202:205], v[10:13]
	v_mfma_f32_16x16x32_bf16 v[62:65], v[134:137], v[170:173], v[62:65]
	v_mfma_f32_16x16x32_bf16 v[58:61], v[142:145], v[170:173], v[58:61]
	v_mfma_f32_16x16x32_bf16 v[46:49], v[134:137], v[190:193], v[46:49]
	v_mfma_f32_16x16x32_bf16 v[42:45], v[142:145], v[190:193], v[42:45]
	v_mfma_f32_16x16x32_bf16 v[30:33], v[134:137], v[198:201], v[30:33]
	v_mfma_f32_16x16x32_bf16 v[26:29], v[142:145], v[198:201], v[26:29]
	s_waitcnt lgkmcnt(0)
	v_mfma_f32_16x16x32_bf16 v[14:17], v[134:137], v[206:209], v[14:17]
	v_mfma_f32_16x16x32_bf16 v[10:13], v[142:145], v[206:209], v[10:13]
	s_setprio 0
	s_setprio 1
	v_mfma_f32_16x16x32_bf16 v[54:57], v[146:149], v[166:169], v[54:57]
	v_mfma_f32_16x16x32_bf16 v[50:53], v[154:157], v[166:169], v[50:53]
	v_mfma_f32_16x16x32_bf16 v[38:41], v[146:149], v[186:189], v[38:41]
	v_mfma_f32_16x16x32_bf16 v[34:37], v[154:157], v[186:189], v[34:37]
	v_mfma_f32_16x16x32_bf16 v[22:25], v[146:149], v[194:197], v[22:25]
	v_mfma_f32_16x16x32_bf16 v[18:21], v[154:157], v[194:197], v[18:21]
	v_mfma_f32_16x16x32_bf16 v[6:9], v[146:149], v[202:205], v[6:9]
	v_mfma_f32_16x16x32_bf16 v[2:5], v[154:157], v[202:205], v[2:5]
	v_mfma_f32_16x16x32_bf16 v[54:57], v[150:153], v[170:173], v[54:57]
	v_mfma_f32_16x16x32_bf16 v[50:53], v[158:161], v[170:173], v[50:53]
	v_mfma_f32_16x16x32_bf16 v[38:41], v[150:153], v[190:193], v[38:41]
	v_mfma_f32_16x16x32_bf16 v[34:37], v[158:161], v[190:193], v[34:37]
	v_mfma_f32_16x16x32_bf16 v[22:25], v[150:153], v[198:201], v[22:25]
	v_mfma_f32_16x16x32_bf16 v[18:21], v[158:161], v[198:201], v[18:21]
	s_setprio 2
	s_barrier
	v_mfma_f32_16x16x32_bf16 v[6:9], v[150:153], v[206:209], v[6:9]
	v_mfma_f32_16x16x32_bf16 v[2:5], v[158:161], v[206:209], v[2:5]
	s_setprio 0
	s_add_i32 s78, s78, 2
	s_add_u32 s74, s74, 0x100
	s_addc_u32 s75, s75, 0
	s_add_u32 s24, s24, 0x100
	s_addc_u32 s25, s25, 0
	s_add_u32 s76, s76, 0x100
	s_addc_u32 s77, s77, 0
	s_cmp_gt_u32 s78, 29
	.p2align 6

.LBB0_2593:
	s_ashr_i32 s11, s10, 31
	s_lshl_b64 s[12:13], s[10:11], 20
	s_add_u32 s12, s26, s12
	s_addc_u32 s13, s27, s13
	s_and_b64 s[14:15], s[2:3], exec
	s_cselect_b32 s11, s13, s21
	s_cselect_b32 s62, s12, s20
	s_ashr_i32 s9, s8, 31
	s_lshl_b64 s[14:15], s[8:9], 20
	s_add_u32 s14, s28, s14
	s_addc_u32 s15, s29, s15
	s_and_b64 s[22:23], s[2:3], exec
	s_cselect_b32 s9, s15, s19
	s_cselect_b32 s63, s14, s18
	s_add_u32 s64, s18, 0x100
	s_addc_u32 s65, s19, 0
	s_add_u32 s18, s20, 0x80080
	s_addc_u32 s19, s21, 0
	s_add_u32 s66, s20, 0x100
	s_addc_u32 s67, s21, 0
	s_mov_b32 s70, -2
	ds_read_b128 v[148:151], v143
	ds_read_b128 v[152:155], v143 offset:1024
	ds_read_b128 v[156:159], v143 offset:2048
	ds_read_b128 v[160:163], v143 offset:3072
	ds_read_b128 v[164:167], v144
	ds_read_b128 v[168:171], v144 offset:1024
	ds_read_b128 v[172:175], v144 offset:2048
	ds_read_b128 v[176:179], v144 offset:3072
	s_cmp_eq_u32 s70, 28
	s_cselect_b32 s21, s9, s65
	s_cselect_b32 s20, s63, s64
	s_cselect_b32 s23, s11, s67
	s_cselect_b32 s22, s62, s66
	ds_read_b128 v[180:183], v145
	ds_read_b128 v[184:187], v145 offset:1024
	ds_read_b128 v[188:191], v145 offset:2048
	ds_read_b128 v[192:195], v145 offset:3072
	ds_read_b128 v[196:199], v145 offset:4096
	ds_read_b128 v[200:203], v145 offset:5120
	ds_read_b128 v[204:207], v145 offset:6144
	ds_read_b128 v[208:211], v145 offset:7168
	s_add_u32 s74, s18, 0xfff80000
	s_addc_u32 s75, s19, -1
	s_mov_b32 s71, m0
	s_mov_b32 m0, s48
	s_nop 0
	global_load_lds_dwordx4 v138, s[74:75]
	s_mov_b32 m0, s71
	s_nop 0
	s_mov_b32 s71, m0
	s_mov_b32 m0, s57
	s_nop 0
	global_load_lds_dwordx4 v140, s[74:75]
	s_mov_b32 m0, s71
	s_nop 0
	s_mov_b32 s71, m0
	s_mov_b32 m0, s49
	s_nop 0
	global_load_lds_dwordx4 v138, s[18:19]
	s_mov_b32 m0, s71
	s_nop 0
	s_mov_b32 s71, m0
	s_mov_b32 m0, s58
	s_nop 0
	global_load_lds_dwordx4 v140, s[18:19]
	s_mov_b32 m0, s71
	s_waitcnt vmcnt(8)
	s_waitcnt lgkmcnt(0)
	s_barrier
	s_setprio 1
	s_waitcnt lgkmcnt(7)
	v_mfma_f32_16x16x32_bf16 v[126:129], v[148:151], v[180:183], 0
	v_mfma_f32_16x16x32_bf16 v[122:125], v[156:159], v[180:183], 0
	s_waitcnt lgkmcnt(5)
	v_mfma_f32_16x16x32_bf16 v[110:113], v[148:151], v[188:191], 0
	v_mfma_f32_16x16x32_bf16 v[106:109], v[156:159], v[188:191], 0
	s_waitcnt lgkmcnt(3)
	v_mfma_f32_16x16x32_bf16 v[94:97], v[148:151], v[196:199], 0
	v_mfma_f32_16x16x32_bf16 v[90:93], v[156:159], v[196:199], 0
	s_waitcnt lgkmcnt(1)
	v_mfma_f32_16x16x32_bf16 v[78:81], v[148:151], v[204:207], 0
	v_mfma_f32_16x16x32_bf16 v[74:77], v[156:159], v[204:207], 0
	v_mfma_f32_16x16x32_bf16 v[126:129], v[152:155], v[184:187], v[126:129]
	v_mfma_f32_16x16x32_bf16 v[122:125], v[160:163], v[184:187], v[122:125]
	v_mfma_f32_16x16x32_bf16 v[110:113], v[152:155], v[192:195], v[110:113]
	v_mfma_f32_16x16x32_bf16 v[106:109], v[160:163], v[192:195], v[106:109]
	v_mfma_f32_16x16x32_bf16 v[94:97], v[152:155], v[200:203], v[94:97]
	v_mfma_f32_16x16x32_bf16 v[90:93], v[160:163], v[200:203], v[90:93]
	s_waitcnt lgkmcnt(0)
	v_mfma_f32_16x16x32_bf16 v[78:81], v[152:155], v[208:211], v[78:81]
	v_mfma_f32_16x16x32_bf16 v[74:77], v[160:163], v[208:211], v[74:77]
	s_setprio 0
	s_setprio 1
	v_mfma_f32_16x16x32_bf16 v[118:121], v[164:167], v[180:183], 0
	v_mfma_f32_16x16x32_bf16 v[114:117], v[172:175], v[180:183], 0
	v_mfma_f32_16x16x32_bf16 v[102:105], v[164:167], v[188:191], 0
	v_mfma_f32_16x16x32_bf16 v[98:101], v[172:175], v[188:191], 0
	v_mfma_f32_16x16x32_bf16 v[86:89], v[164:167], v[196:199], 0
	v_mfma_f32_16x16x32_bf16 v[82:85], v[172:175], v[196:199], 0
	v_mfma_f32_16x16x32_bf16 v[70:73], v[164:167], v[204:207], 0
	v_mfma_f32_16x16x32_bf16 v[66:69], v[172:175], v[204:207], 0
	v_mfma_f32_16x16x32_bf16 v[118:121], v[168:171], v[184:187], v[118:121]
	v_mfma_f32_16x16x32_bf16 v[114:117], v[176:179], v[184:187], v[114:117]
	v_mfma_f32_16x16x32_bf16 v[102:105], v[168:171], v[192:195], v[102:105]
	v_mfma_f32_16x16x32_bf16 v[98:101], v[176:179], v[192:195], v[98:101]
	v_mfma_f32_16x16x32_bf16 v[86:89], v[168:171], v[200:203], v[86:89]
	v_mfma_f32_16x16x32_bf16 v[82:85], v[176:179], v[200:203], v[82:85]
	s_setprio 2
	s_barrier
	v_mfma_f32_16x16x32_bf16 v[70:73], v[168:171], v[208:211], v[70:73]
	v_mfma_f32_16x16x32_bf16 v[66:69], v[176:179], v[208:211], v[66:69]
	s_setprio 0
	ds_read_b128 v[180:183], v145 offset:16384
	ds_read_b128 v[184:187], v145 offset:17408
	ds_read_b128 v[188:191], v145 offset:18432
	ds_read_b128 v[192:195], v145 offset:19456
	ds_read_b128 v[196:199], v145 offset:20480
	ds_read_b128 v[200:203], v145 offset:21504
	ds_read_b128 v[204:207], v145 offset:22528
	ds_read_b128 v[208:211], v145 offset:23552
	s_mov_b32 s71, m0
	s_mov_b32 m0, s35
	s_nop 0
	global_load_lds_dwordx4 v139, s[20:21]
	s_mov_b32 m0, s71
	s_add_u32 s74, s20, 0x80000
	s_mov_b32 s71, m0
	s_mov_b32 m0, s36
	s_nop 0
	global_load_lds_dwordx4 v141, s[20:21]
	s_mov_b32 m0, s71
	s_addc_u32 s75, s21, 0
	s_mov_b32 s71, m0
	s_mov_b32 m0, s37
	s_nop 0
	global_load_lds_dwordx4 v139, s[74:75]
	s_mov_b32 m0, s71
	s_nop 0
	s_mov_b32 s71, m0
	s_mov_b32 m0, s40
	s_nop 0
	global_load_lds_dwordx4 v141, s[74:75]
	s_mov_b32 m0, s71
	s_waitcnt vmcnt(4)
	s_waitcnt lgkmcnt(0)
	s_barrier
	s_setprio 1
	s_waitcnt lgkmcnt(7)
	v_mfma_f32_16x16x32_bf16 v[62:65], v[148:151], v[180:183], 0
	v_mfma_f32_16x16x32_bf16 v[58:61], v[156:159], v[180:183], 0
	s_waitcnt lgkmcnt(5)
	v_mfma_f32_16x16x32_bf16 v[46:49], v[148:151], v[188:191], 0
	v_mfma_f32_16x16x32_bf16 v[42:45], v[156:159], v[188:191], 0
	s_waitcnt lgkmcnt(3)
	v_mfma_f32_16x16x32_bf16 v[30:33], v[148:151], v[196:199], 0
	v_mfma_f32_16x16x32_bf16 v[26:29], v[156:159], v[196:199], 0
	s_waitcnt lgkmcnt(1)
	v_mfma_f32_16x16x32_bf16 v[14:17], v[148:151], v[204:207], 0
	v_mfma_f32_16x16x32_bf16 v[10:13], v[156:159], v[204:207], 0
	v_mfma_f32_16x16x32_bf16 v[62:65], v[152:155], v[184:187], v[62:65]
	v_mfma_f32_16x16x32_bf16 v[58:61], v[160:163], v[184:187], v[58:61]
	v_mfma_f32_16x16x32_bf16 v[46:49], v[152:155], v[192:195], v[46:49]
	v_mfma_f32_16x16x32_bf16 v[42:45], v[160:163], v[192:195], v[42:45]
	v_mfma_f32_16x16x32_bf16 v[30:33], v[152:155], v[200:203], v[30:33]
	v_mfma_f32_16x16x32_bf16 v[26:29], v[160:163], v[200:203], v[26:29]
	s_waitcnt lgkmcnt(0)
	v_mfma_f32_16x16x32_bf16 v[14:17], v[152:155], v[208:211], v[14:17]
	v_mfma_f32_16x16x32_bf16 v[10:13], v[160:163], v[208:211], v[10:13]
	s_setprio 0
	s_setprio 1
	v_mfma_f32_16x16x32_bf16 v[54:57], v[164:167], v[180:183], 0
	v_mfma_f32_16x16x32_bf16 v[50:53], v[172:175], v[180:183], 0
	v_mfma_f32_16x16x32_bf16 v[38:41], v[164:167], v[188:191], 0
	v_mfma_f32_16x16x32_bf16 v[34:37], v[172:175], v[188:191], 0
	v_mfma_f32_16x16x32_bf16 v[22:25], v[164:167], v[196:199], 0
	v_mfma_f32_16x16x32_bf16 v[18:21], v[172:175], v[196:199], 0
	v_mfma_f32_16x16x32_bf16 v[6:9], v[164:167], v[204:207], 0
	v_mfma_f32_16x16x32_bf16 v[2:5], v[172:175], v[204:207], 0
	v_mfma_f32_16x16x32_bf16 v[54:57], v[168:171], v[184:187], v[54:57]
	v_mfma_f32_16x16x32_bf16 v[50:53], v[176:179], v[184:187], v[50:53]
	v_mfma_f32_16x16x32_bf16 v[38:41], v[168:171], v[192:195], v[38:41]
	v_mfma_f32_16x16x32_bf16 v[34:37], v[176:179], v[192:195], v[34:37]
	v_mfma_f32_16x16x32_bf16 v[22:25], v[168:171], v[200:203], v[22:25]
	v_mfma_f32_16x16x32_bf16 v[18:21], v[176:179], v[200:203], v[18:21]
	s_setprio 2
	s_barrier
	v_mfma_f32_16x16x32_bf16 v[6:9], v[168:171], v[208:211], v[6:9]
	v_mfma_f32_16x16x32_bf16 v[2:5], v[176:179], v[208:211], v[2:5]
	s_setprio 0
	ds_read_b128 v[148:151], v146
	ds_read_b128 v[152:155], v146 offset:1024
	ds_read_b128 v[156:159], v146 offset:2048
	ds_read_b128 v[160:163], v146 offset:3072
	ds_read_b128 v[164:167], v147
	ds_read_b128 v[168:171], v147 offset:1024
	ds_read_b128 v[172:175], v147 offset:2048
	ds_read_b128 v[176:179], v147 offset:3072
	ds_read_b128 v[180:183], v145 offset:32768
	ds_read_b128 v[184:187], v145 offset:33792
	ds_read_b128 v[188:191], v145 offset:34816
	ds_read_b128 v[192:195], v145 offset:35840
	ds_read_b128 v[196:199], v145 offset:36864
	ds_read_b128 v[200:203], v145 offset:37888
	ds_read_b128 v[204:207], v145 offset:38912
	ds_read_b128 v[208:211], v145 offset:39936
	s_mov_b32 s71, m0
	s_mov_b32 m0, s31
	s_nop 0
	global_load_lds_dwordx4 v138, s[22:23]
	s_mov_b32 m0, s71
	s_nop 0
	s_mov_b32 s71, m0
	s_mov_b32 m0, s41
	s_nop 0
	global_load_lds_dwordx4 v140, s[22:23]
	s_mov_b32 m0, s71
	s_add_u32 s22, s22, 0x80000
	s_addc_u32 s23, s23, 0
	s_mov_b32 s71, m0
	s_mov_b32 m0, s42
	s_nop 0
	global_load_lds_dwordx4 v138, s[22:23]
	s_mov_b32 m0, s71
	s_nop 0
	s_mov_b32 s71, m0
	s_mov_b32 m0, s43
	s_nop 0
	global_load_lds_dwordx4 v140, s[22:23]
	s_mov_b32 m0, s71
	s_waitcnt vmcnt(8)
	s_waitcnt lgkmcnt(0)
	s_barrier
	s_setprio 1
	s_waitcnt lgkmcnt(7)
	v_mfma_f32_16x16x32_bf16 v[126:129], v[148:151], v[180:183], v[126:129]
	v_mfma_f32_16x16x32_bf16 v[122:125], v[156:159], v[180:183], v[122:125]
	s_waitcnt lgkmcnt(5)
	v_mfma_f32_16x16x32_bf16 v[110:113], v[148:151], v[188:191], v[110:113]
	v_mfma_f32_16x16x32_bf16 v[106:109], v[156:159], v[188:191], v[106:109]
	s_waitcnt lgkmcnt(3)
	v_mfma_f32_16x16x32_bf16 v[94:97], v[148:151], v[196:199], v[94:97]
	v_mfma_f32_16x16x32_bf16 v[90:93], v[156:159], v[196:199], v[90:93]
	s_waitcnt lgkmcnt(1)
	v_mfma_f32_16x16x32_bf16 v[78:81], v[148:151], v[204:207], v[78:81]
	v_mfma_f32_16x16x32_bf16 v[74:77], v[156:159], v[204:207], v[74:77]
	v_mfma_f32_16x16x32_bf16 v[126:129], v[152:155], v[184:187], v[126:129]
	v_mfma_f32_16x16x32_bf16 v[122:125], v[160:163], v[184:187], v[122:125]
	v_mfma_f32_16x16x32_bf16 v[110:113], v[152:155], v[192:195], v[110:113]
	v_mfma_f32_16x16x32_bf16 v[106:109], v[160:163], v[192:195], v[106:109]
	v_mfma_f32_16x16x32_bf16 v[94:97], v[152:155], v[200:203], v[94:97]
	v_mfma_f32_16x16x32_bf16 v[90:93], v[160:163], v[200:203], v[90:93]
	s_waitcnt lgkmcnt(0)
	v_mfma_f32_16x16x32_bf16 v[78:81], v[152:155], v[208:211], v[78:81]
	v_mfma_f32_16x16x32_bf16 v[74:77], v[160:163], v[208:211], v[74:77]
	s_setprio 0
	s_setprio 1
	v_mfma_f32_16x16x32_bf16 v[118:121], v[164:167], v[180:183], v[118:121]
	v_mfma_f32_16x16x32_bf16 v[114:117], v[172:175], v[180:183], v[114:117]
	v_mfma_f32_16x16x32_bf16 v[102:105], v[164:167], v[188:191], v[102:105]
	v_mfma_f32_16x16x32_bf16 v[98:101], v[172:175], v[188:191], v[98:101]
	v_mfma_f32_16x16x32_bf16 v[86:89], v[164:167], v[196:199], v[86:89]
	v_mfma_f32_16x16x32_bf16 v[82:85], v[172:175], v[196:199], v[82:85]
	v_mfma_f32_16x16x32_bf16 v[70:73], v[164:167], v[204:207], v[70:73]
	v_mfma_f32_16x16x32_bf16 v[66:69], v[172:175], v[204:207], v[66:69]
	v_mfma_f32_16x16x32_bf16 v[118:121], v[168:171], v[184:187], v[118:121]
	v_mfma_f32_16x16x32_bf16 v[114:117], v[176:179], v[184:187], v[114:117]
	v_mfma_f32_16x16x32_bf16 v[102:105], v[168:171], v[192:195], v[102:105]
	v_mfma_f32_16x16x32_bf16 v[98:101], v[176:179], v[192:195], v[98:101]
	v_mfma_f32_16x16x32_bf16 v[86:89], v[168:171], v[200:203], v[86:89]
	v_mfma_f32_16x16x32_bf16 v[82:85], v[176:179], v[200:203], v[82:85]
	s_setprio 2
	s_barrier
	v_mfma_f32_16x16x32_bf16 v[70:73], v[168:171], v[208:211], v[70:73]
	v_mfma_f32_16x16x32_bf16 v[66:69], v[176:179], v[208:211], v[66:69]
	s_setprio 0
	ds_read_b128 v[180:183], v145 offset:49152
	ds_read_b128 v[184:187], v145 offset:50176
	ds_read_b128 v[188:191], v145 offset:51200
	ds_read_b128 v[192:195], v145 offset:52224
	ds_read_b128 v[196:199], v145 offset:53248
	ds_read_b128 v[200:203], v145 offset:54272
	ds_read_b128 v[204:207], v145 offset:55296
	ds_read_b128 v[208:211], v145 offset:56320
	s_add_u32 s22, s20, 0x80
	s_addc_u32 s23, s21, 0
	s_mov_b32 s71, m0
	s_mov_b32 m0, s44
	s_nop 0
	global_load_lds_dwordx4 v139, s[22:23]
	s_mov_b32 m0, s71
	s_add_u32 s20, s20, 0x80080
	s_mov_b32 s71, m0
	s_mov_b32 m0, s45
	s_nop 0
	global_load_lds_dwordx4 v141, s[22:23]
	s_mov_b32 m0, s71
	s_addc_u32 s21, s21, 0
	s_mov_b32 s22, m0
	s_mov_b32 m0, s46
	s_nop 0
	global_load_lds_dwordx4 v139, s[20:21]
	s_mov_b32 m0, s22
	s_nop 0
	s_mov_b32 s22, m0
	s_mov_b32 m0, s47
	s_nop 0
	global_load_lds_dwordx4 v141, s[20:21]
	s_mov_b32 m0, s22
	s_waitcnt vmcnt(4)
	s_waitcnt lgkmcnt(0)
	s_barrier
	s_setprio 1
	s_waitcnt lgkmcnt(7)
	v_mfma_f32_16x16x32_bf16 v[62:65], v[148:151], v[180:183], v[62:65]
	v_mfma_f32_16x16x32_bf16 v[58:61], v[156:159], v[180:183], v[58:61]
	s_waitcnt lgkmcnt(5)
	v_mfma_f32_16x16x32_bf16 v[46:49], v[148:151], v[188:191], v[46:49]
	v_mfma_f32_16x16x32_bf16 v[42:45], v[156:159], v[188:191], v[42:45]
	s_waitcnt lgkmcnt(3)
	v_mfma_f32_16x16x32_bf16 v[30:33], v[148:151], v[196:199], v[30:33]
	v_mfma_f32_16x16x32_bf16 v[26:29], v[156:159], v[196:199], v[26:29]
	s_waitcnt lgkmcnt(1)
	v_mfma_f32_16x16x32_bf16 v[14:17], v[148:151], v[204:207], v[14:17]
	v_mfma_f32_16x16x32_bf16 v[10:13], v[156:159], v[204:207], v[10:13]
	v_mfma_f32_16x16x32_bf16 v[62:65], v[152:155], v[184:187], v[62:65]
	v_mfma_f32_16x16x32_bf16 v[58:61], v[160:163], v[184:187], v[58:61]
	v_mfma_f32_16x16x32_bf16 v[46:49], v[152:155], v[192:195], v[46:49]
	v_mfma_f32_16x16x32_bf16 v[42:45], v[160:163], v[192:195], v[42:45]
	v_mfma_f32_16x16x32_bf16 v[30:33], v[152:155], v[200:203], v[30:33]
	v_mfma_f32_16x16x32_bf16 v[26:29], v[160:163], v[200:203], v[26:29]
	s_waitcnt lgkmcnt(0)
	v_mfma_f32_16x16x32_bf16 v[14:17], v[152:155], v[208:211], v[14:17]
	v_mfma_f32_16x16x32_bf16 v[10:13], v[160:163], v[208:211], v[10:13]
	s_setprio 0
	s_setprio 1
	v_mfma_f32_16x16x32_bf16 v[54:57], v[164:167], v[180:183], v[54:57]
	v_mfma_f32_16x16x32_bf16 v[50:53], v[172:175], v[180:183], v[50:53]
	v_mfma_f32_16x16x32_bf16 v[38:41], v[164:167], v[188:191], v[38:41]
	v_mfma_f32_16x16x32_bf16 v[34:37], v[172:175], v[188:191], v[34:37]
	v_mfma_f32_16x16x32_bf16 v[22:25], v[164:167], v[196:199], v[22:25]
	v_mfma_f32_16x16x32_bf16 v[18:21], v[172:175], v[196:199], v[18:21]
	v_mfma_f32_16x16x32_bf16 v[6:9], v[164:167], v[204:207], v[6:9]
	v_mfma_f32_16x16x32_bf16 v[2:5], v[172:175], v[204:207], v[2:5]
	v_mfma_f32_16x16x32_bf16 v[54:57], v[168:171], v[184:187], v[54:57]
	v_mfma_f32_16x16x32_bf16 v[50:53], v[176:179], v[184:187], v[50:53]
	v_mfma_f32_16x16x32_bf16 v[38:41], v[168:171], v[192:195], v[38:41]
	v_mfma_f32_16x16x32_bf16 v[34:37], v[176:179], v[192:195], v[34:37]
	v_mfma_f32_16x16x32_bf16 v[22:25], v[168:171], v[200:203], v[22:25]
	v_mfma_f32_16x16x32_bf16 v[18:21], v[176:179], v[200:203], v[18:21]
	s_setprio 2
	s_barrier
	v_mfma_f32_16x16x32_bf16 v[6:9], v[168:171], v[208:211], v[6:9]
	v_mfma_f32_16x16x32_bf16 v[2:5], v[176:179], v[208:211], v[2:5]
	s_setprio 0
	s_add_i32 s70, s70, 2
	s_add_u32 s64, s64, 0x100
	s_addc_u32 s65, s65, 0
	s_add_u32 s18, s18, 0x100
	s_addc_u32 s19, s19, 0
	s_add_u32 s66, s66, 0x100
	s_addc_u32 s67, s67, 0
	s_cmp_gt_u32 s70, 29
	.p2align 6

.LBB0_2791:
	s_ashr_i32 s21, s20, 31
	s_lshl_b64 s[22:23], s[20:21], 15
	s_add_u32 s22, s37, s22
	s_addc_u32 s23, s40, s23
	s_and_b64 s[24:25], s[2:3], exec
	s_cselect_b32 s21, s23, s31
	s_cselect_b32 s63, s22, s30
	s_ashr_i32 s19, s18, 31
	s_lshl_b64 s[24:25], s[18:19], 15
	s_add_u32 s24, s41, s24
	s_addc_u32 s25, s42, s25
	s_and_b64 s[34:35], s[2:3], exec
	s_cselect_b32 s19, s25, s29
	s_cselect_b32 s64, s24, s28
	s_add_u32 s65, s28, 0x80000
	s_addc_u32 s66, s29, 0
	s_add_u32 s28, s30, 0x204000
	s_addc_u32 s29, s31, 0
	s_add_u32 s67, s30, 0x400000
	s_addc_u32 s68, s31, 0
	s_mov_b32 s69, -2
	s_waitcnt vmcnt(25)
	s_waitcnt vmcnt(24)
	s_waitcnt vmcnt(4)
	s_waitcnt vmcnt(2)
	s_waitcnt vmcnt(1)
	s_waitcnt vmcnt(0)
	ds_read_b128 v[130:133], v181
	ds_read_b128 v[134:137], v181 offset:1024
	ds_read_b128 v[138:141], v181 offset:2048
	ds_read_b128 v[142:145], v181 offset:3072
	ds_read_b128 v[150:153], v182
	ds_read_b128 v[154:157], v182 offset:1024
	ds_read_b128 v[158:161], v182 offset:2048
	ds_read_b128 v[162:165], v182 offset:3072
	s_cmpk_eq_i32 s69, 0x52
	s_cselect_b32 s31, s19, s66
	s_cselect_b32 s30, s64, s65
	s_cselect_b32 s35, s21, s68
	s_cselect_b32 s34, s63, s67
	ds_read_b128 v[166:169], v183
	ds_read_b128 v[170:173], v183 offset:1024
	ds_read_b128 v[186:189], v183 offset:2048
	ds_read_b128 v[190:193], v183 offset:3072
	ds_read_b128 v[194:197], v183 offset:4096
	ds_read_b128 v[198:201], v183 offset:5120
	ds_read_b128 v[202:205], v183 offset:6144
	ds_read_b128 v[206:209], v183 offset:7168
	s_add_u32 s70, s28, 0xffffc000
	s_addc_u32 s71, s29, -1
	s_mov_b32 s73, m0
	s_mov_b32 m0, s57
	s_nop 0
	global_load_lds_dwordx4 v1, s[70:71]
	s_mov_b32 m0, s73
	s_nop 0
	s_mov_b32 s73, m0
	s_mov_b32 m0, s59
	s_nop 0
	global_load_lds_dwordx4 v177, s[70:71]
	s_mov_b32 m0, s73
	s_mov_b32 s70, m0
	s_mov_b32 m0, s58
	s_nop 0
	global_load_lds_dwordx4 v1, s[28:29]
	s_mov_b32 m0, s70
	s_nop 0
	s_mov_b32 s70, m0
	s_mov_b32 m0, s60
	s_nop 0
	global_load_lds_dwordx4 v177, s[28:29]
	s_mov_b32 m0, s70
	s_waitcnt vmcnt(8)
	s_waitcnt lgkmcnt(0)
	s_barrier
	s_setprio 1
	s_waitcnt lgkmcnt(7)
	v_mfma_f32_16x16x32_bf16 v[126:129], v[130:133], v[166:169], 0
	v_mfma_f32_16x16x32_bf16 v[122:125], v[138:141], v[166:169], 0
	s_waitcnt lgkmcnt(5)
	v_mfma_f32_16x16x32_bf16 v[118:121], v[130:133], v[186:189], 0
	v_mfma_f32_16x16x32_bf16 v[110:113], v[138:141], v[186:189], 0
	s_waitcnt lgkmcnt(3)
	v_mfma_f32_16x16x32_bf16 v[94:97], v[130:133], v[194:197], 0
	v_mfma_f32_16x16x32_bf16 v[90:93], v[138:141], v[194:197], 0
	s_waitcnt lgkmcnt(1)
	v_mfma_f32_16x16x32_bf16 v[86:89], v[130:133], v[202:205], 0
	v_mfma_f32_16x16x32_bf16 v[78:81], v[138:141], v[202:205], 0
	v_mfma_f32_16x16x32_bf16 v[126:129], v[134:137], v[170:173], v[126:129]
	v_mfma_f32_16x16x32_bf16 v[122:125], v[142:145], v[170:173], v[122:125]
	v_mfma_f32_16x16x32_bf16 v[118:121], v[134:137], v[190:193], v[118:121]
	v_mfma_f32_16x16x32_bf16 v[110:113], v[142:145], v[190:193], v[110:113]
	v_mfma_f32_16x16x32_bf16 v[94:97], v[134:137], v[198:201], v[94:97]
	v_mfma_f32_16x16x32_bf16 v[90:93], v[142:145], v[198:201], v[90:93]
	s_waitcnt lgkmcnt(0)
	v_mfma_f32_16x16x32_bf16 v[86:89], v[134:137], v[206:209], v[86:89]
	v_mfma_f32_16x16x32_bf16 v[78:81], v[142:145], v[206:209], v[78:81]
	s_setprio 0
	s_setprio 1
	v_mfma_f32_16x16x32_bf16 v[114:117], v[150:153], v[166:169], 0
	v_mfma_f32_16x16x32_bf16 v[106:109], v[158:161], v[166:169], 0
	v_mfma_f32_16x16x32_bf16 v[102:105], v[150:153], v[186:189], 0
	v_mfma_f32_16x16x32_bf16 v[98:101], v[158:161], v[186:189], 0
	v_mfma_f32_16x16x32_bf16 v[82:85], v[150:153], v[194:197], 0
	v_mfma_f32_16x16x32_bf16 v[74:77], v[158:161], v[194:197], 0
	v_mfma_f32_16x16x32_bf16 v[70:73], v[150:153], v[202:205], 0
	v_mfma_f32_16x16x32_bf16 v[66:69], v[158:161], v[202:205], 0
	v_mfma_f32_16x16x32_bf16 v[114:117], v[154:157], v[170:173], v[114:117]
	v_mfma_f32_16x16x32_bf16 v[106:109], v[162:165], v[170:173], v[106:109]
	v_mfma_f32_16x16x32_bf16 v[102:105], v[154:157], v[190:193], v[102:105]
	v_mfma_f32_16x16x32_bf16 v[98:101], v[162:165], v[190:193], v[98:101]
	v_mfma_f32_16x16x32_bf16 v[82:85], v[154:157], v[198:201], v[82:85]
	v_mfma_f32_16x16x32_bf16 v[74:77], v[162:165], v[198:201], v[74:77]
	s_setprio 2
	s_barrier
	v_mfma_f32_16x16x32_bf16 v[70:73], v[154:157], v[206:209], v[70:73]
	v_mfma_f32_16x16x32_bf16 v[66:69], v[162:165], v[206:209], v[66:69]
	s_setprio 0
	ds_read_b128 v[166:169], v183 offset:16384
	ds_read_b128 v[170:173], v183 offset:17408
	ds_read_b128 v[186:189], v183 offset:18432
	ds_read_b128 v[190:193], v183 offset:19456
	ds_read_b128 v[194:197], v183 offset:20480
	ds_read_b128 v[198:201], v183 offset:21504
	ds_read_b128 v[202:205], v183 offset:22528
	ds_read_b128 v[206:209], v183 offset:23552
	s_mov_b32 s70, m0
	s_mov_b32 m0, s27
	s_nop 0
	global_load_lds_dwordx4 v176, s[30:31]
	s_mov_b32 m0, s70
	s_nop 0
	s_mov_b32 s70, m0
	s_mov_b32 m0, s45
	s_nop 0
	global_load_lds_dwordx4 v178, s[30:31]
	s_mov_b32 m0, s70
	s_add_u32 s70, s30, 0x4000
	s_addc_u32 s71, s31, 0
	s_mov_b32 s73, m0
	s_mov_b32 m0, s46
	s_nop 0
	global_load_lds_dwordx4 v176, s[70:71]
	s_mov_b32 m0, s73
	s_nop 0
	s_mov_b32 s73, m0
	s_mov_b32 m0, s47
	s_nop 0
	global_load_lds_dwordx4 v178, s[70:71]
	s_mov_b32 m0, s73
	s_waitcnt vmcnt(4)
	s_waitcnt lgkmcnt(0)
	s_barrier
	s_setprio 1
	s_waitcnt lgkmcnt(7)
	v_mfma_f32_16x16x32_bf16 v[62:65], v[130:133], v[166:169], 0
	v_mfma_f32_16x16x32_bf16 v[58:61], v[138:141], v[166:169], 0
	s_waitcnt lgkmcnt(5)
	v_mfma_f32_16x16x32_bf16 v[46:49], v[130:133], v[186:189], 0
	v_mfma_f32_16x16x32_bf16 v[42:45], v[138:141], v[186:189], 0
	s_waitcnt lgkmcnt(3)
	v_mfma_f32_16x16x32_bf16 v[30:33], v[130:133], v[194:197], 0
	v_mfma_f32_16x16x32_bf16 v[26:29], v[138:141], v[194:197], 0
	s_waitcnt lgkmcnt(1)
	v_mfma_f32_16x16x32_bf16 v[14:17], v[130:133], v[202:205], 0
	v_mfma_f32_16x16x32_bf16 v[10:13], v[138:141], v[202:205], 0
	v_mfma_f32_16x16x32_bf16 v[62:65], v[134:137], v[170:173], v[62:65]
	v_mfma_f32_16x16x32_bf16 v[58:61], v[142:145], v[170:173], v[58:61]
	v_mfma_f32_16x16x32_bf16 v[46:49], v[134:137], v[190:193], v[46:49]
	v_mfma_f32_16x16x32_bf16 v[42:45], v[142:145], v[190:193], v[42:45]
	v_mfma_f32_16x16x32_bf16 v[30:33], v[134:137], v[198:201], v[30:33]
	v_mfma_f32_16x16x32_bf16 v[26:29], v[142:145], v[198:201], v[26:29]
	s_waitcnt lgkmcnt(0)
	v_mfma_f32_16x16x32_bf16 v[14:17], v[134:137], v[206:209], v[14:17]
	v_mfma_f32_16x16x32_bf16 v[10:13], v[142:145], v[206:209], v[10:13]
	s_setprio 0
	s_setprio 1
	v_mfma_f32_16x16x32_bf16 v[54:57], v[150:153], v[166:169], 0
	v_mfma_f32_16x16x32_bf16 v[50:53], v[158:161], v[166:169], 0
	v_mfma_f32_16x16x32_bf16 v[38:41], v[150:153], v[186:189], 0
	v_mfma_f32_16x16x32_bf16 v[34:37], v[158:161], v[186:189], 0
	v_mfma_f32_16x16x32_bf16 v[22:25], v[150:153], v[194:197], 0
	v_mfma_f32_16x16x32_bf16 v[18:21], v[158:161], v[194:197], 0
	v_mfma_f32_16x16x32_bf16 v[6:9], v[150:153], v[202:205], 0
	v_mfma_f32_16x16x32_bf16 v[2:5], v[158:161], v[202:205], 0
	v_mfma_f32_16x16x32_bf16 v[54:57], v[154:157], v[170:173], v[54:57]
	v_mfma_f32_16x16x32_bf16 v[50:53], v[162:165], v[170:173], v[50:53]
	v_mfma_f32_16x16x32_bf16 v[38:41], v[154:157], v[190:193], v[38:41]
	v_mfma_f32_16x16x32_bf16 v[34:37], v[162:165], v[190:193], v[34:37]
	v_mfma_f32_16x16x32_bf16 v[22:25], v[154:157], v[198:201], v[22:25]
	v_mfma_f32_16x16x32_bf16 v[18:21], v[162:165], v[198:201], v[18:21]
	s_setprio 2
	s_barrier
	v_mfma_f32_16x16x32_bf16 v[6:9], v[154:157], v[206:209], v[6:9]
	v_mfma_f32_16x16x32_bf16 v[2:5], v[162:165], v[206:209], v[2:5]
	s_setprio 0
	ds_read_b128 v[130:133], v184
	ds_read_b128 v[134:137], v184 offset:1024
	ds_read_b128 v[138:141], v184 offset:2048
	ds_read_b128 v[142:145], v184 offset:3072
	ds_read_b128 v[150:153], v185
	ds_read_b128 v[154:157], v185 offset:1024
	ds_read_b128 v[158:161], v185 offset:2048
	ds_read_b128 v[162:165], v185 offset:3072
	ds_read_b128 v[166:169], v183 offset:32768
	ds_read_b128 v[170:173], v183 offset:33792
	ds_read_b128 v[186:189], v183 offset:34816
	ds_read_b128 v[190:193], v183 offset:35840
	ds_read_b128 v[194:197], v183 offset:36864
	ds_read_b128 v[198:201], v183 offset:37888
	ds_read_b128 v[202:205], v183 offset:38912
	ds_read_b128 v[206:209], v183 offset:39936
	s_mov_b32 s70, m0
	s_mov_b32 m0, s44
	s_nop 0
	global_load_lds_dwordx4 v1, s[34:35]
	s_mov_b32 m0, s70
	s_nop 0
	s_mov_b32 s70, m0
	s_mov_b32 m0, s48
	s_nop 0
	global_load_lds_dwordx4 v177, s[34:35]
	s_mov_b32 m0, s70
	s_add_u32 s34, s34, 0x4000
	s_addc_u32 s35, s35, 0
	s_mov_b32 s70, m0
	s_mov_b32 m0, s49
	s_nop 0
	global_load_lds_dwordx4 v1, s[34:35]
	s_mov_b32 m0, s70
	s_nop 0
	s_mov_b32 s70, m0
	s_mov_b32 m0, s50
	s_nop 0
	global_load_lds_dwordx4 v177, s[34:35]
	s_mov_b32 m0, s70
	s_waitcnt vmcnt(8)
	s_waitcnt lgkmcnt(0)
	s_barrier
	s_setprio 1
	s_waitcnt lgkmcnt(7)
	v_mfma_f32_16x16x32_bf16 v[126:129], v[130:133], v[166:169], v[126:129]
	v_mfma_f32_16x16x32_bf16 v[122:125], v[138:141], v[166:169], v[122:125]
	s_waitcnt lgkmcnt(5)
	v_mfma_f32_16x16x32_bf16 v[118:121], v[130:133], v[186:189], v[118:121]
	v_mfma_f32_16x16x32_bf16 v[110:113], v[138:141], v[186:189], v[110:113]
	s_waitcnt lgkmcnt(3)
	v_mfma_f32_16x16x32_bf16 v[94:97], v[130:133], v[194:197], v[94:97]
	v_mfma_f32_16x16x32_bf16 v[90:93], v[138:141], v[194:197], v[90:93]
	s_waitcnt lgkmcnt(1)
	v_mfma_f32_16x16x32_bf16 v[86:89], v[130:133], v[202:205], v[86:89]
	v_mfma_f32_16x16x32_bf16 v[78:81], v[138:141], v[202:205], v[78:81]
	v_mfma_f32_16x16x32_bf16 v[126:129], v[134:137], v[170:173], v[126:129]
	v_mfma_f32_16x16x32_bf16 v[122:125], v[142:145], v[170:173], v[122:125]
	v_mfma_f32_16x16x32_bf16 v[118:121], v[134:137], v[190:193], v[118:121]
	v_mfma_f32_16x16x32_bf16 v[110:113], v[142:145], v[190:193], v[110:113]
	v_mfma_f32_16x16x32_bf16 v[94:97], v[134:137], v[198:201], v[94:97]
	v_mfma_f32_16x16x32_bf16 v[90:93], v[142:145], v[198:201], v[90:93]
	s_waitcnt lgkmcnt(0)
	v_mfma_f32_16x16x32_bf16 v[86:89], v[134:137], v[206:209], v[86:89]
	v_mfma_f32_16x16x32_bf16 v[78:81], v[142:145], v[206:209], v[78:81]
	s_setprio 0
	s_setprio 1
	v_mfma_f32_16x16x32_bf16 v[114:117], v[150:153], v[166:169], v[114:117]
	v_mfma_f32_16x16x32_bf16 v[106:109], v[158:161], v[166:169], v[106:109]
	v_mfma_f32_16x16x32_bf16 v[102:105], v[150:153], v[186:189], v[102:105]
	v_mfma_f32_16x16x32_bf16 v[98:101], v[158:161], v[186:189], v[98:101]
	v_mfma_f32_16x16x32_bf16 v[82:85], v[150:153], v[194:197], v[82:85]
	v_mfma_f32_16x16x32_bf16 v[74:77], v[158:161], v[194:197], v[74:77]
	v_mfma_f32_16x16x32_bf16 v[70:73], v[150:153], v[202:205], v[70:73]
	v_mfma_f32_16x16x32_bf16 v[66:69], v[158:161], v[202:205], v[66:69]
	v_mfma_f32_16x16x32_bf16 v[114:117], v[154:157], v[170:173], v[114:117]
	v_mfma_f32_16x16x32_bf16 v[106:109], v[162:165], v[170:173], v[106:109]
	v_mfma_f32_16x16x32_bf16 v[102:105], v[154:157], v[190:193], v[102:105]
	v_mfma_f32_16x16x32_bf16 v[98:101], v[162:165], v[190:193], v[98:101]
	v_mfma_f32_16x16x32_bf16 v[82:85], v[154:157], v[198:201], v[82:85]
	v_mfma_f32_16x16x32_bf16 v[74:77], v[162:165], v[198:201], v[74:77]
	s_setprio 2
	s_barrier
	v_mfma_f32_16x16x32_bf16 v[70:73], v[154:157], v[206:209], v[70:73]
	v_mfma_f32_16x16x32_bf16 v[66:69], v[162:165], v[206:209], v[66:69]
	s_setprio 0
	ds_read_b128 v[166:169], v183 offset:49152
	ds_read_b128 v[170:173], v183 offset:50176
	ds_read_b128 v[186:189], v183 offset:51200
	ds_read_b128 v[190:193], v183 offset:52224
	ds_read_b128 v[194:197], v183 offset:53248
	ds_read_b128 v[198:201], v183 offset:54272
	ds_read_b128 v[202:205], v183 offset:55296
	ds_read_b128 v[206:209], v183 offset:56320
	s_add_u32 s34, s30, 0x40000
	s_addc_u32 s35, s31, 0
	s_mov_b32 s70, m0
	s_mov_b32 m0, s51
	s_nop 0
	global_load_lds_dwordx4 v176, s[34:35]
	s_mov_b32 m0, s70
	s_add_u32 s30, s30, 0x44000
	s_mov_b32 s70, m0
	s_mov_b32 m0, s52
	s_nop 0
	global_load_lds_dwordx4 v178, s[34:35]
	s_mov_b32 m0, s70
	s_addc_u32 s31, s31, 0
	s_mov_b32 s34, m0
	s_mov_b32 m0, s53
	s_nop 0
	global_load_lds_dwordx4 v176, s[30:31]
	s_mov_b32 m0, s34
	s_nop 0
	s_mov_b32 s34, m0
	s_mov_b32 m0, s54
	s_nop 0
	global_load_lds_dwordx4 v178, s[30:31]
	s_mov_b32 m0, s34
	s_waitcnt vmcnt(4)
	s_waitcnt lgkmcnt(0)
	s_barrier
	s_setprio 1
	s_waitcnt lgkmcnt(7)
	v_mfma_f32_16x16x32_bf16 v[62:65], v[130:133], v[166:169], v[62:65]
	v_mfma_f32_16x16x32_bf16 v[58:61], v[138:141], v[166:169], v[58:61]
	s_waitcnt lgkmcnt(5)
	v_mfma_f32_16x16x32_bf16 v[46:49], v[130:133], v[186:189], v[46:49]
	v_mfma_f32_16x16x32_bf16 v[42:45], v[138:141], v[186:189], v[42:45]
	s_waitcnt lgkmcnt(3)
	v_mfma_f32_16x16x32_bf16 v[30:33], v[130:133], v[194:197], v[30:33]
	v_mfma_f32_16x16x32_bf16 v[26:29], v[138:141], v[194:197], v[26:29]
	s_waitcnt lgkmcnt(1)
	v_mfma_f32_16x16x32_bf16 v[14:17], v[130:133], v[202:205], v[14:17]
	v_mfma_f32_16x16x32_bf16 v[10:13], v[138:141], v[202:205], v[10:13]
	v_mfma_f32_16x16x32_bf16 v[62:65], v[134:137], v[170:173], v[62:65]
	v_mfma_f32_16x16x32_bf16 v[58:61], v[142:145], v[170:173], v[58:61]
	v_mfma_f32_16x16x32_bf16 v[46:49], v[134:137], v[190:193], v[46:49]
	v_mfma_f32_16x16x32_bf16 v[42:45], v[142:145], v[190:193], v[42:45]
	v_mfma_f32_16x16x32_bf16 v[30:33], v[134:137], v[198:201], v[30:33]
	v_mfma_f32_16x16x32_bf16 v[26:29], v[142:145], v[198:201], v[26:29]
	s_waitcnt lgkmcnt(0)
	v_mfma_f32_16x16x32_bf16 v[14:17], v[134:137], v[206:209], v[14:17]
	v_mfma_f32_16x16x32_bf16 v[10:13], v[142:145], v[206:209], v[10:13]
	s_setprio 0
	s_setprio 1
	v_mfma_f32_16x16x32_bf16 v[54:57], v[150:153], v[166:169], v[54:57]
	v_mfma_f32_16x16x32_bf16 v[50:53], v[158:161], v[166:169], v[50:53]
	v_mfma_f32_16x16x32_bf16 v[38:41], v[150:153], v[186:189], v[38:41]
	v_mfma_f32_16x16x32_bf16 v[34:37], v[158:161], v[186:189], v[34:37]
	v_mfma_f32_16x16x32_bf16 v[22:25], v[150:153], v[194:197], v[22:25]
	v_mfma_f32_16x16x32_bf16 v[18:21], v[158:161], v[194:197], v[18:21]
	v_mfma_f32_16x16x32_bf16 v[6:9], v[150:153], v[202:205], v[6:9]
	v_mfma_f32_16x16x32_bf16 v[2:5], v[158:161], v[202:205], v[2:5]
	v_mfma_f32_16x16x32_bf16 v[54:57], v[154:157], v[170:173], v[54:57]
	v_mfma_f32_16x16x32_bf16 v[50:53], v[162:165], v[170:173], v[50:53]
	v_mfma_f32_16x16x32_bf16 v[38:41], v[154:157], v[190:193], v[38:41]
	v_mfma_f32_16x16x32_bf16 v[34:37], v[162:165], v[190:193], v[34:37]
	v_mfma_f32_16x16x32_bf16 v[22:25], v[154:157], v[198:201], v[22:25]
	v_mfma_f32_16x16x32_bf16 v[18:21], v[162:165], v[198:201], v[18:21]
	s_setprio 2
	s_barrier
	v_mfma_f32_16x16x32_bf16 v[6:9], v[154:157], v[206:209], v[6:9]
	v_mfma_f32_16x16x32_bf16 v[2:5], v[162:165], v[206:209], v[2:5]
	s_setprio 0
	s_add_i32 s69, s69, 2
	s_add_u32 s65, s65, 0x80000
	s_addc_u32 s66, s66, 0
	s_add_u32 s28, s28, 0x400000
	s_addc_u32 s29, s29, 0
	s_add_u32 s67, s67, 0x400000
	s_addc_u32 s68, s68, 0
	s_cmpk_gt_u32 s69, 0x53
	.p2align 6
